# GEMM K-loops: one static s_setprio 1 for the wr==1 half for the whole loop, per-block toggles removed (on top of previous version)
# speedup vs baseline: 1.0059x; 1.0018x over previous
; #define PG8_STAGE(bufoff, gbase, voff) do { _Pragma("unroll") for (int _i = 0; _i < 2; ++_i) \
;         __builtin_amdgcn_global_load_lds((const unsigned*)((const char*)(gbase) + (voff)[_i]), (LAS unsigned*)(lds + (bufoff) + ldsw + _i * 8192), 16, 0, 0); } while (0)
; #define PG8_LDA(dst, off) do { _Pragma("unroll") for (int m = 0; m < 4; ++m) _Pragma("unroll") for (int k = 0; k < 2; ++k) dst[m][k] = *(const LAS bf16x8*)(lds + (off) + aoff + m * 2048 + k * 1024); } while (0)
; template <class Epi, bool ALIGN_EPI = true>
; __device__ __forceinline__ void gemm_phase(LAS unsigned char* lds, const Gemm g, const StaticOrder& S, const Epi& E) {
;     ...
;     Unit cur, nxt; int ui = 0;
;     if (!S.next(0, cur)) return;
;     Acc acc;
; #pragma unroll
;     for (int a = 0; a < 2; ++a)
; #pragma unroll
;         for (int b = 0; b < 2; ++b)
; #pragma unroll
;             for (int m = 0; m < 4; ++m)
; #pragma unroll
;                 for (int n = 0; n < 2; ++n) acc[a][b][m][n] = (f32x4){0.f, 0.f, 0.f, 0.f};
;     bf16x8 At[4][2], B0[2][2], B1[2][2];
;     const char* cA = PG8_ABASE(cur); const char* cB = PG8_BBASE(cur);
;     int o0 = 6 * HTB, o1 = 7 * HTB, o2 = 8 * HTB;
;     PG8_STAGE(PG8_SB(0, 0), cB, voffB); PG8_STAGE(PG8_SB(0, 1), cB + hstep, voffB); PG8_STAGE(o0, cA, voffA); PG8_STAGE(PG8_SA1(0), cA + hstep, voffA);
;     if (wr == 1) PG8_BAR;
;     PG8_WAIT_V(2); PG8_BAR;
;     PG8_STAGE(PG8_SB(1, 0), cB + kstep, voffB); PG8_STAGE(o1, cA + kstep, voffA); PG8_STAGE(PG8_SB(1, 1), cB + hstep + kstep, voffB);
;     PG8_WAIT_V(6); PG8_BAR;
;     for (;;) {
;         const bool has_next = S.next(ui + 1, nxt);
;         const char* nA = has_next ? PG8_ABASE(nxt) : cA; const char* nB = has_next ? PG8_BBASE(nxt) : cB;
;         for (int t = 0; t < nt; t += 2) {
;             const bool last = (t == nt - 2);
;             const char* a1 = cA + (size_t)(t + 1) * kstep;
;             const char* a2 = last ? nA : cA + (size_t)(t + 2) * kstep; const char* b2 = last ? nB : cB + (size_t)(t + 2) * kstep;
;             const char* a3 = a2 + kstep; const char* b3 = b2 + kstep;
;             PG8_LDB(B0, 0, 0); PG8_LDB(B1, 0, 1); PG8_SCHED; PG8_LDA(At, o0); PG8_STAGE(PG8_SA1(1), a1 + hstep, voffA); PG8_STAGE(o2, a2, voffA);
;             PG8_WAIT_V(10); PG8_WAIT_L(0); PG8_BAR; PG8_MMA(0, 0, At, B0); PG8_MMA(0, 1, At, B1); PG8_BAR; PG8_SCHED;
.LBB0_220:
	s_ashr_i32 s39, s38, 31
	s_lshl_b64 s[40:41], s[38:39], 21
	s_add_u32 s40, s16, s40
	s_addc_u32 s41, s17, s41
	s_and_b64 s[42:43], s[2:3], exec
	s_cselect_b32 s5, s41, s11
	s_cselect_b32 s9, s40, s10
	s_ashr_i32 s29, s28, 31
	s_lshl_b64 s[42:43], s[28:29], 21
	s_add_u32 s42, s88, s42
	s_addc_u32 s43, s89, s43
	s_and_b64 s[44:45], s[2:3], exec
	s_cselect_b32 s29, s43, s13
	s_cselect_b32 s33, s42, s12
	s_add_u32 s10, s10, 0x100080
	s_addc_u32 s11, s11, 0
	s_add_u32 s39, s12, 0x100
	v_mov_b32_e32 v2, 0
	s_addc_u32 s68, s13, 0
	s_mov_b32 s69, -2
	s_mov_b32 s12, s67
	v_mov_b32_e32 v3, v2
	v_mov_b32_e32 v4, v2
	v_mov_b32_e32 v5, v2
	v_mov_b32_e32 v6, v2
	v_mov_b32_e32 v7, v2
	v_mov_b32_e32 v8, v2
	v_mov_b32_e32 v9, v2
	v_mov_b32_e32 v18, v2
	v_mov_b32_e32 v19, v2
	v_mov_b32_e32 v20, v2
	v_mov_b32_e32 v21, v2
	v_mov_b32_e32 v22, v2
	v_mov_b32_e32 v23, v2
	v_mov_b32_e32 v24, v2
	v_mov_b32_e32 v25, v2
	v_mov_b32_e32 v34, v2
	v_mov_b32_e32 v35, v2
	v_mov_b32_e32 v36, v2
	v_mov_b32_e32 v37, v2
	v_mov_b32_e32 v38, v2
	v_mov_b32_e32 v39, v2
	v_mov_b32_e32 v40, v2
	v_mov_b32_e32 v41, v2
	v_mov_b32_e32 v50, v2
	v_mov_b32_e32 v51, v2
	v_mov_b32_e32 v52, v2
	v_mov_b32_e32 v53, v2
	v_mov_b32_e32 v54, v2
	v_mov_b32_e32 v55, v2
	v_mov_b32_e32 v56, v2
	v_mov_b32_e32 v57, v2
	v_mov_b32_e32 v10, v2
	v_mov_b32_e32 v11, v2
	v_mov_b32_e32 v12, v2
	v_mov_b32_e32 v13, v2
	v_mov_b32_e32 v14, v2
	v_mov_b32_e32 v15, v2
	v_mov_b32_e32 v16, v2
	v_mov_b32_e32 v17, v2
	v_mov_b32_e32 v26, v2
	v_mov_b32_e32 v27, v2
	v_mov_b32_e32 v28, v2
	v_mov_b32_e32 v29, v2
	v_mov_b32_e32 v30, v2
	v_mov_b32_e32 v31, v2
	v_mov_b32_e32 v32, v2
	v_mov_b32_e32 v33, v2
	v_mov_b32_e32 v42, v2
	v_mov_b32_e32 v43, v2
	v_mov_b32_e32 v44, v2
	v_mov_b32_e32 v45, v2
	v_mov_b32_e32 v46, v2
	v_mov_b32_e32 v47, v2
	v_mov_b32_e32 v48, v2
	v_mov_b32_e32 v49, v2
	v_mov_b32_e32 v58, v2
	v_mov_b32_e32 v59, v2
	v_mov_b32_e32 v60, v2
	v_mov_b32_e32 v61, v2
	v_mov_b32_e32 v62, v2
	v_mov_b32_e32 v63, v2
	v_mov_b32_e32 v64, v2
	v_mov_b32_e32 v65, v2
	v_mov_b32_e32 v66, v2
	v_mov_b32_e32 v67, v2
	v_mov_b32_e32 v68, v2
	v_mov_b32_e32 v69, v2
	v_mov_b32_e32 v70, v2
	v_mov_b32_e32 v71, v2
	v_mov_b32_e32 v72, v2
	v_mov_b32_e32 v73, v2
	v_mov_b32_e32 v82, v2
	v_mov_b32_e32 v83, v2
	v_mov_b32_e32 v84, v2
	v_mov_b32_e32 v85, v2
	v_mov_b32_e32 v86, v2
	v_mov_b32_e32 v87, v2
	v_mov_b32_e32 v88, v2
	v_mov_b32_e32 v89, v2
	v_mov_b32_e32 v98, v2
	v_mov_b32_e32 v99, v2
	v_mov_b32_e32 v100, v2
	v_mov_b32_e32 v101, v2
	v_mov_b32_e32 v102, v2
	v_mov_b32_e32 v103, v2
	v_mov_b32_e32 v104, v2
	v_mov_b32_e32 v105, v2
	v_mov_b32_e32 v114, v2
	v_mov_b32_e32 v115, v2
	v_mov_b32_e32 v116, v2
	v_mov_b32_e32 v117, v2
	v_mov_b32_e32 v118, v2
	v_mov_b32_e32 v119, v2
	v_mov_b32_e32 v120, v2
	v_mov_b32_e32 v121, v2
	v_mov_b32_e32 v74, v2
	v_mov_b32_e32 v75, v2
	v_mov_b32_e32 v76, v2
	v_mov_b32_e32 v77, v2
	v_mov_b32_e32 v78, v2
	v_mov_b32_e32 v79, v2
	v_mov_b32_e32 v80, v2
	v_mov_b32_e32 v81, v2
	v_mov_b32_e32 v90, v2
	v_mov_b32_e32 v91, v2
	v_mov_b32_e32 v92, v2
	v_mov_b32_e32 v93, v2
	v_mov_b32_e32 v94, v2
	v_mov_b32_e32 v95, v2
	v_mov_b32_e32 v96, v2
	v_mov_b32_e32 v97, v2
	v_mov_b32_e32 v106, v2
	v_mov_b32_e32 v107, v2
	v_mov_b32_e32 v108, v2
	v_mov_b32_e32 v109, v2
	v_mov_b32_e32 v110, v2
	v_mov_b32_e32 v111, v2
	v_mov_b32_e32 v112, v2
	v_mov_b32_e32 v113, v2
	v_mov_b32_e32 v122, v2
	v_mov_b32_e32 v123, v2
	v_mov_b32_e32 v124, v2
	v_mov_b32_e32 v125, v2
	v_mov_b32_e32 v126, v2
	v_mov_b32_e32 v127, v2
	v_mov_b32_e32 v128, v2
	v_mov_b32_e32 v129, v2
	s_and_b64 vcc, exec, s[22:23]
	s_cbranch_vccz .Lkprio_skip_P2
	s_setprio 1
.Lkprio_skip_P2:
.LBB0_221:
	ds_read_b128 v[146:149], v159 offset:32768
	ds_read_b128 v[150:153], v159 offset:33792
	ds_read_b128 v[162:165], v159 offset:34816
	ds_read_b128 v[166:169], v159 offset:35840
	ds_read_b128 v[170:173], v159 offset:49152
	ds_read_b128 v[174:177], v159 offset:50176
	ds_read_b128 v[178:181], v159 offset:51200
	ds_read_b128 v[182:185], v159 offset:52224
	s_mov_b32 s67, s66
	s_mov_b32 s66, s63
	s_mov_b32 s63, s12
	s_add_u32 s12, s10, 0xfff00080
	s_addc_u32 s13, s11, -1
	s_cmp_eq_u32 s69, 60
	s_cselect_b32 s44, s9, s12
	s_cselect_b32 s12, s33, s39
	s_cselect_b32 s45, s5, s13
	s_cselect_b32 s13, s29, s68
	v_add_u32_e32 v154, s63, v157
	ds_read_b128 v[186:189], v154
	ds_read_b128 v[190:193], v154 offset:1024
	ds_read_b128 v[194:197], v154 offset:2048
	ds_read_b128 v[198:201], v154 offset:3072
	ds_read_b128 v[202:205], v154 offset:4096
	ds_read_b128 v[206:209], v154 offset:5120
	ds_read_b128 v[210:213], v154 offset:6144
	ds_read_b128 v[214:217], v154 offset:7168
	v_lshl_add_u64 v[154:155], s[10:11], 0, v[138:139]
	s_add_i32 m0, s46, 0x4000
	s_add_i32 s70, s46, s67
	global_load_lds_dwordx4 v[154:155], off
	v_lshl_add_u64 v[154:155], s[10:11], 0, v[140:141]
	s_add_i32 m0, s46, 0x6000
	v_lshl_add_u64 v[218:219], s[44:45], 0, v[134:135]
	global_load_lds_dwordx4 v[154:155], off
	v_lshl_add_u64 v[154:155], s[44:45], 0, v[130:131]
	s_mov_b32 m0, s70
	s_nop 0
	global_load_lds_dwordx4 v[154:155], off
	s_add_i32 m0, s70, 0x2000
	s_nop 0
	global_load_lds_dwordx4 v[218:219], off
	s_waitcnt vmcnt(10)
	s_waitcnt lgkmcnt(0)
	s_barrier
; #define PG8_STAGE(bufoff, gbase, voff) do { _Pragma("unroll") for (int _i = 0; _i < 2; ++_i) \
;         __builtin_amdgcn_global_load_lds((const unsigned*)((const char*)(gbase) + (voff)[_i]), (LAS unsigned*)(lds + (bufoff) + ldsw + _i * 8192), 16, 0, 0); } while (0)
; #define PG8_LDA(dst, off) do { _Pragma("unroll") for (int m = 0; m < 4; ++m) _Pragma("unroll") for (int k = 0; k < 2; ++k) dst[m][k] = *(const LAS bf16x8*)(lds + (off) + aoff + m * 2048 + k * 1024); } while (0)
; #define PG8_MMA(ai, bj, At, Bt) do { __builtin_amdgcn_s_setprio(1); _Pragma("unroll") for (int m = 0; m < 4; ++m) _Pragma("unroll") for (int n = 0; n < 2; ++n) _Pragma("unroll") for (int k = 0; k < 2; ++k) \
;         acc[ai][bj][m][n] = __builtin_amdgcn_mfma_f32_16x16x32_bf16(Bt[n][k], At[m][k], acc[ai][bj][m][n], 0, 0, 0); __builtin_amdgcn_s_setprio(0); } while (0)
; #define PG8_WAIT_V(n) asm volatile("s_waitcnt vmcnt(" #n ")" ::: "memory")
; #define PG8_WAIT_L(n) asm volatile("s_waitcnt lgkmcnt(" #n ")" ::: "memory")
; #define PG8_BAR __builtin_amdgcn_s_barrier()
; #define PG8_SCHED __builtin_amdgcn_sched_barrier(0)
; template <class Epi, bool ALIGN_EPI = true>
; __device__ __forceinline__ void gemm_phase(LAS unsigned char* lds, const Gemm g, const StaticOrder& S, const Epi& E) {
;     ...
;             PG8_WAIT_V(10); PG8_WAIT_L(0); PG8_BAR; PG8_MMA(0, 0, At, B0); PG8_MMA(0, 1, At, B1); PG8_BAR; PG8_SCHED;
;             PG8_LDA(At, PG8_SA1(0)); PG8_STAGE(PG8_SB(0, 0), b2, voffB); PG8_STAGE(PG8_SB(0, 1), b2 + hstep, voffB);
;             PG8_WAIT_V(8); PG8_WAIT_L(0); PG8_BAR; PG8_MMA(1, 0, At, B0); PG8_MMA(1, 1, At, B1); PG8_BAR; PG8_SCHED;
	s_waitcnt lgkmcnt(0)
	v_mfma_f32_16x16x32_bf16 v[126:129], v[146:149], v[186:189], v[126:129]
	v_mfma_f32_16x16x32_bf16 v[126:129], v[150:153], v[190:193], v[126:129]
	v_mfma_f32_16x16x32_bf16 v[122:125], v[162:165], v[186:189], v[122:125]
	v_mfma_f32_16x16x32_bf16 v[122:125], v[166:169], v[190:193], v[122:125]
	v_mfma_f32_16x16x32_bf16 v[118:121], v[170:173], v[186:189], v[118:121]
	v_mfma_f32_16x16x32_bf16 v[118:121], v[174:177], v[190:193], v[118:121]
	v_mfma_f32_16x16x32_bf16 v[114:117], v[178:181], v[186:189], v[114:117]
	v_mfma_f32_16x16x32_bf16 v[114:117], v[182:185], v[190:193], v[114:117]
	v_mfma_f32_16x16x32_bf16 v[110:113], v[146:149], v[194:197], v[110:113]
	v_mfma_f32_16x16x32_bf16 v[110:113], v[150:153], v[198:201], v[110:113]
	v_mfma_f32_16x16x32_bf16 v[106:109], v[162:165], v[194:197], v[106:109]
	v_mfma_f32_16x16x32_bf16 v[106:109], v[166:169], v[198:201], v[106:109]
	v_mfma_f32_16x16x32_bf16 v[102:105], v[170:173], v[194:197], v[102:105]
	v_mfma_f32_16x16x32_bf16 v[102:105], v[174:177], v[198:201], v[102:105]
	v_mfma_f32_16x16x32_bf16 v[98:101], v[178:181], v[194:197], v[98:101]
	v_mfma_f32_16x16x32_bf16 v[98:101], v[182:185], v[198:201], v[98:101]
	v_mfma_f32_16x16x32_bf16 v[94:97], v[146:149], v[202:205], v[94:97]
	v_mfma_f32_16x16x32_bf16 v[94:97], v[150:153], v[206:209], v[94:97]
	v_mfma_f32_16x16x32_bf16 v[90:93], v[162:165], v[202:205], v[90:93]
	v_mfma_f32_16x16x32_bf16 v[90:93], v[166:169], v[206:209], v[90:93]
	v_mfma_f32_16x16x32_bf16 v[86:89], v[170:173], v[202:205], v[86:89]
	v_mfma_f32_16x16x32_bf16 v[86:89], v[174:177], v[206:209], v[86:89]
	v_mfma_f32_16x16x32_bf16 v[82:85], v[178:181], v[202:205], v[82:85]
	v_mfma_f32_16x16x32_bf16 v[82:85], v[182:185], v[206:209], v[82:85]
	v_mfma_f32_16x16x32_bf16 v[78:81], v[146:149], v[210:213], v[78:81]
	v_mfma_f32_16x16x32_bf16 v[78:81], v[150:153], v[214:217], v[78:81]
	v_mfma_f32_16x16x32_bf16 v[74:77], v[162:165], v[210:213], v[74:77]
	v_mfma_f32_16x16x32_bf16 v[74:77], v[166:169], v[214:217], v[74:77]
	v_mfma_f32_16x16x32_bf16 v[70:73], v[170:173], v[210:213], v[70:73]
	v_mfma_f32_16x16x32_bf16 v[70:73], v[174:177], v[214:217], v[70:73]
	v_mfma_f32_16x16x32_bf16 v[66:69], v[178:181], v[210:213], v[66:69]
	v_mfma_f32_16x16x32_bf16 v[66:69], v[182:185], v[214:217], v[66:69]
	s_barrier
	s_mov_b32 m0, s47
	v_lshl_add_u64 v[220:221], s[12:13], 0, v[132:133]
	s_add_u32 s70, s12, 0x100000
	ds_read_b128 v[186:189], v157
	ds_read_b128 v[190:193], v157 offset:1024
	ds_read_b128 v[194:197], v157 offset:2048
	ds_read_b128 v[198:201], v157 offset:3072
	ds_read_b128 v[202:205], v157 offset:4096
	ds_read_b128 v[206:209], v157 offset:5120
	ds_read_b128 v[210:213], v157 offset:6144
	ds_read_b128 v[214:217], v157 offset:7168
	global_load_lds_dwordx4 v[220:221], off
	v_lshl_add_u64 v[222:223], s[12:13], 0, v[136:137]
	s_mov_b32 m0, s58
	s_addc_u32 s71, s13, 0
	global_load_lds_dwordx4 v[222:223], off
	v_lshl_add_u64 v[224:225], s[70:71], 0, v[132:133]
	s_mov_b32 m0, s59
	s_nop 0
	global_load_lds_dwordx4 v[224:225], off
	v_lshl_add_u64 v[224:225], s[70:71], 0, v[136:137]
	s_mov_b32 m0, s60
	s_nop 0
	global_load_lds_dwordx4 v[224:225], off
	s_waitcnt vmcnt(8)
	s_waitcnt lgkmcnt(0)
	s_barrier
	s_waitcnt lgkmcnt(0)
	v_mfma_f32_16x16x32_bf16 v[62:65], v[146:149], v[186:189], v[62:65]
	v_mfma_f32_16x16x32_bf16 v[62:65], v[150:153], v[190:193], v[62:65]
	v_mfma_f32_16x16x32_bf16 v[58:61], v[162:165], v[186:189], v[58:61]
	v_mfma_f32_16x16x32_bf16 v[58:61], v[166:169], v[190:193], v[58:61]
	v_mfma_f32_16x16x32_bf16 v[54:57], v[170:173], v[186:189], v[54:57]
	v_mfma_f32_16x16x32_bf16 v[54:57], v[174:177], v[190:193], v[54:57]
	v_mfma_f32_16x16x32_bf16 v[50:53], v[178:181], v[186:189], v[50:53]
	v_mfma_f32_16x16x32_bf16 v[50:53], v[182:185], v[190:193], v[50:53]
	v_mfma_f32_16x16x32_bf16 v[46:49], v[146:149], v[194:197], v[46:49]
	v_mfma_f32_16x16x32_bf16 v[46:49], v[150:153], v[198:201], v[46:49]
	v_mfma_f32_16x16x32_bf16 v[42:45], v[162:165], v[194:197], v[42:45]
	v_mfma_f32_16x16x32_bf16 v[42:45], v[166:169], v[198:201], v[42:45]
	v_mfma_f32_16x16x32_bf16 v[38:41], v[170:173], v[194:197], v[38:41]
	v_mfma_f32_16x16x32_bf16 v[38:41], v[174:177], v[198:201], v[38:41]
	v_mfma_f32_16x16x32_bf16 v[34:37], v[178:181], v[194:197], v[34:37]
	v_mfma_f32_16x16x32_bf16 v[34:37], v[182:185], v[198:201], v[34:37]
	v_mfma_f32_16x16x32_bf16 v[30:33], v[146:149], v[202:205], v[30:33]
	v_mfma_f32_16x16x32_bf16 v[30:33], v[150:153], v[206:209], v[30:33]
	v_mfma_f32_16x16x32_bf16 v[26:29], v[162:165], v[202:205], v[26:29]
	v_mfma_f32_16x16x32_bf16 v[26:29], v[166:169], v[206:209], v[26:29]
	v_mfma_f32_16x16x32_bf16 v[22:25], v[170:173], v[202:205], v[22:25]
	v_mfma_f32_16x16x32_bf16 v[22:25], v[174:177], v[206:209], v[22:25]
	v_mfma_f32_16x16x32_bf16 v[18:21], v[178:181], v[202:205], v[18:21]
	v_mfma_f32_16x16x32_bf16 v[18:21], v[182:185], v[206:209], v[18:21]
	v_mfma_f32_16x16x32_bf16 v[14:17], v[146:149], v[210:213], v[14:17]
	v_mfma_f32_16x16x32_bf16 v[14:17], v[150:153], v[214:217], v[14:17]
	v_mfma_f32_16x16x32_bf16 v[10:13], v[162:165], v[210:213], v[10:13]
	v_mfma_f32_16x16x32_bf16 v[10:13], v[166:169], v[214:217], v[10:13]
	v_mfma_f32_16x16x32_bf16 v[6:9], v[170:173], v[210:213], v[6:9]
	v_mfma_f32_16x16x32_bf16 v[6:9], v[174:177], v[214:217], v[6:9]
	v_mfma_f32_16x16x32_bf16 v[2:5], v[178:181], v[210:213], v[2:5]
	v_mfma_f32_16x16x32_bf16 v[2:5], v[182:185], v[214:217], v[2:5]
	s_barrier
; #define PG8_STAGE(bufoff, gbase, voff) do { _Pragma("unroll") for (int _i = 0; _i < 2; ++_i) \
;         __builtin_amdgcn_global_load_lds((const unsigned*)((const char*)(gbase) + (voff)[_i]), (LAS unsigned*)(lds + (bufoff) + ldsw + _i * 8192), 16, 0, 0); } while (0)
; #define PG8_LDA(dst, off) do { _Pragma("unroll") for (int m = 0; m < 4; ++m) _Pragma("unroll") for (int k = 0; k < 2; ++k) dst[m][k] = *(const LAS bf16x8*)(lds + (off) + aoff + m * 2048 + k * 1024); } while (0)
; #define PG8_LDB(dst, b, h) do { _Pragma("unroll") for (int n = 0; n < 2; ++n) _Pragma("unroll") for (int k = 0; k < 2; ++k) dst[n][k] = *(const LAS bf16x8*)(lds + PG8_SB(b, h) + boff + n * 2048 + k * 1024); } while (0)
; #define PG8_MMA(ai, bj, At, Bt) do { __builtin_amdgcn_s_setprio(1); _Pragma("unroll") for (int m = 0; m < 4; ++m) _Pragma("unroll") for (int n = 0; n < 2; ++n) _Pragma("unroll") for (int k = 0; k < 2; ++k) \
;         acc[ai][bj][m][n] = __builtin_amdgcn_mfma_f32_16x16x32_bf16(Bt[n][k], At[m][k], acc[ai][bj][m][n], 0, 0, 0); __builtin_amdgcn_s_setprio(0); } while (0)
; #define PG8_WAIT_V(n) asm volatile("s_waitcnt vmcnt(" #n ")" ::: "memory")
; #define PG8_WAIT_L(n) asm volatile("s_waitcnt lgkmcnt(" #n ")" ::: "memory")
; #define PG8_BAR __builtin_amdgcn_s_barrier()
; #define PG8_SCHED __builtin_amdgcn_sched_barrier(0)
; template <class Epi, bool ALIGN_EPI = true>
; __device__ __forceinline__ void gemm_phase(LAS unsigned char* lds, const Gemm g, const StaticOrder& S, const Epi& E) {
;     ...
;             PG8_LDB(B0, 1, 0); PG8_LDB(B1, 1, 1); PG8_SCHED; PG8_LDA(At, o1); PG8_STAGE(PG8_SA1(0), a2 + hstep, voffA); PG8_STAGE(o0, a3, voffA);
;             PG8_WAIT_V(10); PG8_WAIT_L(0); PG8_BAR; PG8_MMA(0, 0, At, B0); PG8_MMA(0, 1, At, B1); PG8_BAR; PG8_SCHED;
	s_add_i32 s70, 0, 0x10000
	v_add_u32_e32 v161, s70, v156
	s_add_i32 s71, 0, 0x14000
	ds_read_b128 v[146:149], v161
	ds_read_b128 v[150:153], v161 offset:1024
	ds_read_b128 v[162:165], v161 offset:2048
	ds_read_b128 v[166:169], v161 offset:3072
	v_add_u32_e32 v161, s71, v156
	ds_read_b128 v[170:173], v161
	ds_read_b128 v[174:177], v161 offset:1024
	ds_read_b128 v[178:181], v161 offset:2048
	ds_read_b128 v[182:185], v161 offset:3072
	s_add_u32 s44, s44, 0x100000
	s_addc_u32 s45, s45, 0
	s_mov_b32 m0, s46
	v_add_u32_e32 v161, s66, v157
	v_lshl_add_u64 v[224:225], s[44:45], 0, v[130:131]
	ds_read_b128 v[186:189], v161
	ds_read_b128 v[190:193], v161 offset:1024
	ds_read_b128 v[194:197], v161 offset:2048
	ds_read_b128 v[198:201], v161 offset:3072
	ds_read_b128 v[202:205], v161 offset:4096
	ds_read_b128 v[206:209], v161 offset:5120
	ds_read_b128 v[210:213], v161 offset:6144
	ds_read_b128 v[214:217], v161 offset:7168
	global_load_lds_dwordx4 v[224:225], off
	v_lshl_add_u64 v[224:225], s[44:45], 0, v[134:135]
	s_mov_b32 m0, s61
	s_add_i32 s44, s46, s63
	global_load_lds_dwordx4 v[224:225], off
	v_lshl_add_u64 v[154:155], v[154:155], 0, s[24:25]
	s_mov_b32 m0, s44
	s_nop 0
	global_load_lds_dwordx4 v[154:155], off
	v_lshl_add_u64 v[154:155], v[218:219], 0, s[24:25]
	s_add_i32 m0, s44, 0x2000
	s_nop 0
	global_load_lds_dwordx4 v[154:155], off
	s_waitcnt vmcnt(10)
	s_waitcnt lgkmcnt(0)
	s_barrier
	s_waitcnt lgkmcnt(0)
	v_mfma_f32_16x16x32_bf16 v[126:129], v[146:149], v[186:189], v[126:129]
	v_mfma_f32_16x16x32_bf16 v[126:129], v[150:153], v[190:193], v[126:129]
	v_mfma_f32_16x16x32_bf16 v[122:125], v[162:165], v[186:189], v[122:125]
	v_mfma_f32_16x16x32_bf16 v[122:125], v[166:169], v[190:193], v[122:125]
	v_mfma_f32_16x16x32_bf16 v[118:121], v[170:173], v[186:189], v[118:121]
	v_mfma_f32_16x16x32_bf16 v[118:121], v[174:177], v[190:193], v[118:121]
	v_mfma_f32_16x16x32_bf16 v[114:117], v[178:181], v[186:189], v[114:117]
	v_mfma_f32_16x16x32_bf16 v[114:117], v[182:185], v[190:193], v[114:117]
	v_mfma_f32_16x16x32_bf16 v[110:113], v[146:149], v[194:197], v[110:113]
	v_mfma_f32_16x16x32_bf16 v[110:113], v[150:153], v[198:201], v[110:113]
	v_mfma_f32_16x16x32_bf16 v[106:109], v[162:165], v[194:197], v[106:109]
	v_mfma_f32_16x16x32_bf16 v[106:109], v[166:169], v[198:201], v[106:109]
	v_mfma_f32_16x16x32_bf16 v[102:105], v[170:173], v[194:197], v[102:105]
	v_mfma_f32_16x16x32_bf16 v[102:105], v[174:177], v[198:201], v[102:105]
	v_mfma_f32_16x16x32_bf16 v[98:101], v[178:181], v[194:197], v[98:101]
	v_mfma_f32_16x16x32_bf16 v[98:101], v[182:185], v[198:201], v[98:101]
	v_mfma_f32_16x16x32_bf16 v[94:97], v[146:149], v[202:205], v[94:97]
	v_mfma_f32_16x16x32_bf16 v[94:97], v[150:153], v[206:209], v[94:97]
	v_mfma_f32_16x16x32_bf16 v[90:93], v[162:165], v[202:205], v[90:93]
	v_mfma_f32_16x16x32_bf16 v[90:93], v[166:169], v[206:209], v[90:93]
	v_mfma_f32_16x16x32_bf16 v[86:89], v[170:173], v[202:205], v[86:89]
	v_mfma_f32_16x16x32_bf16 v[86:89], v[174:177], v[206:209], v[86:89]
	v_mfma_f32_16x16x32_bf16 v[82:85], v[178:181], v[202:205], v[82:85]
	v_mfma_f32_16x16x32_bf16 v[82:85], v[182:185], v[206:209], v[82:85]
	v_mfma_f32_16x16x32_bf16 v[78:81], v[146:149], v[210:213], v[78:81]
	v_mfma_f32_16x16x32_bf16 v[78:81], v[150:153], v[214:217], v[78:81]
	v_mfma_f32_16x16x32_bf16 v[74:77], v[162:165], v[210:213], v[74:77]
	v_mfma_f32_16x16x32_bf16 v[74:77], v[166:169], v[214:217], v[74:77]
	v_mfma_f32_16x16x32_bf16 v[70:73], v[170:173], v[210:213], v[70:73]
	v_mfma_f32_16x16x32_bf16 v[70:73], v[174:177], v[214:217], v[70:73]
	v_mfma_f32_16x16x32_bf16 v[66:69], v[178:181], v[210:213], v[66:69]
	v_mfma_f32_16x16x32_bf16 v[66:69], v[182:185], v[214:217], v[66:69]
	s_barrier
; #define PG8_STAGE(bufoff, gbase, voff) do { _Pragma("unroll") for (int _i = 0; _i < 2; ++_i) \
;         __builtin_amdgcn_global_load_lds((const unsigned*)((const char*)(gbase) + (voff)[_i]), (LAS unsigned*)(lds + (bufoff) + ldsw + _i * 8192), 16, 0, 0); } while (0)
; #define PG8_LDA(dst, off) do { _Pragma("unroll") for (int m = 0; m < 4; ++m) _Pragma("unroll") for (int k = 0; k < 2; ++k) dst[m][k] = *(const LAS bf16x8*)(lds + (off) + aoff + m * 2048 + k * 1024); } while (0)
; #define PG8_MMA(ai, bj, At, Bt) do { __builtin_amdgcn_s_setprio(1); _Pragma("unroll") for (int m = 0; m < 4; ++m) _Pragma("unroll") for (int n = 0; n < 2; ++n) _Pragma("unroll") for (int k = 0; k < 2; ++k) \
;         acc[ai][bj][m][n] = __builtin_amdgcn_mfma_f32_16x16x32_bf16(Bt[n][k], At[m][k], acc[ai][bj][m][n], 0, 0, 0); __builtin_amdgcn_s_setprio(0); } while (0)
; #define PG8_WAIT_V(n) asm volatile("s_waitcnt vmcnt(" #n ")" ::: "memory")
; #define PG8_WAIT_L(n) asm volatile("s_waitcnt lgkmcnt(" #n ")" ::: "memory")
; #define PG8_BAR __builtin_amdgcn_s_barrier()
; #define PG8_SCHED __builtin_amdgcn_sched_barrier(0)
; template <class Epi, bool ALIGN_EPI = true>
; __device__ __forceinline__ void gemm_phase(LAS unsigned char* lds, const Gemm g, const StaticOrder& S, const Epi& E) {
;     ...
;             PG8_LDA(At, PG8_SA1(1)); PG8_STAGE(PG8_SB(1, 0), b3, voffB); PG8_STAGE(PG8_SB(1, 1), b3 + hstep, voffB);
;             PG8_WAIT_V(8); PG8_WAIT_L(0); PG8_BAR; PG8_MMA(1, 0, At, B0); PG8_MMA(1, 1, At, B1); PG8_BAR; PG8_SCHED;
;             { const int t_ = o0; o0 = o2; o2 = o1; o1 = t_; }
;         }
;         if constexpr (ALIGN_EPI) { if (wr == 0) PG8_BAR; }
	s_add_i32 s44, s70, s35
	v_lshl_add_u64 v[154:155], v[220:221], 0, s[24:25]
	s_mov_b32 m0, s44
	ds_read_b128 v[186:189], v157 offset:16384
	ds_read_b128 v[190:193], v157 offset:17408
	ds_read_b128 v[194:197], v157 offset:18432
	ds_read_b128 v[198:201], v157 offset:19456
	ds_read_b128 v[202:205], v157 offset:20480
	ds_read_b128 v[206:209], v157 offset:21504
	ds_read_b128 v[210:213], v157 offset:22528
	ds_read_b128 v[214:217], v157 offset:23552
	global_load_lds_dwordx4 v[154:155], off
	s_add_i32 m0, s44, 0x2000
	s_add_u32 s12, s12, 0x100080
	v_lshl_add_u64 v[154:155], v[222:223], 0, s[24:25]
	s_addc_u32 s13, s13, 0
	s_add_i32 s44, s71, s35
	global_load_lds_dwordx4 v[154:155], off
	v_lshl_add_u64 v[154:155], s[12:13], 0, v[132:133]
	s_mov_b32 m0, s44
	s_nop 0
	global_load_lds_dwordx4 v[154:155], off
	v_lshl_add_u64 v[154:155], s[12:13], 0, v[136:137]
	s_add_i32 m0, s44, 0x2000
	s_nop 0
	global_load_lds_dwordx4 v[154:155], off
	s_waitcnt vmcnt(8)
	s_waitcnt lgkmcnt(0)
	s_barrier
	s_waitcnt lgkmcnt(0)
	v_mfma_f32_16x16x32_bf16 v[62:65], v[146:149], v[186:189], v[62:65]
	v_mfma_f32_16x16x32_bf16 v[62:65], v[150:153], v[190:193], v[62:65]
	v_mfma_f32_16x16x32_bf16 v[58:61], v[162:165], v[186:189], v[58:61]
	v_mfma_f32_16x16x32_bf16 v[58:61], v[166:169], v[190:193], v[58:61]
	v_mfma_f32_16x16x32_bf16 v[54:57], v[170:173], v[186:189], v[54:57]
	v_mfma_f32_16x16x32_bf16 v[54:57], v[174:177], v[190:193], v[54:57]
	v_mfma_f32_16x16x32_bf16 v[50:53], v[178:181], v[186:189], v[50:53]
	v_mfma_f32_16x16x32_bf16 v[50:53], v[182:185], v[190:193], v[50:53]
	v_mfma_f32_16x16x32_bf16 v[46:49], v[146:149], v[194:197], v[46:49]
	v_mfma_f32_16x16x32_bf16 v[46:49], v[150:153], v[198:201], v[46:49]
	v_mfma_f32_16x16x32_bf16 v[42:45], v[162:165], v[194:197], v[42:45]
	v_mfma_f32_16x16x32_bf16 v[42:45], v[166:169], v[198:201], v[42:45]
	v_mfma_f32_16x16x32_bf16 v[38:41], v[170:173], v[194:197], v[38:41]
	v_mfma_f32_16x16x32_bf16 v[38:41], v[174:177], v[198:201], v[38:41]
	v_mfma_f32_16x16x32_bf16 v[34:37], v[178:181], v[194:197], v[34:37]
	v_mfma_f32_16x16x32_bf16 v[34:37], v[182:185], v[198:201], v[34:37]
	v_mfma_f32_16x16x32_bf16 v[30:33], v[146:149], v[202:205], v[30:33]
	v_mfma_f32_16x16x32_bf16 v[30:33], v[150:153], v[206:209], v[30:33]
	v_mfma_f32_16x16x32_bf16 v[26:29], v[162:165], v[202:205], v[26:29]
	v_mfma_f32_16x16x32_bf16 v[26:29], v[166:169], v[206:209], v[26:29]
	v_mfma_f32_16x16x32_bf16 v[22:25], v[170:173], v[202:205], v[22:25]
	v_mfma_f32_16x16x32_bf16 v[22:25], v[174:177], v[206:209], v[22:25]
	v_mfma_f32_16x16x32_bf16 v[18:21], v[178:181], v[202:205], v[18:21]
	v_mfma_f32_16x16x32_bf16 v[18:21], v[182:185], v[206:209], v[18:21]
	v_mfma_f32_16x16x32_bf16 v[14:17], v[146:149], v[210:213], v[14:17]
	v_mfma_f32_16x16x32_bf16 v[14:17], v[150:153], v[214:217], v[14:17]
	v_mfma_f32_16x16x32_bf16 v[10:13], v[162:165], v[210:213], v[10:13]
	v_mfma_f32_16x16x32_bf16 v[10:13], v[166:169], v[214:217], v[10:13]
	v_mfma_f32_16x16x32_bf16 v[6:9], v[170:173], v[210:213], v[6:9]
	v_mfma_f32_16x16x32_bf16 v[6:9], v[174:177], v[214:217], v[6:9]
	v_mfma_f32_16x16x32_bf16 v[2:5], v[178:181], v[210:213], v[2:5]
	v_mfma_f32_16x16x32_bf16 v[2:5], v[182:185], v[214:217], v[2:5]
	s_barrier
	s_add_i32 s69, s69, 2
	s_add_u32 s10, s10, 0x100
	s_addc_u32 s11, s11, 0
	s_add_u32 s39, s39, 0x100
	s_addc_u32 s68, s68, 0
	s_cmp_gt_u32 s69, 61
	s_mov_b32 s12, s67
	s_cbranch_scc0 .LBB0_221
	s_setprio 0
	s_and_b64 vcc, exec, s[26:27]
	s_cbranch_vccz .LBB0_224
	s_barrier

; #define PG8_STAGE(bufoff, gbase, voff) do { _Pragma("unroll") for (int _i = 0; _i < 2; ++_i) \
;         __builtin_amdgcn_global_load_lds((const unsigned*)((const char*)(gbase) + (voff)[_i]), (LAS unsigned*)(lds + (bufoff) + ldsw + _i * 8192), 16, 0, 0); } while (0)
; #define PG8_LDA(dst, off) do { _Pragma("unroll") for (int m = 0; m < 4; ++m) _Pragma("unroll") for (int k = 0; k < 2; ++k) dst[m][k] = *(const LAS bf16x8*)(lds + (off) + aoff + m * 2048 + k * 1024); } while (0)
; template <class Epi, bool ALIGN_EPI = true>
; __device__ __forceinline__ void gemm_phase(LAS unsigned char* lds, const Gemm g, const StaticOrder& S, const Epi& E) {
;     ...
;     Unit cur, nxt; int ui = 0;
;     if (!S.next(0, cur)) return;
;     Acc acc;
; #pragma unroll
;     for (int a = 0; a < 2; ++a)
; #pragma unroll
;         for (int b = 0; b < 2; ++b)
; #pragma unroll
;             for (int m = 0; m < 4; ++m)
; #pragma unroll
;                 for (int n = 0; n < 2; ++n) acc[a][b][m][n] = (f32x4){0.f, 0.f, 0.f, 0.f};
;     bf16x8 At[4][2], B0[2][2], B1[2][2];
;     const char* cA = PG8_ABASE(cur); const char* cB = PG8_BBASE(cur);
;     int o0 = 6 * HTB, o1 = 7 * HTB, o2 = 8 * HTB;
;     PG8_STAGE(PG8_SB(0, 0), cB, voffB); PG8_STAGE(PG8_SB(0, 1), cB + hstep, voffB); PG8_STAGE(o0, cA, voffA); PG8_STAGE(PG8_SA1(0), cA + hstep, voffA);
;     if (wr == 1) PG8_BAR;
;     PG8_WAIT_V(2); PG8_BAR;
;     PG8_STAGE(PG8_SB(1, 0), cB + kstep, voffB); PG8_STAGE(o1, cA + kstep, voffA); PG8_STAGE(PG8_SB(1, 1), cB + hstep + kstep, voffB);
;     PG8_WAIT_V(6); PG8_BAR;
;     for (;;) {
;         const bool has_next = S.next(ui + 1, nxt);
;         const char* nA = has_next ? PG8_ABASE(nxt) : cA; const char* nB = has_next ? PG8_BBASE(nxt) : cB;
;         for (int t = 0; t < nt; t += 2) {
;             const bool last = (t == nt - 2);
;             const char* a1 = cA + (size_t)(t + 1) * kstep;
;             const char* a2 = last ? nA : cA + (size_t)(t + 2) * kstep; const char* b2 = last ? nB : cB + (size_t)(t + 2) * kstep;
;             const char* a3 = a2 + kstep; const char* b3 = b2 + kstep;
;             PG8_LDB(B0, 0, 0); PG8_LDB(B1, 0, 1); PG8_SCHED; PG8_LDA(At, o0); PG8_STAGE(PG8_SA1(1), a1 + hstep, voffA); PG8_STAGE(o2, a2, voffA);
;             PG8_WAIT_V(10); PG8_WAIT_L(0); PG8_BAR; PG8_MMA(0, 0, At, B0); PG8_MMA(0, 1, At, B1); PG8_BAR; PG8_SCHED;
.LBB0_609:
	s_ashr_i32 s25, s24, 31
	s_lshl_b64 s[26:27], s[24:25], 20
	s_add_u32 s26, s88, s26
	s_addc_u32 s27, s89, s27
	s_and_b64 s[28:29], s[2:3], exec
	s_cselect_b32 s25, s27, s41
	s_cselect_b32 s58, s26, s40
	s_ashr_i32 s23, s22, 31
	s_lshl_b64 s[28:29], s[22:23], 20
	v_readlane_b32 s36, v252, 5
	v_readlane_b32 s37, v252, 6
	s_add_u32 s28, s36, s28
	s_addc_u32 s29, s37, s29
	s_and_b64 s[44:45], s[2:3], exec
	s_cselect_b32 s23, s29, s43
	s_cselect_b32 s59, s28, s42
	s_add_u32 s40, s40, 0x80080
	s_addc_u32 s41, s41, 0
	s_add_u32 s60, s42, 0x100
	v_mov_b32_e32 v2, 0
	s_addc_u32 s61, s43, 0
	s_mov_b32 s62, -2
	s_mov_b32 s42, s56
	v_mov_b32_e32 v3, v2
	v_mov_b32_e32 v4, v2
	v_mov_b32_e32 v5, v2
	v_mov_b32_e32 v6, v2
	v_mov_b32_e32 v7, v2
	v_mov_b32_e32 v8, v2
	v_mov_b32_e32 v9, v2
	v_mov_b32_e32 v18, v2
	v_mov_b32_e32 v19, v2
	v_mov_b32_e32 v20, v2
	v_mov_b32_e32 v21, v2
	v_mov_b32_e32 v22, v2
	v_mov_b32_e32 v23, v2
	v_mov_b32_e32 v24, v2
	v_mov_b32_e32 v25, v2
	v_mov_b32_e32 v34, v2
	v_mov_b32_e32 v35, v2
	v_mov_b32_e32 v36, v2
	v_mov_b32_e32 v37, v2
	v_mov_b32_e32 v38, v2
	v_mov_b32_e32 v39, v2
	v_mov_b32_e32 v40, v2
	v_mov_b32_e32 v41, v2
	v_mov_b32_e32 v50, v2
	v_mov_b32_e32 v51, v2
	v_mov_b32_e32 v52, v2
	v_mov_b32_e32 v53, v2
	v_mov_b32_e32 v54, v2
	v_mov_b32_e32 v55, v2
	v_mov_b32_e32 v56, v2
	v_mov_b32_e32 v57, v2
	v_mov_b32_e32 v10, v2
	v_mov_b32_e32 v11, v2
	v_mov_b32_e32 v12, v2
	v_mov_b32_e32 v13, v2
	v_mov_b32_e32 v14, v2
	v_mov_b32_e32 v15, v2
	v_mov_b32_e32 v16, v2
	v_mov_b32_e32 v17, v2
	v_mov_b32_e32 v26, v2
	v_mov_b32_e32 v27, v2
	v_mov_b32_e32 v28, v2
	v_mov_b32_e32 v29, v2
	v_mov_b32_e32 v30, v2
	v_mov_b32_e32 v31, v2
	v_mov_b32_e32 v32, v2
	v_mov_b32_e32 v33, v2
	v_mov_b32_e32 v42, v2
	v_mov_b32_e32 v43, v2
	v_mov_b32_e32 v44, v2
	v_mov_b32_e32 v45, v2
	v_mov_b32_e32 v46, v2
	v_mov_b32_e32 v47, v2
	v_mov_b32_e32 v48, v2
	v_mov_b32_e32 v49, v2
	v_mov_b32_e32 v58, v2
	v_mov_b32_e32 v59, v2
	v_mov_b32_e32 v60, v2
	v_mov_b32_e32 v61, v2
	v_mov_b32_e32 v62, v2
	v_mov_b32_e32 v63, v2
	v_mov_b32_e32 v64, v2
	v_mov_b32_e32 v65, v2
	v_mov_b32_e32 v66, v2
	v_mov_b32_e32 v67, v2
	v_mov_b32_e32 v68, v2
	v_mov_b32_e32 v69, v2
	v_mov_b32_e32 v70, v2
	v_mov_b32_e32 v71, v2
	v_mov_b32_e32 v72, v2
	v_mov_b32_e32 v73, v2
	v_mov_b32_e32 v90, v2
	v_mov_b32_e32 v91, v2
	v_mov_b32_e32 v92, v2
	v_mov_b32_e32 v93, v2
	v_mov_b32_e32 v94, v2
	v_mov_b32_e32 v95, v2
	v_mov_b32_e32 v96, v2
	v_mov_b32_e32 v97, v2
	v_mov_b32_e32 v114, v2
	v_mov_b32_e32 v115, v2
	v_mov_b32_e32 v116, v2
	v_mov_b32_e32 v117, v2
	v_mov_b32_e32 v118, v2
	v_mov_b32_e32 v119, v2
	v_mov_b32_e32 v120, v2
	v_mov_b32_e32 v121, v2
	v_mov_b32_e32 v138, v2
	v_mov_b32_e32 v139, v2
	v_mov_b32_e32 v140, v2
	v_mov_b32_e32 v141, v2
	v_mov_b32_e32 v142, v2
	v_mov_b32_e32 v143, v2
	v_mov_b32_e32 v144, v2
	v_mov_b32_e32 v145, v2
	v_mov_b32_e32 v78, v2
	v_mov_b32_e32 v79, v2
	v_mov_b32_e32 v80, v2
	v_mov_b32_e32 v81, v2
	v_mov_b32_e32 v82, v2
	v_mov_b32_e32 v83, v2
	v_mov_b32_e32 v84, v2
	v_mov_b32_e32 v85, v2
	v_mov_b32_e32 v102, v2
	v_mov_b32_e32 v103, v2
	v_mov_b32_e32 v104, v2
	v_mov_b32_e32 v105, v2
	v_mov_b32_e32 v106, v2
	v_mov_b32_e32 v107, v2
	v_mov_b32_e32 v108, v2
	v_mov_b32_e32 v109, v2
	v_mov_b32_e32 v126, v2
	v_mov_b32_e32 v127, v2
	v_mov_b32_e32 v128, v2
	v_mov_b32_e32 v129, v2
	v_mov_b32_e32 v130, v2
	v_mov_b32_e32 v131, v2
	v_mov_b32_e32 v132, v2
	v_mov_b32_e32 v133, v2
	v_mov_b32_e32 v74, v2
	v_mov_b32_e32 v75, v2
	v_mov_b32_e32 v76, v2
	v_mov_b32_e32 v77, v2
	v_mov_b32_e32 v86, v2
	v_mov_b32_e32 v87, v2
	v_mov_b32_e32 v88, v2
	v_mov_b32_e32 v89, v2
	s_and_b64 vcc, exec, s[8:9]
	s_cbranch_vccz .Lkprio_skip_P5
	s_setprio 1
.Lkprio_skip_P5:
.LBB0_610:
	ds_read_b128 v[98:101], v209 offset:32768
	ds_read_b128 v[110:113], v209 offset:33792
	ds_read_b128 v[122:125], v209 offset:34816
	ds_read_b128 v[134:137], v209 offset:35840
	ds_read_b128 v[146:149], v209 offset:49152
	ds_read_b128 v[150:153], v209 offset:50176
	ds_read_b128 v[154:157], v209 offset:51200
	ds_read_b128 v[158:161], v209 offset:52224
	s_mov_b32 s56, s54
	s_mov_b32 s54, s52
	s_mov_b32 s52, s42
	s_add_u32 s42, s40, 0xfff80080
	s_addc_u32 s43, s41, -1
	s_cmp_eq_u32 s62, 28
	s_cselect_b32 s44, s58, s42
	s_cselect_b32 s42, s59, s60
	s_cselect_b32 s45, s25, s43
	s_cselect_b32 s43, s23, s61
	v_add_u32_e32 v210, s52, v207
	v_lshl_add_u64 v[214:215], s[40:41], 0, v[182:183]
	s_add_i32 m0, s39, 0x4000
	ds_read_b128 v[162:165], v210
	ds_read_b128 v[166:169], v210 offset:1024
	ds_read_b128 v[170:173], v210 offset:2048
	ds_read_b128 v[190:193], v210 offset:3072
	ds_read_b128 v[194:197], v210 offset:4096
	ds_read_b128 v[198:201], v210 offset:5120
	ds_read_b128 v[202:205], v210 offset:6144
	ds_read_b128 v[210:213], v210 offset:7168
	global_load_lds_dwordx4 v[214:215], off
	v_lshl_add_u64 v[214:215], s[40:41], 0, v[184:185]
	s_add_i32 m0, s39, 0x6000
	s_add_i32 s63, s39, s56
	global_load_lds_dwordx4 v[214:215], off
	v_lshl_add_u64 v[214:215], s[44:45], 0, v[174:175]
	s_mov_b32 m0, s63
	v_lshl_add_u64 v[216:217], s[44:45], 0, v[178:179]
	global_load_lds_dwordx4 v[214:215], off
	s_add_i32 m0, s63, 0x2000
	s_nop 0
	global_load_lds_dwordx4 v[216:217], off
	s_waitcnt vmcnt(10)
	s_waitcnt lgkmcnt(0)
	s_barrier
; #define PG8_STAGE(bufoff, gbase, voff) do { _Pragma("unroll") for (int _i = 0; _i < 2; ++_i) \
;         __builtin_amdgcn_global_load_lds((const unsigned*)((const char*)(gbase) + (voff)[_i]), (LAS unsigned*)(lds + (bufoff) + ldsw + _i * 8192), 16, 0, 0); } while (0)
; #define PG8_LDA(dst, off) do { _Pragma("unroll") for (int m = 0; m < 4; ++m) _Pragma("unroll") for (int k = 0; k < 2; ++k) dst[m][k] = *(const LAS bf16x8*)(lds + (off) + aoff + m * 2048 + k * 1024); } while (0)
; #define PG8_MMA(ai, bj, At, Bt) do { __builtin_amdgcn_s_setprio(1); _Pragma("unroll") for (int m = 0; m < 4; ++m) _Pragma("unroll") for (int n = 0; n < 2; ++n) _Pragma("unroll") for (int k = 0; k < 2; ++k) \
;         acc[ai][bj][m][n] = __builtin_amdgcn_mfma_f32_16x16x32_bf16(Bt[n][k], At[m][k], acc[ai][bj][m][n], 0, 0, 0); __builtin_amdgcn_s_setprio(0); } while (0)
; #define PG8_WAIT_V(n) asm volatile("s_waitcnt vmcnt(" #n ")" ::: "memory")
; #define PG8_WAIT_L(n) asm volatile("s_waitcnt lgkmcnt(" #n ")" ::: "memory")
; #define PG8_BAR __builtin_amdgcn_s_barrier()
; #define PG8_SCHED __builtin_amdgcn_sched_barrier(0)
; template <class Epi, bool ALIGN_EPI = true>
; __device__ __forceinline__ void gemm_phase(LAS unsigned char* lds, const Gemm g, const StaticOrder& S, const Epi& E) {
;     ...
;             PG8_WAIT_V(10); PG8_WAIT_L(0); PG8_BAR; PG8_MMA(0, 0, At, B0); PG8_MMA(0, 1, At, B1); PG8_BAR; PG8_SCHED;
;             PG8_LDA(At, PG8_SA1(0)); PG8_STAGE(PG8_SB(0, 0), b2, voffB); PG8_STAGE(PG8_SB(0, 1), b2 + hstep, voffB);
;             PG8_WAIT_V(8); PG8_WAIT_L(0); PG8_BAR; PG8_MMA(1, 0, At, B0); PG8_MMA(1, 1, At, B1); PG8_BAR; PG8_SCHED;
	s_waitcnt lgkmcnt(0)
	v_mfma_f32_16x16x32_bf16 v[86:89], v[98:101], v[162:165], v[86:89]
	v_mfma_f32_16x16x32_bf16 v[86:89], v[110:113], v[166:169], v[86:89]
	v_mfma_f32_16x16x32_bf16 v[74:77], v[122:125], v[162:165], v[74:77]
	v_mfma_f32_16x16x32_bf16 v[74:77], v[134:137], v[166:169], v[74:77]
	v_mfma_f32_16x16x32_bf16 v[142:145], v[146:149], v[162:165], v[142:145]
	v_mfma_f32_16x16x32_bf16 v[142:145], v[150:153], v[166:169], v[142:145]
	v_mfma_f32_16x16x32_bf16 v[138:141], v[154:157], v[162:165], v[138:141]
	v_mfma_f32_16x16x32_bf16 v[138:141], v[158:161], v[166:169], v[138:141]
	v_mfma_f32_16x16x32_bf16 v[130:133], v[98:101], v[170:173], v[130:133]
	v_mfma_f32_16x16x32_bf16 v[130:133], v[110:113], v[190:193], v[130:133]
	v_mfma_f32_16x16x32_bf16 v[126:129], v[122:125], v[170:173], v[126:129]
	v_mfma_f32_16x16x32_bf16 v[126:129], v[134:137], v[190:193], v[126:129]
	v_mfma_f32_16x16x32_bf16 v[118:121], v[146:149], v[170:173], v[118:121]
	v_mfma_f32_16x16x32_bf16 v[118:121], v[150:153], v[190:193], v[118:121]
	v_mfma_f32_16x16x32_bf16 v[114:117], v[154:157], v[170:173], v[114:117]
	v_mfma_f32_16x16x32_bf16 v[114:117], v[158:161], v[190:193], v[114:117]
	v_mfma_f32_16x16x32_bf16 v[106:109], v[98:101], v[194:197], v[106:109]
	v_mfma_f32_16x16x32_bf16 v[106:109], v[110:113], v[198:201], v[106:109]
	v_mfma_f32_16x16x32_bf16 v[102:105], v[122:125], v[194:197], v[102:105]
	v_mfma_f32_16x16x32_bf16 v[102:105], v[134:137], v[198:201], v[102:105]
	v_mfma_f32_16x16x32_bf16 v[94:97], v[146:149], v[194:197], v[94:97]
	v_mfma_f32_16x16x32_bf16 v[94:97], v[150:153], v[198:201], v[94:97]
	v_mfma_f32_16x16x32_bf16 v[90:93], v[154:157], v[194:197], v[90:93]
	v_mfma_f32_16x16x32_bf16 v[90:93], v[158:161], v[198:201], v[90:93]
	v_mfma_f32_16x16x32_bf16 v[82:85], v[98:101], v[202:205], v[82:85]
	v_mfma_f32_16x16x32_bf16 v[82:85], v[110:113], v[210:213], v[82:85]
	v_mfma_f32_16x16x32_bf16 v[78:81], v[122:125], v[202:205], v[78:81]
	v_mfma_f32_16x16x32_bf16 v[78:81], v[134:137], v[210:213], v[78:81]
	v_mfma_f32_16x16x32_bf16 v[70:73], v[146:149], v[202:205], v[70:73]
	v_mfma_f32_16x16x32_bf16 v[70:73], v[150:153], v[210:213], v[70:73]
	v_mfma_f32_16x16x32_bf16 v[66:69], v[154:157], v[202:205], v[66:69]
	v_mfma_f32_16x16x32_bf16 v[66:69], v[158:161], v[210:213], v[66:69]
	s_barrier
	s_mov_b32 m0, s46
	v_lshl_add_u64 v[218:219], s[42:43], 0, v[176:177]
	s_add_u32 s64, s42, 0x80000
	ds_read_b128 v[162:165], v207
	ds_read_b128 v[166:169], v207 offset:1024
	ds_read_b128 v[170:173], v207 offset:2048
	ds_read_b128 v[190:193], v207 offset:3072
	ds_read_b128 v[194:197], v207 offset:4096
	ds_read_b128 v[198:201], v207 offset:5120
	ds_read_b128 v[202:205], v207 offset:6144
	ds_read_b128 v[210:213], v207 offset:7168
	global_load_lds_dwordx4 v[218:219], off
	v_lshl_add_u64 v[220:221], s[42:43], 0, v[180:181]
	s_mov_b32 m0, s47
	s_addc_u32 s65, s43, 0
	global_load_lds_dwordx4 v[220:221], off
	v_lshl_add_u64 v[222:223], s[64:65], 0, v[176:177]
	s_mov_b32 m0, s48
	s_nop 0
	global_load_lds_dwordx4 v[222:223], off
	v_lshl_add_u64 v[222:223], s[64:65], 0, v[180:181]
	s_mov_b32 m0, s49
	s_nop 0
	global_load_lds_dwordx4 v[222:223], off
	s_waitcnt vmcnt(8)
	s_waitcnt lgkmcnt(0)
	s_barrier
	s_waitcnt lgkmcnt(0)
	v_mfma_f32_16x16x32_bf16 v[62:65], v[98:101], v[162:165], v[62:65]
	v_mfma_f32_16x16x32_bf16 v[62:65], v[110:113], v[166:169], v[62:65]
	v_mfma_f32_16x16x32_bf16 v[58:61], v[122:125], v[162:165], v[58:61]
	v_mfma_f32_16x16x32_bf16 v[58:61], v[134:137], v[166:169], v[58:61]
	v_mfma_f32_16x16x32_bf16 v[54:57], v[146:149], v[162:165], v[54:57]
	v_mfma_f32_16x16x32_bf16 v[54:57], v[150:153], v[166:169], v[54:57]
	v_mfma_f32_16x16x32_bf16 v[50:53], v[154:157], v[162:165], v[50:53]
	v_mfma_f32_16x16x32_bf16 v[50:53], v[158:161], v[166:169], v[50:53]
	v_mfma_f32_16x16x32_bf16 v[46:49], v[98:101], v[170:173], v[46:49]
	v_mfma_f32_16x16x32_bf16 v[46:49], v[110:113], v[190:193], v[46:49]
	v_mfma_f32_16x16x32_bf16 v[42:45], v[122:125], v[170:173], v[42:45]
	v_mfma_f32_16x16x32_bf16 v[42:45], v[134:137], v[190:193], v[42:45]
	v_mfma_f32_16x16x32_bf16 v[38:41], v[146:149], v[170:173], v[38:41]
	v_mfma_f32_16x16x32_bf16 v[38:41], v[150:153], v[190:193], v[38:41]
	v_mfma_f32_16x16x32_bf16 v[34:37], v[154:157], v[170:173], v[34:37]
	v_mfma_f32_16x16x32_bf16 v[34:37], v[158:161], v[190:193], v[34:37]
	v_mfma_f32_16x16x32_bf16 v[30:33], v[98:101], v[194:197], v[30:33]
	v_mfma_f32_16x16x32_bf16 v[30:33], v[110:113], v[198:201], v[30:33]
	v_mfma_f32_16x16x32_bf16 v[26:29], v[122:125], v[194:197], v[26:29]
	v_mfma_f32_16x16x32_bf16 v[26:29], v[134:137], v[198:201], v[26:29]
	v_mfma_f32_16x16x32_bf16 v[22:25], v[146:149], v[194:197], v[22:25]
	v_mfma_f32_16x16x32_bf16 v[22:25], v[150:153], v[198:201], v[22:25]
	v_mfma_f32_16x16x32_bf16 v[18:21], v[154:157], v[194:197], v[18:21]
	v_mfma_f32_16x16x32_bf16 v[18:21], v[158:161], v[198:201], v[18:21]
	v_mfma_f32_16x16x32_bf16 v[14:17], v[98:101], v[202:205], v[14:17]
	v_mfma_f32_16x16x32_bf16 v[14:17], v[110:113], v[210:213], v[14:17]
	v_mfma_f32_16x16x32_bf16 v[10:13], v[122:125], v[202:205], v[10:13]
	v_mfma_f32_16x16x32_bf16 v[10:13], v[134:137], v[210:213], v[10:13]
	v_mfma_f32_16x16x32_bf16 v[6:9], v[146:149], v[202:205], v[6:9]
	v_mfma_f32_16x16x32_bf16 v[6:9], v[150:153], v[210:213], v[6:9]
	v_mfma_f32_16x16x32_bf16 v[2:5], v[154:157], v[202:205], v[2:5]
	v_mfma_f32_16x16x32_bf16 v[2:5], v[158:161], v[210:213], v[2:5]
	s_barrier
; #define PG8_STAGE(bufoff, gbase, voff) do { _Pragma("unroll") for (int _i = 0; _i < 2; ++_i) \
;         __builtin_amdgcn_global_load_lds((const unsigned*)((const char*)(gbase) + (voff)[_i]), (LAS unsigned*)(lds + (bufoff) + ldsw + _i * 8192), 16, 0, 0); } while (0)
; #define PG8_LDA(dst, off) do { _Pragma("unroll") for (int m = 0; m < 4; ++m) _Pragma("unroll") for (int k = 0; k < 2; ++k) dst[m][k] = *(const LAS bf16x8*)(lds + (off) + aoff + m * 2048 + k * 1024); } while (0)
; #define PG8_LDB(dst, b, h) do { _Pragma("unroll") for (int n = 0; n < 2; ++n) _Pragma("unroll") for (int k = 0; k < 2; ++k) dst[n][k] = *(const LAS bf16x8*)(lds + PG8_SB(b, h) + boff + n * 2048 + k * 1024); } while (0)
; #define PG8_MMA(ai, bj, At, Bt) do { __builtin_amdgcn_s_setprio(1); _Pragma("unroll") for (int m = 0; m < 4; ++m) _Pragma("unroll") for (int n = 0; n < 2; ++n) _Pragma("unroll") for (int k = 0; k < 2; ++k) \
;         acc[ai][bj][m][n] = __builtin_amdgcn_mfma_f32_16x16x32_bf16(Bt[n][k], At[m][k], acc[ai][bj][m][n], 0, 0, 0); __builtin_amdgcn_s_setprio(0); } while (0)
; #define PG8_WAIT_V(n) asm volatile("s_waitcnt vmcnt(" #n ")" ::: "memory")
; #define PG8_WAIT_L(n) asm volatile("s_waitcnt lgkmcnt(" #n ")" ::: "memory")
; #define PG8_BAR __builtin_amdgcn_s_barrier()
; #define PG8_SCHED __builtin_amdgcn_sched_barrier(0)
; template <class Epi, bool ALIGN_EPI = true>
; __device__ __forceinline__ void gemm_phase(LAS unsigned char* lds, const Gemm g, const StaticOrder& S, const Epi& E) {
;     ...
;             PG8_LDB(B0, 1, 0); PG8_LDB(B1, 1, 1); PG8_SCHED; PG8_LDA(At, o1); PG8_STAGE(PG8_SA1(0), a2 + hstep, voffA); PG8_STAGE(o0, a3, voffA);
;             PG8_WAIT_V(10); PG8_WAIT_L(0); PG8_BAR; PG8_MMA(0, 0, At, B0); PG8_MMA(0, 1, At, B1); PG8_BAR; PG8_SCHED;
	s_add_i32 s63, 0, 0x10000
	s_add_i32 s64, 0, 0x14000
	v_add_u32_e32 v134, s63, v206
	v_add_u32_e32 v158, s64, v206
	ds_read_b128 v[98:101], v134
	ds_read_b128 v[110:113], v134 offset:1024
	ds_read_b128 v[122:125], v134 offset:2048
	ds_read_b128 v[134:137], v134 offset:3072
	ds_read_b128 v[146:149], v158
	ds_read_b128 v[150:153], v158 offset:1024
	ds_read_b128 v[154:157], v158 offset:2048
	ds_read_b128 v[158:161], v158 offset:3072
	s_add_u32 s44, s44, 0x80000
	s_addc_u32 s45, s45, 0
	s_mov_b32 m0, s39
	v_add_u32_e32 v210, s54, v207
	v_lshl_add_u64 v[222:223], s[44:45], 0, v[174:175]
	ds_read_b128 v[162:165], v210
	ds_read_b128 v[166:169], v210 offset:1024
	ds_read_b128 v[170:173], v210 offset:2048
	ds_read_b128 v[190:193], v210 offset:3072
	ds_read_b128 v[194:197], v210 offset:4096
	ds_read_b128 v[198:201], v210 offset:5120
	ds_read_b128 v[202:205], v210 offset:6144
	ds_read_b128 v[210:213], v210 offset:7168
	global_load_lds_dwordx4 v[222:223], off
	v_lshl_add_u64 v[222:223], s[44:45], 0, v[178:179]
	s_mov_b32 m0, s50
	s_add_i32 s44, s39, s52
	global_load_lds_dwordx4 v[222:223], off
	v_lshl_add_u64 v[214:215], v[214:215], 0, s[10:11]
	s_mov_b32 m0, s44
	s_nop 0
	global_load_lds_dwordx4 v[214:215], off
	v_lshl_add_u64 v[214:215], v[216:217], 0, s[10:11]
	s_add_i32 m0, s44, 0x2000
	s_nop 0
	global_load_lds_dwordx4 v[214:215], off
	s_waitcnt vmcnt(10)
	s_waitcnt lgkmcnt(0)
	s_barrier
	s_waitcnt lgkmcnt(0)
	v_mfma_f32_16x16x32_bf16 v[86:89], v[98:101], v[162:165], v[86:89]
	v_mfma_f32_16x16x32_bf16 v[86:89], v[110:113], v[166:169], v[86:89]
	v_mfma_f32_16x16x32_bf16 v[74:77], v[122:125], v[162:165], v[74:77]
	v_mfma_f32_16x16x32_bf16 v[74:77], v[134:137], v[166:169], v[74:77]
	v_mfma_f32_16x16x32_bf16 v[142:145], v[146:149], v[162:165], v[142:145]
	v_mfma_f32_16x16x32_bf16 v[142:145], v[150:153], v[166:169], v[142:145]
	v_mfma_f32_16x16x32_bf16 v[138:141], v[154:157], v[162:165], v[138:141]
	v_mfma_f32_16x16x32_bf16 v[138:141], v[158:161], v[166:169], v[138:141]
	v_mfma_f32_16x16x32_bf16 v[130:133], v[98:101], v[170:173], v[130:133]
	v_mfma_f32_16x16x32_bf16 v[130:133], v[110:113], v[190:193], v[130:133]
	v_mfma_f32_16x16x32_bf16 v[126:129], v[122:125], v[170:173], v[126:129]
	v_mfma_f32_16x16x32_bf16 v[126:129], v[134:137], v[190:193], v[126:129]
	v_mfma_f32_16x16x32_bf16 v[118:121], v[146:149], v[170:173], v[118:121]
	v_mfma_f32_16x16x32_bf16 v[118:121], v[150:153], v[190:193], v[118:121]
	v_mfma_f32_16x16x32_bf16 v[114:117], v[154:157], v[170:173], v[114:117]
	v_mfma_f32_16x16x32_bf16 v[114:117], v[158:161], v[190:193], v[114:117]
	v_mfma_f32_16x16x32_bf16 v[106:109], v[98:101], v[194:197], v[106:109]
	v_mfma_f32_16x16x32_bf16 v[106:109], v[110:113], v[198:201], v[106:109]
	v_mfma_f32_16x16x32_bf16 v[102:105], v[122:125], v[194:197], v[102:105]
	v_mfma_f32_16x16x32_bf16 v[102:105], v[134:137], v[198:201], v[102:105]
	v_mfma_f32_16x16x32_bf16 v[94:97], v[146:149], v[194:197], v[94:97]
	v_mfma_f32_16x16x32_bf16 v[94:97], v[150:153], v[198:201], v[94:97]
	v_mfma_f32_16x16x32_bf16 v[90:93], v[154:157], v[194:197], v[90:93]
	v_mfma_f32_16x16x32_bf16 v[90:93], v[158:161], v[198:201], v[90:93]
	v_mfma_f32_16x16x32_bf16 v[82:85], v[98:101], v[202:205], v[82:85]
	v_mfma_f32_16x16x32_bf16 v[82:85], v[110:113], v[210:213], v[82:85]
	v_mfma_f32_16x16x32_bf16 v[78:81], v[122:125], v[202:205], v[78:81]
	v_mfma_f32_16x16x32_bf16 v[78:81], v[134:137], v[210:213], v[78:81]
	v_mfma_f32_16x16x32_bf16 v[70:73], v[146:149], v[202:205], v[70:73]
	v_mfma_f32_16x16x32_bf16 v[70:73], v[150:153], v[210:213], v[70:73]
	v_mfma_f32_16x16x32_bf16 v[66:69], v[154:157], v[202:205], v[66:69]
	v_mfma_f32_16x16x32_bf16 v[66:69], v[158:161], v[210:213], v[66:69]
	s_barrier
; #define PG8_STAGE(bufoff, gbase, voff) do { _Pragma("unroll") for (int _i = 0; _i < 2; ++_i) \
;         __builtin_amdgcn_global_load_lds((const unsigned*)((const char*)(gbase) + (voff)[_i]), (LAS unsigned*)(lds + (bufoff) + ldsw + _i * 8192), 16, 0, 0); } while (0)
; #define PG8_LDA(dst, off) do { _Pragma("unroll") for (int m = 0; m < 4; ++m) _Pragma("unroll") for (int k = 0; k < 2; ++k) dst[m][k] = *(const LAS bf16x8*)(lds + (off) + aoff + m * 2048 + k * 1024); } while (0)
; #define PG8_MMA(ai, bj, At, Bt) do { __builtin_amdgcn_s_setprio(1); _Pragma("unroll") for (int m = 0; m < 4; ++m) _Pragma("unroll") for (int n = 0; n < 2; ++n) _Pragma("unroll") for (int k = 0; k < 2; ++k) \
;         acc[ai][bj][m][n] = __builtin_amdgcn_mfma_f32_16x16x32_bf16(Bt[n][k], At[m][k], acc[ai][bj][m][n], 0, 0, 0); __builtin_amdgcn_s_setprio(0); } while (0)
; #define PG8_WAIT_V(n) asm volatile("s_waitcnt vmcnt(" #n ")" ::: "memory")
; #define PG8_WAIT_L(n) asm volatile("s_waitcnt lgkmcnt(" #n ")" ::: "memory")
; #define PG8_BAR __builtin_amdgcn_s_barrier()
; #define PG8_SCHED __builtin_amdgcn_sched_barrier(0)
; template <class Epi, bool ALIGN_EPI = true>
; __device__ __forceinline__ void gemm_phase(LAS unsigned char* lds, const Gemm g, const StaticOrder& S, const Epi& E) {
;     ...
;             PG8_LDA(At, PG8_SA1(1)); PG8_STAGE(PG8_SB(1, 0), b3, voffB); PG8_STAGE(PG8_SB(1, 1), b3 + hstep, voffB);
;             PG8_WAIT_V(8); PG8_WAIT_L(0); PG8_BAR; PG8_MMA(1, 0, At, B0); PG8_MMA(1, 1, At, B1); PG8_BAR; PG8_SCHED;
;             { const int t_ = o0; o0 = o2; o2 = o1; o1 = t_; }
;         }
;         if constexpr (ALIGN_EPI) { if (wr == 0) PG8_BAR; }
	s_add_i32 s44, s63, s35
	v_lshl_add_u64 v[214:215], v[218:219], 0, s[10:11]
	s_mov_b32 m0, s44
	ds_read_b128 v[162:165], v207 offset:16384
	ds_read_b128 v[166:169], v207 offset:17408
	ds_read_b128 v[170:173], v207 offset:18432
	ds_read_b128 v[190:193], v207 offset:19456
	ds_read_b128 v[194:197], v207 offset:20480
	ds_read_b128 v[198:201], v207 offset:21504
	ds_read_b128 v[202:205], v207 offset:22528
	ds_read_b128 v[210:213], v207 offset:23552
	global_load_lds_dwordx4 v[214:215], off
	s_add_i32 m0, s44, 0x2000
	s_add_u32 s42, s42, 0x80080
	v_lshl_add_u64 v[214:215], v[220:221], 0, s[10:11]
	s_addc_u32 s43, s43, 0
	s_add_i32 s44, s64, s35
	global_load_lds_dwordx4 v[214:215], off
	v_lshl_add_u64 v[214:215], s[42:43], 0, v[176:177]
	s_mov_b32 m0, s44
	s_nop 0
	global_load_lds_dwordx4 v[214:215], off
	v_lshl_add_u64 v[214:215], s[42:43], 0, v[180:181]
	s_add_i32 m0, s44, 0x2000
	s_nop 0
	global_load_lds_dwordx4 v[214:215], off
	s_waitcnt vmcnt(8)
	s_waitcnt lgkmcnt(0)
	s_barrier
	s_waitcnt lgkmcnt(0)
	v_mfma_f32_16x16x32_bf16 v[62:65], v[98:101], v[162:165], v[62:65]
	v_mfma_f32_16x16x32_bf16 v[62:65], v[110:113], v[166:169], v[62:65]
	v_mfma_f32_16x16x32_bf16 v[58:61], v[122:125], v[162:165], v[58:61]
	v_mfma_f32_16x16x32_bf16 v[58:61], v[134:137], v[166:169], v[58:61]
	v_mfma_f32_16x16x32_bf16 v[54:57], v[146:149], v[162:165], v[54:57]
	v_mfma_f32_16x16x32_bf16 v[54:57], v[150:153], v[166:169], v[54:57]
	v_mfma_f32_16x16x32_bf16 v[50:53], v[154:157], v[162:165], v[50:53]
	v_mfma_f32_16x16x32_bf16 v[50:53], v[158:161], v[166:169], v[50:53]
	v_mfma_f32_16x16x32_bf16 v[46:49], v[98:101], v[170:173], v[46:49]
	v_mfma_f32_16x16x32_bf16 v[46:49], v[110:113], v[190:193], v[46:49]
	v_mfma_f32_16x16x32_bf16 v[42:45], v[122:125], v[170:173], v[42:45]
	v_mfma_f32_16x16x32_bf16 v[42:45], v[134:137], v[190:193], v[42:45]
	v_mfma_f32_16x16x32_bf16 v[38:41], v[146:149], v[170:173], v[38:41]
	v_mfma_f32_16x16x32_bf16 v[38:41], v[150:153], v[190:193], v[38:41]
	v_mfma_f32_16x16x32_bf16 v[34:37], v[154:157], v[170:173], v[34:37]
	v_mfma_f32_16x16x32_bf16 v[34:37], v[158:161], v[190:193], v[34:37]
	v_mfma_f32_16x16x32_bf16 v[30:33], v[98:101], v[194:197], v[30:33]
	v_mfma_f32_16x16x32_bf16 v[30:33], v[110:113], v[198:201], v[30:33]
	v_mfma_f32_16x16x32_bf16 v[26:29], v[122:125], v[194:197], v[26:29]
	v_mfma_f32_16x16x32_bf16 v[26:29], v[134:137], v[198:201], v[26:29]
	v_mfma_f32_16x16x32_bf16 v[22:25], v[146:149], v[194:197], v[22:25]
	v_mfma_f32_16x16x32_bf16 v[22:25], v[150:153], v[198:201], v[22:25]
	v_mfma_f32_16x16x32_bf16 v[18:21], v[154:157], v[194:197], v[18:21]
	v_mfma_f32_16x16x32_bf16 v[18:21], v[158:161], v[198:201], v[18:21]
	v_mfma_f32_16x16x32_bf16 v[14:17], v[98:101], v[202:205], v[14:17]
	v_mfma_f32_16x16x32_bf16 v[14:17], v[110:113], v[210:213], v[14:17]
	v_mfma_f32_16x16x32_bf16 v[10:13], v[122:125], v[202:205], v[10:13]
	v_mfma_f32_16x16x32_bf16 v[10:13], v[134:137], v[210:213], v[10:13]
	v_mfma_f32_16x16x32_bf16 v[6:9], v[146:149], v[202:205], v[6:9]
	v_mfma_f32_16x16x32_bf16 v[6:9], v[150:153], v[210:213], v[6:9]
	v_mfma_f32_16x16x32_bf16 v[2:5], v[154:157], v[202:205], v[2:5]
	v_mfma_f32_16x16x32_bf16 v[2:5], v[158:161], v[210:213], v[2:5]
	s_barrier
	s_add_i32 s62, s62, 2
	s_add_u32 s40, s40, 0x100
	s_addc_u32 s41, s41, 0
	s_add_u32 s60, s60, 0x100
	s_addc_u32 s61, s61, 0
	s_cmp_gt_u32 s62, 29
	s_mov_b32 s42, s56
	s_cbranch_scc0 .LBB0_610
	s_setprio 0
	s_and_b64 vcc, exec, s[12:13]
	s_cbranch_vccz .LBB0_613
	s_barrier

; #define PG8_STAGE(bufoff, gbase, voff) do { _Pragma("unroll") for (int _i = 0; _i < 2; ++_i) \
;         __builtin_amdgcn_global_load_lds((const unsigned*)((const char*)(gbase) + (voff)[_i]), (LAS unsigned*)(lds + (bufoff) + ldsw + _i * 8192), 16, 0, 0); } while (0)
; #define PG8_LDA(dst, off) do { _Pragma("unroll") for (int m = 0; m < 4; ++m) _Pragma("unroll") for (int k = 0; k < 2; ++k) dst[m][k] = *(const LAS bf16x8*)(lds + (off) + aoff + m * 2048 + k * 1024); } while (0)
; template <class Epi, bool ALIGN_EPI = true>
; __device__ __forceinline__ void gemm_phase(LAS unsigned char* lds, const Gemm g, const StaticOrder& S, const Epi& E) {
;     ...
;     Unit cur, nxt; int ui = 0;
;     if (!S.next(0, cur)) return;
;     Acc acc;
; #pragma unroll
;     for (int a = 0; a < 2; ++a)
; #pragma unroll
;         for (int b = 0; b < 2; ++b)
; #pragma unroll
;             for (int m = 0; m < 4; ++m)
; #pragma unroll
;                 for (int n = 0; n < 2; ++n) acc[a][b][m][n] = (f32x4){0.f, 0.f, 0.f, 0.f};
;     bf16x8 At[4][2], B0[2][2], B1[2][2];
;     const char* cA = PG8_ABASE(cur); const char* cB = PG8_BBASE(cur);
;     int o0 = 6 * HTB, o1 = 7 * HTB, o2 = 8 * HTB;
;     PG8_STAGE(PG8_SB(0, 0), cB, voffB); PG8_STAGE(PG8_SB(0, 1), cB + hstep, voffB); PG8_STAGE(o0, cA, voffA); PG8_STAGE(PG8_SA1(0), cA + hstep, voffA);
;     if (wr == 1) PG8_BAR;
;     PG8_WAIT_V(2); PG8_BAR;
;     PG8_STAGE(PG8_SB(1, 0), cB + kstep, voffB); PG8_STAGE(o1, cA + kstep, voffA); PG8_STAGE(PG8_SB(1, 1), cB + hstep + kstep, voffB);
;     PG8_WAIT_V(6); PG8_BAR;
;     for (;;) {
;         const bool has_next = S.next(ui + 1, nxt);
;         const char* nA = has_next ? PG8_ABASE(nxt) : cA; const char* nB = has_next ? PG8_BBASE(nxt) : cB;
;         for (int t = 0; t < nt; t += 2) {
;             const bool last = (t == nt - 2);
;             const char* a1 = cA + (size_t)(t + 1) * kstep;
;             const char* a2 = last ? nA : cA + (size_t)(t + 2) * kstep; const char* b2 = last ? nB : cB + (size_t)(t + 2) * kstep;
;             const char* a3 = a2 + kstep; const char* b3 = b2 + kstep;
;             PG8_LDB(B0, 0, 0); PG8_LDB(B1, 0, 1); PG8_SCHED; PG8_LDA(At, o0); PG8_STAGE(PG8_SA1(1), a1 + hstep, voffA); PG8_STAGE(o2, a2, voffA);
;             PG8_WAIT_V(10); PG8_WAIT_L(0); PG8_BAR; PG8_MMA(0, 0, At, B0); PG8_MMA(0, 1, At, B1); PG8_BAR; PG8_SCHED;
.LBB0_688:
	s_ashr_i32 s41, s40, 31
	s_and_b32 s60, s59, 1
	s_lshl_b64 s[42:43], s[40:41], 20
	s_cmp_eq_u32 s60, 0
	v_readlane_b32 s36, v252, 7
	v_readlane_b32 s44, v252, 9
	s_cselect_b32 s41, s4, s0
	v_readlane_b32 s37, v252, 8
	v_readlane_b32 s45, v252, 10
	s_cselect_b32 s39, s5, s1
	s_cselect_b32 s46, s36, s44
	s_cselect_b32 s47, s37, s45
	s_add_u32 s42, s41, s42
	s_addc_u32 s43, s39, s43
	s_and_b64 s[44:45], s[2:3], exec
	s_cselect_b32 s41, s43, s11
	s_cselect_b32 s62, s42, s10
	s_ashr_i32 s39, s38, 31
	s_lshl_b64 s[44:45], s[38:39], 20
	s_add_u32 s44, s46, s44
	s_addc_u32 s45, s47, s45
	s_and_b64 s[46:47], s[2:3], exec
	s_cselect_b32 s39, s45, s13
	s_cselect_b32 s63, s44, s12
	s_add_u32 s10, s10, 0x80080
	s_addc_u32 s11, s11, 0
	s_add_u32 s64, s12, 0x100
	v_mov_b32_e32 v2, 0
	s_addc_u32 s65, s13, 0
	s_mov_b32 s66, -2
	s_mov_b32 s12, s61
	v_mov_b32_e32 v3, v2
	v_mov_b32_e32 v4, v2
	v_mov_b32_e32 v5, v2
	v_mov_b32_e32 v6, v2
	v_mov_b32_e32 v7, v2
	v_mov_b32_e32 v8, v2
	v_mov_b32_e32 v9, v2
	v_mov_b32_e32 v18, v2
	v_mov_b32_e32 v19, v2
	v_mov_b32_e32 v20, v2
	v_mov_b32_e32 v21, v2
	v_mov_b32_e32 v22, v2
	v_mov_b32_e32 v23, v2
	v_mov_b32_e32 v24, v2
	v_mov_b32_e32 v25, v2
	v_mov_b32_e32 v34, v2
	v_mov_b32_e32 v35, v2
	v_mov_b32_e32 v36, v2
	v_mov_b32_e32 v37, v2
	v_mov_b32_e32 v38, v2
	v_mov_b32_e32 v39, v2
	v_mov_b32_e32 v40, v2
	v_mov_b32_e32 v41, v2
	v_mov_b32_e32 v50, v2
	v_mov_b32_e32 v51, v2
	v_mov_b32_e32 v52, v2
	v_mov_b32_e32 v53, v2
	v_mov_b32_e32 v54, v2
	v_mov_b32_e32 v55, v2
	v_mov_b32_e32 v56, v2
	v_mov_b32_e32 v57, v2
	v_mov_b32_e32 v10, v2
	v_mov_b32_e32 v11, v2
	v_mov_b32_e32 v12, v2
	v_mov_b32_e32 v13, v2
	v_mov_b32_e32 v14, v2
	v_mov_b32_e32 v15, v2
	v_mov_b32_e32 v16, v2
	v_mov_b32_e32 v17, v2
	v_mov_b32_e32 v26, v2
	v_mov_b32_e32 v27, v2
	v_mov_b32_e32 v28, v2
	v_mov_b32_e32 v29, v2
	v_mov_b32_e32 v30, v2
	v_mov_b32_e32 v31, v2
	v_mov_b32_e32 v32, v2
	v_mov_b32_e32 v33, v2
	v_mov_b32_e32 v42, v2
	v_mov_b32_e32 v43, v2
	v_mov_b32_e32 v44, v2
	v_mov_b32_e32 v45, v2
	v_mov_b32_e32 v46, v2
	v_mov_b32_e32 v47, v2
	v_mov_b32_e32 v48, v2
	v_mov_b32_e32 v49, v2
	v_mov_b32_e32 v58, v2
	v_mov_b32_e32 v59, v2
	v_mov_b32_e32 v60, v2
	v_mov_b32_e32 v61, v2
	v_mov_b32_e32 v62, v2
	v_mov_b32_e32 v63, v2
	v_mov_b32_e32 v64, v2
	v_mov_b32_e32 v65, v2
	v_mov_b32_e32 v66, v2
	v_mov_b32_e32 v67, v2
	v_mov_b32_e32 v68, v2
	v_mov_b32_e32 v69, v2
	v_mov_b32_e32 v70, v2
	v_mov_b32_e32 v71, v2
	v_mov_b32_e32 v72, v2
	v_mov_b32_e32 v73, v2
	v_mov_b32_e32 v82, v2
	v_mov_b32_e32 v83, v2
	v_mov_b32_e32 v84, v2
	v_mov_b32_e32 v85, v2
	v_mov_b32_e32 v86, v2
	v_mov_b32_e32 v87, v2
	v_mov_b32_e32 v88, v2
	v_mov_b32_e32 v89, v2
	v_mov_b32_e32 v98, v2
	v_mov_b32_e32 v99, v2
	v_mov_b32_e32 v100, v2
	v_mov_b32_e32 v101, v2
	v_mov_b32_e32 v102, v2
	v_mov_b32_e32 v103, v2
	v_mov_b32_e32 v104, v2
	v_mov_b32_e32 v105, v2
	v_mov_b32_e32 v114, v2
	v_mov_b32_e32 v115, v2
	v_mov_b32_e32 v116, v2
	v_mov_b32_e32 v117, v2
	v_mov_b32_e32 v118, v2
	v_mov_b32_e32 v119, v2
	v_mov_b32_e32 v120, v2
	v_mov_b32_e32 v121, v2
	v_mov_b32_e32 v74, v2
	v_mov_b32_e32 v75, v2
	v_mov_b32_e32 v76, v2
	v_mov_b32_e32 v77, v2
	v_mov_b32_e32 v78, v2
	v_mov_b32_e32 v79, v2
	v_mov_b32_e32 v80, v2
	v_mov_b32_e32 v81, v2
	v_mov_b32_e32 v90, v2
	v_mov_b32_e32 v91, v2
	v_mov_b32_e32 v92, v2
	v_mov_b32_e32 v93, v2
	v_mov_b32_e32 v94, v2
	v_mov_b32_e32 v95, v2
	v_mov_b32_e32 v96, v2
	v_mov_b32_e32 v97, v2
	v_mov_b32_e32 v106, v2
	v_mov_b32_e32 v107, v2
	v_mov_b32_e32 v108, v2
	v_mov_b32_e32 v109, v2
	v_mov_b32_e32 v110, v2
	v_mov_b32_e32 v111, v2
	v_mov_b32_e32 v112, v2
	v_mov_b32_e32 v113, v2
	v_mov_b32_e32 v122, v2
	v_mov_b32_e32 v123, v2
	v_mov_b32_e32 v124, v2
	v_mov_b32_e32 v125, v2
	v_mov_b32_e32 v126, v2
	v_mov_b32_e32 v127, v2
	v_mov_b32_e32 v128, v2
	v_mov_b32_e32 v129, v2
	s_and_b64 vcc, exec, s[22:23]
	s_cbranch_vccz .Lkprio_skip_P6
	s_setprio 1
.Lkprio_skip_P6:
.LBB0_689:
	ds_read_b128 v[130:133], v215 offset:32768
	ds_read_b128 v[134:137], v215 offset:33792
	ds_read_b128 v[138:141], v215 offset:34816
	ds_read_b128 v[142:145], v215 offset:35840
	ds_read_b128 v[146:149], v215 offset:49152
	ds_read_b128 v[150:153], v215 offset:50176
	ds_read_b128 v[154:157], v215 offset:51200
	ds_read_b128 v[158:161], v215 offset:52224
	s_mov_b32 s61, s57
	s_mov_b32 s57, s56
	s_mov_b32 s56, s12
	s_add_u32 s12, s10, 0xfff80080
	s_addc_u32 s13, s11, -1
	s_cmp_eq_u32 s66, 28
	s_cselect_b32 s46, s62, s12
	s_cselect_b32 s12, s63, s64
	s_cselect_b32 s47, s41, s13
	s_cselect_b32 s13, s39, s65
	v_add_u32_e32 v206, s56, v213
	v_lshl_add_u64 v[210:211], s[10:11], 0, v[186:187]
	s_add_i32 m0, s49, 0x4000
	ds_read_b128 v[162:165], v206
	ds_read_b128 v[166:169], v206 offset:1024
	ds_read_b128 v[170:173], v206 offset:2048
	ds_read_b128 v[174:177], v206 offset:3072
	ds_read_b128 v[194:197], v206 offset:4096
	ds_read_b128 v[198:201], v206 offset:5120
	ds_read_b128 v[202:205], v206 offset:6144
	ds_read_b128 v[206:209], v206 offset:7168
	global_load_lds_dwordx4 v[210:211], off
	v_lshl_add_u64 v[210:211], s[10:11], 0, v[188:189]
	s_add_i32 m0, s49, 0x6000
	s_add_i32 s67, s49, s61
	global_load_lds_dwordx4 v[210:211], off
	v_lshl_add_u64 v[210:211], s[46:47], 0, v[178:179]
	s_mov_b32 m0, s67
	v_lshl_add_u64 v[216:217], s[46:47], 0, v[182:183]
	global_load_lds_dwordx4 v[210:211], off
	s_add_i32 m0, s67, 0x2000
	s_nop 0
	global_load_lds_dwordx4 v[216:217], off
	s_waitcnt vmcnt(10)
	s_waitcnt lgkmcnt(0)
	s_barrier
; #define PG8_STAGE(bufoff, gbase, voff) do { _Pragma("unroll") for (int _i = 0; _i < 2; ++_i) \
;         __builtin_amdgcn_global_load_lds((const unsigned*)((const char*)(gbase) + (voff)[_i]), (LAS unsigned*)(lds + (bufoff) + ldsw + _i * 8192), 16, 0, 0); } while (0)
; #define PG8_LDA(dst, off) do { _Pragma("unroll") for (int m = 0; m < 4; ++m) _Pragma("unroll") for (int k = 0; k < 2; ++k) dst[m][k] = *(const LAS bf16x8*)(lds + (off) + aoff + m * 2048 + k * 1024); } while (0)
; #define PG8_MMA(ai, bj, At, Bt) do { __builtin_amdgcn_s_setprio(1); _Pragma("unroll") for (int m = 0; m < 4; ++m) _Pragma("unroll") for (int n = 0; n < 2; ++n) _Pragma("unroll") for (int k = 0; k < 2; ++k) \
;         acc[ai][bj][m][n] = __builtin_amdgcn_mfma_f32_16x16x32_bf16(Bt[n][k], At[m][k], acc[ai][bj][m][n], 0, 0, 0); __builtin_amdgcn_s_setprio(0); } while (0)
; #define PG8_WAIT_V(n) asm volatile("s_waitcnt vmcnt(" #n ")" ::: "memory")
; #define PG8_WAIT_L(n) asm volatile("s_waitcnt lgkmcnt(" #n ")" ::: "memory")
; #define PG8_BAR __builtin_amdgcn_s_barrier()
; #define PG8_SCHED __builtin_amdgcn_sched_barrier(0)
; template <class Epi, bool ALIGN_EPI = true>
; __device__ __forceinline__ void gemm_phase(LAS unsigned char* lds, const Gemm g, const StaticOrder& S, const Epi& E) {
;     ...
;             PG8_WAIT_V(10); PG8_WAIT_L(0); PG8_BAR; PG8_MMA(0, 0, At, B0); PG8_MMA(0, 1, At, B1); PG8_BAR; PG8_SCHED;
;             PG8_LDA(At, PG8_SA1(0)); PG8_STAGE(PG8_SB(0, 0), b2, voffB); PG8_STAGE(PG8_SB(0, 1), b2 + hstep, voffB);
;             PG8_WAIT_V(8); PG8_WAIT_L(0); PG8_BAR; PG8_MMA(1, 0, At, B0); PG8_MMA(1, 1, At, B1); PG8_BAR; PG8_SCHED;
	s_waitcnt lgkmcnt(0)
	v_mfma_f32_16x16x32_bf16 v[126:129], v[130:133], v[162:165], v[126:129]
	v_mfma_f32_16x16x32_bf16 v[126:129], v[134:137], v[166:169], v[126:129]
	v_mfma_f32_16x16x32_bf16 v[122:125], v[138:141], v[162:165], v[122:125]
	v_mfma_f32_16x16x32_bf16 v[122:125], v[142:145], v[166:169], v[122:125]
	v_mfma_f32_16x16x32_bf16 v[118:121], v[146:149], v[162:165], v[118:121]
	v_mfma_f32_16x16x32_bf16 v[118:121], v[150:153], v[166:169], v[118:121]
	v_mfma_f32_16x16x32_bf16 v[114:117], v[154:157], v[162:165], v[114:117]
	v_mfma_f32_16x16x32_bf16 v[114:117], v[158:161], v[166:169], v[114:117]
	v_mfma_f32_16x16x32_bf16 v[110:113], v[130:133], v[170:173], v[110:113]
	v_mfma_f32_16x16x32_bf16 v[110:113], v[134:137], v[174:177], v[110:113]
	v_mfma_f32_16x16x32_bf16 v[106:109], v[138:141], v[170:173], v[106:109]
	v_mfma_f32_16x16x32_bf16 v[106:109], v[142:145], v[174:177], v[106:109]
	v_mfma_f32_16x16x32_bf16 v[102:105], v[146:149], v[170:173], v[102:105]
	v_mfma_f32_16x16x32_bf16 v[102:105], v[150:153], v[174:177], v[102:105]
	v_mfma_f32_16x16x32_bf16 v[98:101], v[154:157], v[170:173], v[98:101]
	v_mfma_f32_16x16x32_bf16 v[98:101], v[158:161], v[174:177], v[98:101]
	v_mfma_f32_16x16x32_bf16 v[94:97], v[130:133], v[194:197], v[94:97]
	v_mfma_f32_16x16x32_bf16 v[94:97], v[134:137], v[198:201], v[94:97]
	v_mfma_f32_16x16x32_bf16 v[90:93], v[138:141], v[194:197], v[90:93]
	v_mfma_f32_16x16x32_bf16 v[90:93], v[142:145], v[198:201], v[90:93]
	v_mfma_f32_16x16x32_bf16 v[86:89], v[146:149], v[194:197], v[86:89]
	v_mfma_f32_16x16x32_bf16 v[86:89], v[150:153], v[198:201], v[86:89]
	v_mfma_f32_16x16x32_bf16 v[82:85], v[154:157], v[194:197], v[82:85]
	v_mfma_f32_16x16x32_bf16 v[82:85], v[158:161], v[198:201], v[82:85]
	v_mfma_f32_16x16x32_bf16 v[78:81], v[130:133], v[202:205], v[78:81]
	v_mfma_f32_16x16x32_bf16 v[78:81], v[134:137], v[206:209], v[78:81]
	v_mfma_f32_16x16x32_bf16 v[74:77], v[138:141], v[202:205], v[74:77]
	v_mfma_f32_16x16x32_bf16 v[74:77], v[142:145], v[206:209], v[74:77]
	v_mfma_f32_16x16x32_bf16 v[70:73], v[146:149], v[202:205], v[70:73]
	v_mfma_f32_16x16x32_bf16 v[70:73], v[150:153], v[206:209], v[70:73]
	v_mfma_f32_16x16x32_bf16 v[66:69], v[154:157], v[202:205], v[66:69]
	v_mfma_f32_16x16x32_bf16 v[66:69], v[158:161], v[206:209], v[66:69]
	s_barrier
	s_mov_b32 m0, s50
	v_lshl_add_u64 v[218:219], s[12:13], 0, v[180:181]
	s_add_u32 s68, s12, 0x80000
	ds_read_b128 v[162:165], v213
	ds_read_b128 v[166:169], v213 offset:1024
	ds_read_b128 v[170:173], v213 offset:2048
	ds_read_b128 v[174:177], v213 offset:3072
	ds_read_b128 v[194:197], v213 offset:4096
	ds_read_b128 v[198:201], v213 offset:5120
	ds_read_b128 v[202:205], v213 offset:6144
	ds_read_b128 v[206:209], v213 offset:7168
	global_load_lds_dwordx4 v[218:219], off
	v_lshl_add_u64 v[220:221], s[12:13], 0, v[184:185]
	s_mov_b32 m0, s51
	s_addc_u32 s69, s13, 0
	global_load_lds_dwordx4 v[220:221], off
	v_lshl_add_u64 v[222:223], s[68:69], 0, v[180:181]
	s_mov_b32 m0, s52
	s_nop 0
	global_load_lds_dwordx4 v[222:223], off
	v_lshl_add_u64 v[222:223], s[68:69], 0, v[184:185]
	s_mov_b32 m0, s53
	s_nop 0
	global_load_lds_dwordx4 v[222:223], off
	s_waitcnt vmcnt(8)
	s_waitcnt lgkmcnt(0)
	s_barrier
	s_waitcnt lgkmcnt(0)
	v_mfma_f32_16x16x32_bf16 v[62:65], v[130:133], v[162:165], v[62:65]
	v_mfma_f32_16x16x32_bf16 v[62:65], v[134:137], v[166:169], v[62:65]
	v_mfma_f32_16x16x32_bf16 v[58:61], v[138:141], v[162:165], v[58:61]
	v_mfma_f32_16x16x32_bf16 v[58:61], v[142:145], v[166:169], v[58:61]
	v_mfma_f32_16x16x32_bf16 v[54:57], v[146:149], v[162:165], v[54:57]
	v_mfma_f32_16x16x32_bf16 v[54:57], v[150:153], v[166:169], v[54:57]
	v_mfma_f32_16x16x32_bf16 v[50:53], v[154:157], v[162:165], v[50:53]
	v_mfma_f32_16x16x32_bf16 v[50:53], v[158:161], v[166:169], v[50:53]
	v_mfma_f32_16x16x32_bf16 v[46:49], v[130:133], v[170:173], v[46:49]
	v_mfma_f32_16x16x32_bf16 v[46:49], v[134:137], v[174:177], v[46:49]
	v_mfma_f32_16x16x32_bf16 v[42:45], v[138:141], v[170:173], v[42:45]
	v_mfma_f32_16x16x32_bf16 v[42:45], v[142:145], v[174:177], v[42:45]
	v_mfma_f32_16x16x32_bf16 v[38:41], v[146:149], v[170:173], v[38:41]
	v_mfma_f32_16x16x32_bf16 v[38:41], v[150:153], v[174:177], v[38:41]
	v_mfma_f32_16x16x32_bf16 v[34:37], v[154:157], v[170:173], v[34:37]
	v_mfma_f32_16x16x32_bf16 v[34:37], v[158:161], v[174:177], v[34:37]
	v_mfma_f32_16x16x32_bf16 v[30:33], v[130:133], v[194:197], v[30:33]
	v_mfma_f32_16x16x32_bf16 v[30:33], v[134:137], v[198:201], v[30:33]
	v_mfma_f32_16x16x32_bf16 v[26:29], v[138:141], v[194:197], v[26:29]
	v_mfma_f32_16x16x32_bf16 v[26:29], v[142:145], v[198:201], v[26:29]
	v_mfma_f32_16x16x32_bf16 v[22:25], v[146:149], v[194:197], v[22:25]
	v_mfma_f32_16x16x32_bf16 v[22:25], v[150:153], v[198:201], v[22:25]
	v_mfma_f32_16x16x32_bf16 v[18:21], v[154:157], v[194:197], v[18:21]
	v_mfma_f32_16x16x32_bf16 v[18:21], v[158:161], v[198:201], v[18:21]
	v_mfma_f32_16x16x32_bf16 v[14:17], v[130:133], v[202:205], v[14:17]
	v_mfma_f32_16x16x32_bf16 v[14:17], v[134:137], v[206:209], v[14:17]
	v_mfma_f32_16x16x32_bf16 v[10:13], v[138:141], v[202:205], v[10:13]
	v_mfma_f32_16x16x32_bf16 v[10:13], v[142:145], v[206:209], v[10:13]
	v_mfma_f32_16x16x32_bf16 v[6:9], v[146:149], v[202:205], v[6:9]
	v_mfma_f32_16x16x32_bf16 v[6:9], v[150:153], v[206:209], v[6:9]
	v_mfma_f32_16x16x32_bf16 v[2:5], v[154:157], v[202:205], v[2:5]
	v_mfma_f32_16x16x32_bf16 v[2:5], v[158:161], v[206:209], v[2:5]
	s_barrier
; #define PG8_STAGE(bufoff, gbase, voff) do { _Pragma("unroll") for (int _i = 0; _i < 2; ++_i) \
;         __builtin_amdgcn_global_load_lds((const unsigned*)((const char*)(gbase) + (voff)[_i]), (LAS unsigned*)(lds + (bufoff) + ldsw + _i * 8192), 16, 0, 0); } while (0)
; #define PG8_LDA(dst, off) do { _Pragma("unroll") for (int m = 0; m < 4; ++m) _Pragma("unroll") for (int k = 0; k < 2; ++k) dst[m][k] = *(const LAS bf16x8*)(lds + (off) + aoff + m * 2048 + k * 1024); } while (0)
; #define PG8_LDB(dst, b, h) do { _Pragma("unroll") for (int n = 0; n < 2; ++n) _Pragma("unroll") for (int k = 0; k < 2; ++k) dst[n][k] = *(const LAS bf16x8*)(lds + PG8_SB(b, h) + boff + n * 2048 + k * 1024); } while (0)
; #define PG8_MMA(ai, bj, At, Bt) do { __builtin_amdgcn_s_setprio(1); _Pragma("unroll") for (int m = 0; m < 4; ++m) _Pragma("unroll") for (int n = 0; n < 2; ++n) _Pragma("unroll") for (int k = 0; k < 2; ++k) \
;         acc[ai][bj][m][n] = __builtin_amdgcn_mfma_f32_16x16x32_bf16(Bt[n][k], At[m][k], acc[ai][bj][m][n], 0, 0, 0); __builtin_amdgcn_s_setprio(0); } while (0)
; #define PG8_WAIT_V(n) asm volatile("s_waitcnt vmcnt(" #n ")" ::: "memory")
; #define PG8_WAIT_L(n) asm volatile("s_waitcnt lgkmcnt(" #n ")" ::: "memory")
; #define PG8_BAR __builtin_amdgcn_s_barrier()
; #define PG8_SCHED __builtin_amdgcn_sched_barrier(0)
; template <class Epi, bool ALIGN_EPI = true>
; __device__ __forceinline__ void gemm_phase(LAS unsigned char* lds, const Gemm g, const StaticOrder& S, const Epi& E) {
;     ...
;             PG8_LDB(B0, 1, 0); PG8_LDB(B1, 1, 1); PG8_SCHED; PG8_LDA(At, o1); PG8_STAGE(PG8_SA1(0), a2 + hstep, voffA); PG8_STAGE(o0, a3, voffA);
;             PG8_WAIT_V(10); PG8_WAIT_L(0); PG8_BAR; PG8_MMA(0, 0, At, B0); PG8_MMA(0, 1, At, B1); PG8_BAR; PG8_SCHED;
	s_add_i32 s67, 0, 0x10000
	s_add_i32 s68, 0, 0x14000
	v_add_u32_e32 v142, s67, v212
	v_add_u32_e32 v158, s68, v212
	ds_read_b128 v[130:133], v142
	ds_read_b128 v[134:137], v142 offset:1024
	ds_read_b128 v[138:141], v142 offset:2048
	ds_read_b128 v[142:145], v142 offset:3072
	ds_read_b128 v[146:149], v158
	ds_read_b128 v[150:153], v158 offset:1024
	ds_read_b128 v[154:157], v158 offset:2048
	ds_read_b128 v[158:161], v158 offset:3072
	s_add_u32 s46, s46, 0x80000
	s_addc_u32 s47, s47, 0
	s_mov_b32 m0, s49
	v_add_u32_e32 v206, s57, v213
	v_lshl_add_u64 v[222:223], s[46:47], 0, v[178:179]
	ds_read_b128 v[162:165], v206
	ds_read_b128 v[166:169], v206 offset:1024
	ds_read_b128 v[170:173], v206 offset:2048
	ds_read_b128 v[174:177], v206 offset:3072
	ds_read_b128 v[194:197], v206 offset:4096
	ds_read_b128 v[198:201], v206 offset:5120
	ds_read_b128 v[202:205], v206 offset:6144
	ds_read_b128 v[206:209], v206 offset:7168
	global_load_lds_dwordx4 v[222:223], off
	v_lshl_add_u64 v[222:223], s[46:47], 0, v[182:183]
	s_mov_b32 m0, s54
	s_add_i32 s46, s49, s56
	global_load_lds_dwordx4 v[222:223], off
	v_lshl_add_u64 v[210:211], v[210:211], 0, s[24:25]
	s_mov_b32 m0, s46
	s_nop 0
	global_load_lds_dwordx4 v[210:211], off
	v_lshl_add_u64 v[210:211], v[216:217], 0, s[24:25]
	s_add_i32 m0, s46, 0x2000
	s_nop 0
	global_load_lds_dwordx4 v[210:211], off
	s_waitcnt vmcnt(10)
	s_waitcnt lgkmcnt(0)
	s_barrier
	s_waitcnt lgkmcnt(0)
	v_mfma_f32_16x16x32_bf16 v[126:129], v[130:133], v[162:165], v[126:129]
	v_mfma_f32_16x16x32_bf16 v[126:129], v[134:137], v[166:169], v[126:129]
	v_mfma_f32_16x16x32_bf16 v[122:125], v[138:141], v[162:165], v[122:125]
	v_mfma_f32_16x16x32_bf16 v[122:125], v[142:145], v[166:169], v[122:125]
	v_mfma_f32_16x16x32_bf16 v[118:121], v[146:149], v[162:165], v[118:121]
	v_mfma_f32_16x16x32_bf16 v[118:121], v[150:153], v[166:169], v[118:121]
	v_mfma_f32_16x16x32_bf16 v[114:117], v[154:157], v[162:165], v[114:117]
	v_mfma_f32_16x16x32_bf16 v[114:117], v[158:161], v[166:169], v[114:117]
	v_mfma_f32_16x16x32_bf16 v[110:113], v[130:133], v[170:173], v[110:113]
	v_mfma_f32_16x16x32_bf16 v[110:113], v[134:137], v[174:177], v[110:113]
	v_mfma_f32_16x16x32_bf16 v[106:109], v[138:141], v[170:173], v[106:109]
	v_mfma_f32_16x16x32_bf16 v[106:109], v[142:145], v[174:177], v[106:109]
	v_mfma_f32_16x16x32_bf16 v[102:105], v[146:149], v[170:173], v[102:105]
	v_mfma_f32_16x16x32_bf16 v[102:105], v[150:153], v[174:177], v[102:105]
	v_mfma_f32_16x16x32_bf16 v[98:101], v[154:157], v[170:173], v[98:101]
	v_mfma_f32_16x16x32_bf16 v[98:101], v[158:161], v[174:177], v[98:101]
	v_mfma_f32_16x16x32_bf16 v[94:97], v[130:133], v[194:197], v[94:97]
	v_mfma_f32_16x16x32_bf16 v[94:97], v[134:137], v[198:201], v[94:97]
	v_mfma_f32_16x16x32_bf16 v[90:93], v[138:141], v[194:197], v[90:93]
	v_mfma_f32_16x16x32_bf16 v[90:93], v[142:145], v[198:201], v[90:93]
	v_mfma_f32_16x16x32_bf16 v[86:89], v[146:149], v[194:197], v[86:89]
	v_mfma_f32_16x16x32_bf16 v[86:89], v[150:153], v[198:201], v[86:89]
	v_mfma_f32_16x16x32_bf16 v[82:85], v[154:157], v[194:197], v[82:85]
	v_mfma_f32_16x16x32_bf16 v[82:85], v[158:161], v[198:201], v[82:85]
	v_mfma_f32_16x16x32_bf16 v[78:81], v[130:133], v[202:205], v[78:81]
	v_mfma_f32_16x16x32_bf16 v[78:81], v[134:137], v[206:209], v[78:81]
	v_mfma_f32_16x16x32_bf16 v[74:77], v[138:141], v[202:205], v[74:77]
	v_mfma_f32_16x16x32_bf16 v[74:77], v[142:145], v[206:209], v[74:77]
	v_mfma_f32_16x16x32_bf16 v[70:73], v[146:149], v[202:205], v[70:73]
	v_mfma_f32_16x16x32_bf16 v[70:73], v[150:153], v[206:209], v[70:73]
	v_mfma_f32_16x16x32_bf16 v[66:69], v[154:157], v[202:205], v[66:69]
	v_mfma_f32_16x16x32_bf16 v[66:69], v[158:161], v[206:209], v[66:69]
	s_barrier
; #define PG8_STAGE(bufoff, gbase, voff) do { _Pragma("unroll") for (int _i = 0; _i < 2; ++_i) \
;         __builtin_amdgcn_global_load_lds((const unsigned*)((const char*)(gbase) + (voff)[_i]), (LAS unsigned*)(lds + (bufoff) + ldsw + _i * 8192), 16, 0, 0); } while (0)
; #define PG8_LDA(dst, off) do { _Pragma("unroll") for (int m = 0; m < 4; ++m) _Pragma("unroll") for (int k = 0; k < 2; ++k) dst[m][k] = *(const LAS bf16x8*)(lds + (off) + aoff + m * 2048 + k * 1024); } while (0)
; #define PG8_MMA(ai, bj, At, Bt) do { __builtin_amdgcn_s_setprio(1); _Pragma("unroll") for (int m = 0; m < 4; ++m) _Pragma("unroll") for (int n = 0; n < 2; ++n) _Pragma("unroll") for (int k = 0; k < 2; ++k) \
;         acc[ai][bj][m][n] = __builtin_amdgcn_mfma_f32_16x16x32_bf16(Bt[n][k], At[m][k], acc[ai][bj][m][n], 0, 0, 0); __builtin_amdgcn_s_setprio(0); } while (0)
; #define PG8_WAIT_V(n) asm volatile("s_waitcnt vmcnt(" #n ")" ::: "memory")
; #define PG8_WAIT_L(n) asm volatile("s_waitcnt lgkmcnt(" #n ")" ::: "memory")
; #define PG8_BAR __builtin_amdgcn_s_barrier()
; #define PG8_SCHED __builtin_amdgcn_sched_barrier(0)
; template <class Epi, bool ALIGN_EPI = true>
; __device__ __forceinline__ void gemm_phase(LAS unsigned char* lds, const Gemm g, const StaticOrder& S, const Epi& E) {
;     ...
;             PG8_LDA(At, PG8_SA1(1)); PG8_STAGE(PG8_SB(1, 0), b3, voffB); PG8_STAGE(PG8_SB(1, 1), b3 + hstep, voffB);
;             PG8_WAIT_V(8); PG8_WAIT_L(0); PG8_BAR; PG8_MMA(1, 0, At, B0); PG8_MMA(1, 1, At, B1); PG8_BAR; PG8_SCHED;
;             { const int t_ = o0; o0 = o2; o2 = o1; o1 = t_; }
;         }
;         if constexpr (ALIGN_EPI) { if (wr == 0) PG8_BAR; }
	s_add_i32 s46, s67, s48
	v_lshl_add_u64 v[210:211], v[218:219], 0, s[24:25]
	s_mov_b32 m0, s46
	ds_read_b128 v[162:165], v213 offset:16384
	ds_read_b128 v[166:169], v213 offset:17408
	ds_read_b128 v[170:173], v213 offset:18432
	ds_read_b128 v[174:177], v213 offset:19456
	ds_read_b128 v[194:197], v213 offset:20480
	ds_read_b128 v[198:201], v213 offset:21504
	ds_read_b128 v[202:205], v213 offset:22528
	ds_read_b128 v[206:209], v213 offset:23552
	global_load_lds_dwordx4 v[210:211], off
	s_add_i32 m0, s46, 0x2000
	s_add_u32 s12, s12, 0x80080
	v_lshl_add_u64 v[210:211], v[220:221], 0, s[24:25]
	s_addc_u32 s13, s13, 0
	s_add_i32 s46, s68, s48
	global_load_lds_dwordx4 v[210:211], off
	v_lshl_add_u64 v[210:211], s[12:13], 0, v[180:181]
	s_mov_b32 m0, s46
	s_nop 0
	global_load_lds_dwordx4 v[210:211], off
	v_lshl_add_u64 v[210:211], s[12:13], 0, v[184:185]
	s_add_i32 m0, s46, 0x2000
	s_nop 0
	global_load_lds_dwordx4 v[210:211], off
	s_waitcnt vmcnt(8)
	s_waitcnt lgkmcnt(0)
	s_barrier
	s_waitcnt lgkmcnt(0)
	v_mfma_f32_16x16x32_bf16 v[62:65], v[130:133], v[162:165], v[62:65]
	v_mfma_f32_16x16x32_bf16 v[62:65], v[134:137], v[166:169], v[62:65]
	v_mfma_f32_16x16x32_bf16 v[58:61], v[138:141], v[162:165], v[58:61]
	v_mfma_f32_16x16x32_bf16 v[58:61], v[142:145], v[166:169], v[58:61]
	v_mfma_f32_16x16x32_bf16 v[54:57], v[146:149], v[162:165], v[54:57]
	v_mfma_f32_16x16x32_bf16 v[54:57], v[150:153], v[166:169], v[54:57]
	v_mfma_f32_16x16x32_bf16 v[50:53], v[154:157], v[162:165], v[50:53]
	v_mfma_f32_16x16x32_bf16 v[50:53], v[158:161], v[166:169], v[50:53]
	v_mfma_f32_16x16x32_bf16 v[46:49], v[130:133], v[170:173], v[46:49]
	v_mfma_f32_16x16x32_bf16 v[46:49], v[134:137], v[174:177], v[46:49]
	v_mfma_f32_16x16x32_bf16 v[42:45], v[138:141], v[170:173], v[42:45]
	v_mfma_f32_16x16x32_bf16 v[42:45], v[142:145], v[174:177], v[42:45]
	v_mfma_f32_16x16x32_bf16 v[38:41], v[146:149], v[170:173], v[38:41]
	v_mfma_f32_16x16x32_bf16 v[38:41], v[150:153], v[174:177], v[38:41]
	v_mfma_f32_16x16x32_bf16 v[34:37], v[154:157], v[170:173], v[34:37]
	v_mfma_f32_16x16x32_bf16 v[34:37], v[158:161], v[174:177], v[34:37]
	v_mfma_f32_16x16x32_bf16 v[30:33], v[130:133], v[194:197], v[30:33]
	v_mfma_f32_16x16x32_bf16 v[30:33], v[134:137], v[198:201], v[30:33]
	v_mfma_f32_16x16x32_bf16 v[26:29], v[138:141], v[194:197], v[26:29]
	v_mfma_f32_16x16x32_bf16 v[26:29], v[142:145], v[198:201], v[26:29]
	v_mfma_f32_16x16x32_bf16 v[22:25], v[146:149], v[194:197], v[22:25]
	v_mfma_f32_16x16x32_bf16 v[22:25], v[150:153], v[198:201], v[22:25]
	v_mfma_f32_16x16x32_bf16 v[18:21], v[154:157], v[194:197], v[18:21]
	v_mfma_f32_16x16x32_bf16 v[18:21], v[158:161], v[198:201], v[18:21]
	v_mfma_f32_16x16x32_bf16 v[14:17], v[130:133], v[202:205], v[14:17]
	v_mfma_f32_16x16x32_bf16 v[14:17], v[134:137], v[206:209], v[14:17]
	v_mfma_f32_16x16x32_bf16 v[10:13], v[138:141], v[202:205], v[10:13]
	v_mfma_f32_16x16x32_bf16 v[10:13], v[142:145], v[206:209], v[10:13]
	v_mfma_f32_16x16x32_bf16 v[6:9], v[146:149], v[202:205], v[6:9]
	v_mfma_f32_16x16x32_bf16 v[6:9], v[150:153], v[206:209], v[6:9]
	v_mfma_f32_16x16x32_bf16 v[2:5], v[154:157], v[202:205], v[2:5]
	v_mfma_f32_16x16x32_bf16 v[2:5], v[158:161], v[206:209], v[2:5]
	s_barrier
	s_add_i32 s66, s66, 2
	s_add_u32 s10, s10, 0x100
	s_addc_u32 s11, s11, 0
	s_add_u32 s64, s64, 0x100
	s_addc_u32 s65, s65, 0
	s_cmp_gt_u32 s66, 29
	s_mov_b32 s12, s61
	s_cbranch_scc0 .LBB0_689
	s_setprio 0
	s_and_b64 vcc, exec, s[26:27]
	s_cbranch_vccz .LBB0_692
	s_barrier

; #define PG8_STAGE(bufoff, gbase, voff) do { _Pragma("unroll") for (int _i = 0; _i < 2; ++_i) \
;         __builtin_amdgcn_global_load_lds((const unsigned*)((const char*)(gbase) + (voff)[_i]), (LAS unsigned*)(lds + (bufoff) + ldsw + _i * 8192), 16, 0, 0); } while (0)
; #define PG8_LDA(dst, off) do { _Pragma("unroll") for (int m = 0; m < 4; ++m) _Pragma("unroll") for (int k = 0; k < 2; ++k) dst[m][k] = *(const LAS bf16x8*)(lds + (off) + aoff + m * 2048 + k * 1024); } while (0)
; template <class Epi, bool ALIGN_EPI = true>
; __device__ __forceinline__ void gemm_phase(LAS unsigned char* lds, const Gemm g, const StaticOrder& S, const Epi& E) {
;     ...
;     Unit cur, nxt; int ui = 0;
;     if (!S.next(0, cur)) return;
;     Acc acc;
; #pragma unroll
;     for (int a = 0; a < 2; ++a)
; #pragma unroll
;         for (int b = 0; b < 2; ++b)
; #pragma unroll
;             for (int m = 0; m < 4; ++m)
; #pragma unroll
;                 for (int n = 0; n < 2; ++n) acc[a][b][m][n] = (f32x4){0.f, 0.f, 0.f, 0.f};
;     bf16x8 At[4][2], B0[2][2], B1[2][2];
;     const char* cA = PG8_ABASE(cur); const char* cB = PG8_BBASE(cur);
;     int o0 = 6 * HTB, o1 = 7 * HTB, o2 = 8 * HTB;
;     PG8_STAGE(PG8_SB(0, 0), cB, voffB); PG8_STAGE(PG8_SB(0, 1), cB + hstep, voffB); PG8_STAGE(o0, cA, voffA); PG8_STAGE(PG8_SA1(0), cA + hstep, voffA);
;     if (wr == 1) PG8_BAR;
;     PG8_WAIT_V(2); PG8_BAR;
;     PG8_STAGE(PG8_SB(1, 0), cB + kstep, voffB); PG8_STAGE(o1, cA + kstep, voffA); PG8_STAGE(PG8_SB(1, 1), cB + hstep + kstep, voffB);
;     PG8_WAIT_V(6); PG8_BAR;
;     for (;;) {
;         const bool has_next = S.next(ui + 1, nxt);
;         const char* nA = has_next ? PG8_ABASE(nxt) : cA; const char* nB = has_next ? PG8_BBASE(nxt) : cB;
;         for (int t = 0; t < nt; t += 2) {
;             const bool last = (t == nt - 2);
;             const char* a1 = cA + (size_t)(t + 1) * kstep;
;             const char* a2 = last ? nA : cA + (size_t)(t + 2) * kstep; const char* b2 = last ? nB : cB + (size_t)(t + 2) * kstep;
;             const char* a3 = a2 + kstep; const char* b3 = b2 + kstep;
;             PG8_LDB(B0, 0, 0); PG8_LDB(B1, 0, 1); PG8_SCHED; PG8_LDA(At, o0); PG8_STAGE(PG8_SA1(1), a1 + hstep, voffA); PG8_STAGE(o2, a2, voffA);
;             PG8_WAIT_V(10); PG8_WAIT_L(0); PG8_BAR; PG8_MMA(0, 0, At, B0); PG8_MMA(0, 1, At, B1); PG8_BAR; PG8_SCHED;
.LBB0_771:
	s_ashr_i32 s13, s12, 31
	s_lshl_b64 s[18:19], s[12:13], 21
	s_add_u32 s18, s16, s18
	s_addc_u32 s19, s17, s19
	s_and_b64 s[22:23], s[2:3], exec
	s_cselect_b32 s13, s19, s27
	s_cselect_b32 s53, s18, s26
	s_ashr_i32 s11, s10, 31
	s_lshl_b64 s[22:23], s[10:11], 21
	v_readlane_b32 s36, v252, 11
	v_readlane_b32 s37, v252, 12
	s_add_u32 s22, s36, s22
	s_addc_u32 s23, s37, s23
	s_and_b64 s[38:39], s[2:3], exec
	s_cselect_b32 s11, s23, s29
	s_cselect_b32 s54, s22, s28
	s_add_u32 s26, s26, 0x100080
	s_addc_u32 s27, s27, 0
	s_add_u32 s55, s28, 0x100
	v_mov_b32_e32 v2, 0
	s_addc_u32 s56, s29, 0
	s_mov_b32 s57, -2
	s_mov_b32 s28, s51
	v_mov_b32_e32 v3, v2
	v_mov_b32_e32 v4, v2
	v_mov_b32_e32 v5, v2
	v_mov_b32_e32 v6, v2
	v_mov_b32_e32 v7, v2
	v_mov_b32_e32 v8, v2
	v_mov_b32_e32 v9, v2
	v_mov_b32_e32 v14, v2
	v_mov_b32_e32 v15, v2
	v_mov_b32_e32 v16, v2
	v_mov_b32_e32 v17, v2
	v_mov_b32_e32 v22, v2
	v_mov_b32_e32 v23, v2
	v_mov_b32_e32 v24, v2
	v_mov_b32_e32 v25, v2
	v_mov_b32_e32 v30, v2
	v_mov_b32_e32 v31, v2
	v_mov_b32_e32 v32, v2
	v_mov_b32_e32 v33, v2
	v_mov_b32_e32 v38, v2
	v_mov_b32_e32 v39, v2
	v_mov_b32_e32 v40, v2
	v_mov_b32_e32 v41, v2
	v_mov_b32_e32 v46, v2
	v_mov_b32_e32 v47, v2
	v_mov_b32_e32 v48, v2
	v_mov_b32_e32 v49, v2
	v_mov_b32_e32 v54, v2
	v_mov_b32_e32 v55, v2
	v_mov_b32_e32 v56, v2
	v_mov_b32_e32 v57, v2
	v_mov_b32_e32 v10, v2
	v_mov_b32_e32 v11, v2
	v_mov_b32_e32 v12, v2
	v_mov_b32_e32 v13, v2
	v_mov_b32_e32 v18, v2
	v_mov_b32_e32 v19, v2
	v_mov_b32_e32 v20, v2
	v_mov_b32_e32 v21, v2
	v_mov_b32_e32 v26, v2
	v_mov_b32_e32 v27, v2
	v_mov_b32_e32 v28, v2
	v_mov_b32_e32 v29, v2
	v_mov_b32_e32 v34, v2
	v_mov_b32_e32 v35, v2
	v_mov_b32_e32 v36, v2
	v_mov_b32_e32 v37, v2
	v_mov_b32_e32 v42, v2
	v_mov_b32_e32 v43, v2
	v_mov_b32_e32 v44, v2
	v_mov_b32_e32 v45, v2
	v_mov_b32_e32 v50, v2
	v_mov_b32_e32 v51, v2
	v_mov_b32_e32 v52, v2
	v_mov_b32_e32 v53, v2
	v_mov_b32_e32 v58, v2
	v_mov_b32_e32 v59, v2
	v_mov_b32_e32 v60, v2
	v_mov_b32_e32 v61, v2
	v_mov_b32_e32 v62, v2
	v_mov_b32_e32 v63, v2
	v_mov_b32_e32 v64, v2
	v_mov_b32_e32 v65, v2
	v_mov_b32_e32 v66, v2
	v_mov_b32_e32 v67, v2
	v_mov_b32_e32 v68, v2
	v_mov_b32_e32 v69, v2
	v_mov_b32_e32 v70, v2
	v_mov_b32_e32 v71, v2
	v_mov_b32_e32 v72, v2
	v_mov_b32_e32 v73, v2
	v_mov_b32_e32 v78, v2
	v_mov_b32_e32 v79, v2
	v_mov_b32_e32 v80, v2
	v_mov_b32_e32 v81, v2
	v_mov_b32_e32 v86, v2
	v_mov_b32_e32 v87, v2
	v_mov_b32_e32 v88, v2
	v_mov_b32_e32 v89, v2
	v_mov_b32_e32 v98, v2
	v_mov_b32_e32 v99, v2
	v_mov_b32_e32 v100, v2
	v_mov_b32_e32 v101, v2
	v_mov_b32_e32 v102, v2
	v_mov_b32_e32 v103, v2
	v_mov_b32_e32 v104, v2
	v_mov_b32_e32 v105, v2
	v_mov_b32_e32 v106, v2
	v_mov_b32_e32 v107, v2
	v_mov_b32_e32 v108, v2
	v_mov_b32_e32 v109, v2
	v_mov_b32_e32 v110, v2
	v_mov_b32_e32 v111, v2
	v_mov_b32_e32 v112, v2
	v_mov_b32_e32 v113, v2
	v_mov_b32_e32 v74, v2
	v_mov_b32_e32 v75, v2
	v_mov_b32_e32 v76, v2
	v_mov_b32_e32 v77, v2
	v_mov_b32_e32 v82, v2
	v_mov_b32_e32 v83, v2
	v_mov_b32_e32 v84, v2
	v_mov_b32_e32 v85, v2
	v_mov_b32_e32 v90, v2
	v_mov_b32_e32 v91, v2
	v_mov_b32_e32 v92, v2
	v_mov_b32_e32 v93, v2
	v_mov_b32_e32 v94, v2
	v_mov_b32_e32 v95, v2
	v_mov_b32_e32 v96, v2
	v_mov_b32_e32 v97, v2
	v_mov_b32_e32 v114, v2
	v_mov_b32_e32 v115, v2
	v_mov_b32_e32 v116, v2
	v_mov_b32_e32 v117, v2
	v_mov_b32_e32 v118, v2
	v_mov_b32_e32 v119, v2
	v_mov_b32_e32 v120, v2
	v_mov_b32_e32 v121, v2
	v_mov_b32_e32 v122, v2
	v_mov_b32_e32 v123, v2
	v_mov_b32_e32 v124, v2
	v_mov_b32_e32 v125, v2
	v_mov_b32_e32 v126, v2
	v_mov_b32_e32 v127, v2
	v_mov_b32_e32 v128, v2
	v_mov_b32_e32 v129, v2
	s_and_b64 vcc, exec, s[4:5]
	s_cbranch_vccz .Lkprio_skip_P7
	s_setprio 1
.Lkprio_skip_P7:
.LBB0_772:
	ds_read_b128 v[130:133], v179 offset:32768
	ds_read_b128 v[134:137], v179 offset:33792
	ds_read_b128 v[138:141], v179 offset:34816
	ds_read_b128 v[142:145], v179 offset:35840
	ds_read_b128 v[146:149], v179 offset:49152
	ds_read_b128 v[150:153], v179 offset:50176
	ds_read_b128 v[170:173], v179 offset:51200
	ds_read_b128 v[180:183], v179 offset:52224
	s_mov_b32 s51, s50
	s_mov_b32 s50, s48
	s_mov_b32 s48, s28
	s_add_u32 s28, s26, 0xfff00080
	s_addc_u32 s29, s27, -1
	s_cmp_eq_u32 s57, 60
	s_cselect_b32 s38, s53, s28
	s_cselect_b32 s28, s54, s55
	s_cselect_b32 s39, s13, s29
	s_cselect_b32 s29, s11, s56
	v_add_u32_e32 v174, s48, v177
	ds_read_b128 v[184:187], v174
	ds_read_b128 v[188:191], v174 offset:1024
	ds_read_b128 v[192:195], v174 offset:2048
	ds_read_b128 v[196:199], v174 offset:3072
	ds_read_b128 v[200:203], v174 offset:4096
	ds_read_b128 v[204:207], v174 offset:5120
	ds_read_b128 v[208:211], v174 offset:6144
	ds_read_b128 v[212:215], v174 offset:7168
	v_lshl_add_u64 v[174:175], s[26:27], 0, v[162:163]
	s_add_i32 m0, s25, 0x4000
	s_add_i32 s58, s25, s51
	global_load_lds_dwordx4 v[174:175], off
	v_lshl_add_u64 v[174:175], s[26:27], 0, v[164:165]
	s_add_i32 m0, s25, 0x6000
	v_lshl_add_u64 v[216:217], s[38:39], 0, v[158:159]
	global_load_lds_dwordx4 v[174:175], off
	v_lshl_add_u64 v[174:175], s[38:39], 0, v[154:155]
	s_mov_b32 m0, s58
	s_nop 0
	global_load_lds_dwordx4 v[174:175], off
	s_add_i32 m0, s58, 0x2000
	s_nop 0
	global_load_lds_dwordx4 v[216:217], off
	s_waitcnt vmcnt(10)
	s_waitcnt lgkmcnt(0)
	s_barrier
; #define PG8_STAGE(bufoff, gbase, voff) do { _Pragma("unroll") for (int _i = 0; _i < 2; ++_i) \
;         __builtin_amdgcn_global_load_lds((const unsigned*)((const char*)(gbase) + (voff)[_i]), (LAS unsigned*)(lds + (bufoff) + ldsw + _i * 8192), 16, 0, 0); } while (0)
; #define PG8_LDA(dst, off) do { _Pragma("unroll") for (int m = 0; m < 4; ++m) _Pragma("unroll") for (int k = 0; k < 2; ++k) dst[m][k] = *(const LAS bf16x8*)(lds + (off) + aoff + m * 2048 + k * 1024); } while (0)
; #define PG8_MMA(ai, bj, At, Bt) do { __builtin_amdgcn_s_setprio(1); _Pragma("unroll") for (int m = 0; m < 4; ++m) _Pragma("unroll") for (int n = 0; n < 2; ++n) _Pragma("unroll") for (int k = 0; k < 2; ++k) \
;         acc[ai][bj][m][n] = __builtin_amdgcn_mfma_f32_16x16x32_bf16(Bt[n][k], At[m][k], acc[ai][bj][m][n], 0, 0, 0); __builtin_amdgcn_s_setprio(0); } while (0)
; #define PG8_WAIT_V(n) asm volatile("s_waitcnt vmcnt(" #n ")" ::: "memory")
; #define PG8_WAIT_L(n) asm volatile("s_waitcnt lgkmcnt(" #n ")" ::: "memory")
; #define PG8_BAR __builtin_amdgcn_s_barrier()
; #define PG8_SCHED __builtin_amdgcn_sched_barrier(0)
; template <class Epi, bool ALIGN_EPI = true>
; __device__ __forceinline__ void gemm_phase(LAS unsigned char* lds, const Gemm g, const StaticOrder& S, const Epi& E) {
;     ...
;             PG8_WAIT_V(10); PG8_WAIT_L(0); PG8_BAR; PG8_MMA(0, 0, At, B0); PG8_MMA(0, 1, At, B1); PG8_BAR; PG8_SCHED;
;             PG8_LDA(At, PG8_SA1(0)); PG8_STAGE(PG8_SB(0, 0), b2, voffB); PG8_STAGE(PG8_SB(0, 1), b2 + hstep, voffB);
;             PG8_WAIT_V(8); PG8_WAIT_L(0); PG8_BAR; PG8_MMA(1, 0, At, B0); PG8_MMA(1, 1, At, B1); PG8_BAR; PG8_SCHED;
	s_waitcnt lgkmcnt(0)
	v_mfma_f32_16x16x32_bf16 v[126:129], v[130:133], v[184:187], v[126:129]
	v_mfma_f32_16x16x32_bf16 v[126:129], v[134:137], v[188:191], v[126:129]
	v_mfma_f32_16x16x32_bf16 v[122:125], v[138:141], v[184:187], v[122:125]
	v_mfma_f32_16x16x32_bf16 v[122:125], v[142:145], v[188:191], v[122:125]
	v_mfma_f32_16x16x32_bf16 v[110:113], v[146:149], v[184:187], v[110:113]
	v_mfma_f32_16x16x32_bf16 v[110:113], v[150:153], v[188:191], v[110:113]
	v_mfma_f32_16x16x32_bf16 v[106:109], v[170:173], v[184:187], v[106:109]
	v_mfma_f32_16x16x32_bf16 v[106:109], v[180:183], v[188:191], v[106:109]
	v_mfma_f32_16x16x32_bf16 v[118:121], v[130:133], v[192:195], v[118:121]
	v_mfma_f32_16x16x32_bf16 v[118:121], v[134:137], v[196:199], v[118:121]
	v_mfma_f32_16x16x32_bf16 v[114:117], v[138:141], v[192:195], v[114:117]
	v_mfma_f32_16x16x32_bf16 v[114:117], v[142:145], v[196:199], v[114:117]
	v_mfma_f32_16x16x32_bf16 v[102:105], v[146:149], v[192:195], v[102:105]
	v_mfma_f32_16x16x32_bf16 v[102:105], v[150:153], v[196:199], v[102:105]
	v_mfma_f32_16x16x32_bf16 v[98:101], v[170:173], v[192:195], v[98:101]
	v_mfma_f32_16x16x32_bf16 v[98:101], v[180:183], v[196:199], v[98:101]
	v_mfma_f32_16x16x32_bf16 v[94:97], v[130:133], v[200:203], v[94:97]
	v_mfma_f32_16x16x32_bf16 v[94:97], v[134:137], v[204:207], v[94:97]
	v_mfma_f32_16x16x32_bf16 v[90:93], v[138:141], v[200:203], v[90:93]
	v_mfma_f32_16x16x32_bf16 v[90:93], v[142:145], v[204:207], v[90:93]
	v_mfma_f32_16x16x32_bf16 v[86:89], v[146:149], v[200:203], v[86:89]
	v_mfma_f32_16x16x32_bf16 v[86:89], v[150:153], v[204:207], v[86:89]
	v_mfma_f32_16x16x32_bf16 v[78:81], v[170:173], v[200:203], v[78:81]
	v_mfma_f32_16x16x32_bf16 v[78:81], v[180:183], v[204:207], v[78:81]
	v_mfma_f32_16x16x32_bf16 v[82:85], v[130:133], v[208:211], v[82:85]
	v_mfma_f32_16x16x32_bf16 v[82:85], v[134:137], v[212:215], v[82:85]
	v_mfma_f32_16x16x32_bf16 v[74:77], v[138:141], v[208:211], v[74:77]
	v_mfma_f32_16x16x32_bf16 v[74:77], v[142:145], v[212:215], v[74:77]
	v_mfma_f32_16x16x32_bf16 v[70:73], v[146:149], v[208:211], v[70:73]
	v_mfma_f32_16x16x32_bf16 v[70:73], v[150:153], v[212:215], v[70:73]
	v_mfma_f32_16x16x32_bf16 v[66:69], v[170:173], v[208:211], v[66:69]
	v_mfma_f32_16x16x32_bf16 v[66:69], v[180:183], v[212:215], v[66:69]
	s_barrier
	s_mov_b32 m0, s40
	v_lshl_add_u64 v[218:219], s[28:29], 0, v[156:157]
	s_add_u32 s58, s28, 0x100000
	ds_read_b128 v[184:187], v177
	ds_read_b128 v[188:191], v177 offset:1024
	ds_read_b128 v[192:195], v177 offset:2048
	ds_read_b128 v[196:199], v177 offset:3072
	ds_read_b128 v[200:203], v177 offset:4096
	ds_read_b128 v[204:207], v177 offset:5120
	ds_read_b128 v[208:211], v177 offset:6144
	ds_read_b128 v[212:215], v177 offset:7168
	global_load_lds_dwordx4 v[218:219], off
	v_lshl_add_u64 v[220:221], s[28:29], 0, v[160:161]
	s_mov_b32 m0, s41
	s_addc_u32 s59, s29, 0
	global_load_lds_dwordx4 v[220:221], off
	v_lshl_add_u64 v[222:223], s[58:59], 0, v[156:157]
	s_mov_b32 m0, s42
	s_nop 0
	global_load_lds_dwordx4 v[222:223], off
	v_lshl_add_u64 v[222:223], s[58:59], 0, v[160:161]
	s_mov_b32 m0, s43
	s_nop 0
	global_load_lds_dwordx4 v[222:223], off
	s_waitcnt vmcnt(8)
	s_waitcnt lgkmcnt(0)
	s_barrier
	s_waitcnt lgkmcnt(0)
	v_mfma_f32_16x16x32_bf16 v[62:65], v[130:133], v[184:187], v[62:65]
	v_mfma_f32_16x16x32_bf16 v[62:65], v[134:137], v[188:191], v[62:65]
	v_mfma_f32_16x16x32_bf16 v[58:61], v[138:141], v[184:187], v[58:61]
	v_mfma_f32_16x16x32_bf16 v[58:61], v[142:145], v[188:191], v[58:61]
	v_mfma_f32_16x16x32_bf16 v[54:57], v[146:149], v[184:187], v[54:57]
	v_mfma_f32_16x16x32_bf16 v[54:57], v[150:153], v[188:191], v[54:57]
	v_mfma_f32_16x16x32_bf16 v[46:49], v[170:173], v[184:187], v[46:49]
	v_mfma_f32_16x16x32_bf16 v[46:49], v[180:183], v[188:191], v[46:49]
	v_mfma_f32_16x16x32_bf16 v[50:53], v[130:133], v[192:195], v[50:53]
	v_mfma_f32_16x16x32_bf16 v[50:53], v[134:137], v[196:199], v[50:53]
	v_mfma_f32_16x16x32_bf16 v[42:45], v[138:141], v[192:195], v[42:45]
	v_mfma_f32_16x16x32_bf16 v[42:45], v[142:145], v[196:199], v[42:45]
	v_mfma_f32_16x16x32_bf16 v[38:41], v[146:149], v[192:195], v[38:41]
	v_mfma_f32_16x16x32_bf16 v[38:41], v[150:153], v[196:199], v[38:41]
	v_mfma_f32_16x16x32_bf16 v[30:33], v[170:173], v[192:195], v[30:33]
	v_mfma_f32_16x16x32_bf16 v[30:33], v[180:183], v[196:199], v[30:33]
	v_mfma_f32_16x16x32_bf16 v[34:37], v[130:133], v[200:203], v[34:37]
	v_mfma_f32_16x16x32_bf16 v[34:37], v[134:137], v[204:207], v[34:37]
	v_mfma_f32_16x16x32_bf16 v[26:29], v[138:141], v[200:203], v[26:29]
	v_mfma_f32_16x16x32_bf16 v[26:29], v[142:145], v[204:207], v[26:29]
	v_mfma_f32_16x16x32_bf16 v[22:25], v[146:149], v[200:203], v[22:25]
	v_mfma_f32_16x16x32_bf16 v[22:25], v[150:153], v[204:207], v[22:25]
	v_mfma_f32_16x16x32_bf16 v[14:17], v[170:173], v[200:203], v[14:17]
	v_mfma_f32_16x16x32_bf16 v[14:17], v[180:183], v[204:207], v[14:17]
	v_mfma_f32_16x16x32_bf16 v[18:21], v[130:133], v[208:211], v[18:21]
	v_mfma_f32_16x16x32_bf16 v[18:21], v[134:137], v[212:215], v[18:21]
	v_mfma_f32_16x16x32_bf16 v[10:13], v[138:141], v[208:211], v[10:13]
	v_mfma_f32_16x16x32_bf16 v[10:13], v[142:145], v[212:215], v[10:13]
	v_mfma_f32_16x16x32_bf16 v[6:9], v[146:149], v[208:211], v[6:9]
	v_mfma_f32_16x16x32_bf16 v[6:9], v[150:153], v[212:215], v[6:9]
	v_mfma_f32_16x16x32_bf16 v[2:5], v[170:173], v[208:211], v[2:5]
	v_mfma_f32_16x16x32_bf16 v[2:5], v[180:183], v[212:215], v[2:5]
	s_barrier
; #define PG8_STAGE(bufoff, gbase, voff) do { _Pragma("unroll") for (int _i = 0; _i < 2; ++_i) \
;         __builtin_amdgcn_global_load_lds((const unsigned*)((const char*)(gbase) + (voff)[_i]), (LAS unsigned*)(lds + (bufoff) + ldsw + _i * 8192), 16, 0, 0); } while (0)
; #define PG8_LDA(dst, off) do { _Pragma("unroll") for (int m = 0; m < 4; ++m) _Pragma("unroll") for (int k = 0; k < 2; ++k) dst[m][k] = *(const LAS bf16x8*)(lds + (off) + aoff + m * 2048 + k * 1024); } while (0)
; #define PG8_LDB(dst, b, h) do { _Pragma("unroll") for (int n = 0; n < 2; ++n) _Pragma("unroll") for (int k = 0; k < 2; ++k) dst[n][k] = *(const LAS bf16x8*)(lds + PG8_SB(b, h) + boff + n * 2048 + k * 1024); } while (0)
; #define PG8_MMA(ai, bj, At, Bt) do { __builtin_amdgcn_s_setprio(1); _Pragma("unroll") for (int m = 0; m < 4; ++m) _Pragma("unroll") for (int n = 0; n < 2; ++n) _Pragma("unroll") for (int k = 0; k < 2; ++k) \
;         acc[ai][bj][m][n] = __builtin_amdgcn_mfma_f32_16x16x32_bf16(Bt[n][k], At[m][k], acc[ai][bj][m][n], 0, 0, 0); __builtin_amdgcn_s_setprio(0); } while (0)
; #define PG8_WAIT_V(n) asm volatile("s_waitcnt vmcnt(" #n ")" ::: "memory")
; #define PG8_WAIT_L(n) asm volatile("s_waitcnt lgkmcnt(" #n ")" ::: "memory")
; #define PG8_BAR __builtin_amdgcn_s_barrier()
; #define PG8_SCHED __builtin_amdgcn_sched_barrier(0)
; template <class Epi, bool ALIGN_EPI = true>
; __device__ __forceinline__ void gemm_phase(LAS unsigned char* lds, const Gemm g, const StaticOrder& S, const Epi& E) {
;     ...
;             PG8_LDB(B0, 1, 0); PG8_LDB(B1, 1, 1); PG8_SCHED; PG8_LDA(At, o1); PG8_STAGE(PG8_SA1(0), a2 + hstep, voffA); PG8_STAGE(o0, a3, voffA);
;             PG8_WAIT_V(10); PG8_WAIT_L(0); PG8_BAR; PG8_MMA(0, 0, At, B0); PG8_MMA(0, 1, At, B1); PG8_BAR; PG8_SCHED;
	s_add_i32 s58, 0, 0x10000
	s_add_i32 s59, 0, 0x14000
	v_add_u32_e32 v142, s58, v176
	v_add_u32_e32 v180, s59, v176
	ds_read_b128 v[130:133], v142
	ds_read_b128 v[134:137], v142 offset:1024
	ds_read_b128 v[138:141], v142 offset:2048
	ds_read_b128 v[142:145], v142 offset:3072
	ds_read_b128 v[146:149], v180
	ds_read_b128 v[150:153], v180 offset:1024
	ds_read_b128 v[170:173], v180 offset:2048
	ds_read_b128 v[180:183], v180 offset:3072
	s_add_u32 s38, s38, 0x100000
	s_addc_u32 s39, s39, 0
	s_mov_b32 m0, s25
	v_add_u32_e32 v212, s50, v177
	v_lshl_add_u64 v[222:223], s[38:39], 0, v[154:155]
	ds_read_b128 v[184:187], v212
	ds_read_b128 v[188:191], v212 offset:1024
	ds_read_b128 v[192:195], v212 offset:2048
	ds_read_b128 v[196:199], v212 offset:3072
	ds_read_b128 v[200:203], v212 offset:4096
	ds_read_b128 v[204:207], v212 offset:5120
	ds_read_b128 v[208:211], v212 offset:6144
	ds_read_b128 v[212:215], v212 offset:7168
	global_load_lds_dwordx4 v[222:223], off
	v_lshl_add_u64 v[222:223], s[38:39], 0, v[158:159]
	s_mov_b32 m0, s44
	s_add_i32 s38, s25, s48
	global_load_lds_dwordx4 v[222:223], off
	v_lshl_add_u64 v[174:175], v[174:175], 0, s[6:7]
	s_mov_b32 m0, s38
	s_nop 0
	global_load_lds_dwordx4 v[174:175], off
	v_lshl_add_u64 v[174:175], v[216:217], 0, s[6:7]
	s_add_i32 m0, s38, 0x2000
	s_nop 0
	global_load_lds_dwordx4 v[174:175], off
	s_waitcnt vmcnt(10)
	s_waitcnt lgkmcnt(0)
	s_barrier
	s_waitcnt lgkmcnt(0)
	v_mfma_f32_16x16x32_bf16 v[126:129], v[130:133], v[184:187], v[126:129]
	v_mfma_f32_16x16x32_bf16 v[126:129], v[134:137], v[188:191], v[126:129]
	v_mfma_f32_16x16x32_bf16 v[122:125], v[138:141], v[184:187], v[122:125]
	v_mfma_f32_16x16x32_bf16 v[122:125], v[142:145], v[188:191], v[122:125]
	v_mfma_f32_16x16x32_bf16 v[110:113], v[146:149], v[184:187], v[110:113]
	v_mfma_f32_16x16x32_bf16 v[110:113], v[150:153], v[188:191], v[110:113]
	v_mfma_f32_16x16x32_bf16 v[106:109], v[170:173], v[184:187], v[106:109]
	v_mfma_f32_16x16x32_bf16 v[106:109], v[180:183], v[188:191], v[106:109]
	v_mfma_f32_16x16x32_bf16 v[118:121], v[130:133], v[192:195], v[118:121]
	v_mfma_f32_16x16x32_bf16 v[118:121], v[134:137], v[196:199], v[118:121]
	v_mfma_f32_16x16x32_bf16 v[114:117], v[138:141], v[192:195], v[114:117]
	v_mfma_f32_16x16x32_bf16 v[114:117], v[142:145], v[196:199], v[114:117]
	v_mfma_f32_16x16x32_bf16 v[102:105], v[146:149], v[192:195], v[102:105]
	v_mfma_f32_16x16x32_bf16 v[102:105], v[150:153], v[196:199], v[102:105]
	v_mfma_f32_16x16x32_bf16 v[98:101], v[170:173], v[192:195], v[98:101]
	v_mfma_f32_16x16x32_bf16 v[98:101], v[180:183], v[196:199], v[98:101]
	v_mfma_f32_16x16x32_bf16 v[94:97], v[130:133], v[200:203], v[94:97]
	v_mfma_f32_16x16x32_bf16 v[94:97], v[134:137], v[204:207], v[94:97]
	v_mfma_f32_16x16x32_bf16 v[90:93], v[138:141], v[200:203], v[90:93]
	v_mfma_f32_16x16x32_bf16 v[90:93], v[142:145], v[204:207], v[90:93]
	v_mfma_f32_16x16x32_bf16 v[86:89], v[146:149], v[200:203], v[86:89]
	v_mfma_f32_16x16x32_bf16 v[86:89], v[150:153], v[204:207], v[86:89]
	v_mfma_f32_16x16x32_bf16 v[78:81], v[170:173], v[200:203], v[78:81]
	v_mfma_f32_16x16x32_bf16 v[78:81], v[180:183], v[204:207], v[78:81]
	v_mfma_f32_16x16x32_bf16 v[82:85], v[130:133], v[208:211], v[82:85]
	v_mfma_f32_16x16x32_bf16 v[82:85], v[134:137], v[212:215], v[82:85]
	v_mfma_f32_16x16x32_bf16 v[74:77], v[138:141], v[208:211], v[74:77]
	v_mfma_f32_16x16x32_bf16 v[74:77], v[142:145], v[212:215], v[74:77]
	v_mfma_f32_16x16x32_bf16 v[70:73], v[146:149], v[208:211], v[70:73]
	v_mfma_f32_16x16x32_bf16 v[70:73], v[150:153], v[212:215], v[70:73]
	v_mfma_f32_16x16x32_bf16 v[66:69], v[170:173], v[208:211], v[66:69]
	v_mfma_f32_16x16x32_bf16 v[66:69], v[180:183], v[212:215], v[66:69]
	s_barrier
; #define PG8_STAGE(bufoff, gbase, voff) do { _Pragma("unroll") for (int _i = 0; _i < 2; ++_i) \
;         __builtin_amdgcn_global_load_lds((const unsigned*)((const char*)(gbase) + (voff)[_i]), (LAS unsigned*)(lds + (bufoff) + ldsw + _i * 8192), 16, 0, 0); } while (0)
; #define PG8_LDA(dst, off) do { _Pragma("unroll") for (int m = 0; m < 4; ++m) _Pragma("unroll") for (int k = 0; k < 2; ++k) dst[m][k] = *(const LAS bf16x8*)(lds + (off) + aoff + m * 2048 + k * 1024); } while (0)
; #define PG8_MMA(ai, bj, At, Bt) do { __builtin_amdgcn_s_setprio(1); _Pragma("unroll") for (int m = 0; m < 4; ++m) _Pragma("unroll") for (int n = 0; n < 2; ++n) _Pragma("unroll") for (int k = 0; k < 2; ++k) \
;         acc[ai][bj][m][n] = __builtin_amdgcn_mfma_f32_16x16x32_bf16(Bt[n][k], At[m][k], acc[ai][bj][m][n], 0, 0, 0); __builtin_amdgcn_s_setprio(0); } while (0)
; #define PG8_WAIT_V(n) asm volatile("s_waitcnt vmcnt(" #n ")" ::: "memory")
; #define PG8_WAIT_L(n) asm volatile("s_waitcnt lgkmcnt(" #n ")" ::: "memory")
; #define PG8_BAR __builtin_amdgcn_s_barrier()
; #define PG8_SCHED __builtin_amdgcn_sched_barrier(0)
; template <class Epi, bool ALIGN_EPI = true>
; __device__ __forceinline__ void gemm_phase(LAS unsigned char* lds, const Gemm g, const StaticOrder& S, const Epi& E) {
;     ...
;             PG8_LDA(At, PG8_SA1(1)); PG8_STAGE(PG8_SB(1, 0), b3, voffB); PG8_STAGE(PG8_SB(1, 1), b3 + hstep, voffB);
;             PG8_WAIT_V(8); PG8_WAIT_L(0); PG8_BAR; PG8_MMA(1, 0, At, B0); PG8_MMA(1, 1, At, B1); PG8_BAR; PG8_SCHED;
;             { const int t_ = o0; o0 = o2; o2 = o1; o1 = t_; }
;         }
;         if constexpr (ALIGN_EPI) { if (wr == 0) PG8_BAR; }
	s_add_i32 s38, s58, s35
	v_lshl_add_u64 v[174:175], v[218:219], 0, s[6:7]
	s_mov_b32 m0, s38
	ds_read_b128 v[184:187], v177 offset:16384
	ds_read_b128 v[188:191], v177 offset:17408
	ds_read_b128 v[192:195], v177 offset:18432
	ds_read_b128 v[196:199], v177 offset:19456
	ds_read_b128 v[200:203], v177 offset:20480
	ds_read_b128 v[204:207], v177 offset:21504
	ds_read_b128 v[208:211], v177 offset:22528
	ds_read_b128 v[212:215], v177 offset:23552
	global_load_lds_dwordx4 v[174:175], off
	s_add_i32 m0, s38, 0x2000
	s_add_u32 s28, s28, 0x100080
	v_lshl_add_u64 v[174:175], v[220:221], 0, s[6:7]
	s_addc_u32 s29, s29, 0
	s_add_i32 s38, s59, s35
	global_load_lds_dwordx4 v[174:175], off
	v_lshl_add_u64 v[174:175], s[28:29], 0, v[156:157]
	s_mov_b32 m0, s38
	s_nop 0
	global_load_lds_dwordx4 v[174:175], off
	v_lshl_add_u64 v[174:175], s[28:29], 0, v[160:161]
	s_add_i32 m0, s38, 0x2000
	s_nop 0
	global_load_lds_dwordx4 v[174:175], off
	s_waitcnt vmcnt(8)
	s_waitcnt lgkmcnt(0)
	s_barrier
	s_waitcnt lgkmcnt(0)
	v_mfma_f32_16x16x32_bf16 v[62:65], v[130:133], v[184:187], v[62:65]
	v_mfma_f32_16x16x32_bf16 v[62:65], v[134:137], v[188:191], v[62:65]
	v_mfma_f32_16x16x32_bf16 v[58:61], v[138:141], v[184:187], v[58:61]
	v_mfma_f32_16x16x32_bf16 v[58:61], v[142:145], v[188:191], v[58:61]
	v_mfma_f32_16x16x32_bf16 v[54:57], v[146:149], v[184:187], v[54:57]
	v_mfma_f32_16x16x32_bf16 v[54:57], v[150:153], v[188:191], v[54:57]
	v_mfma_f32_16x16x32_bf16 v[46:49], v[170:173], v[184:187], v[46:49]
	v_mfma_f32_16x16x32_bf16 v[46:49], v[180:183], v[188:191], v[46:49]
	v_mfma_f32_16x16x32_bf16 v[50:53], v[130:133], v[192:195], v[50:53]
	v_mfma_f32_16x16x32_bf16 v[50:53], v[134:137], v[196:199], v[50:53]
	v_mfma_f32_16x16x32_bf16 v[42:45], v[138:141], v[192:195], v[42:45]
	v_mfma_f32_16x16x32_bf16 v[42:45], v[142:145], v[196:199], v[42:45]
	v_mfma_f32_16x16x32_bf16 v[38:41], v[146:149], v[192:195], v[38:41]
	v_mfma_f32_16x16x32_bf16 v[38:41], v[150:153], v[196:199], v[38:41]
	v_mfma_f32_16x16x32_bf16 v[30:33], v[170:173], v[192:195], v[30:33]
	v_mfma_f32_16x16x32_bf16 v[30:33], v[180:183], v[196:199], v[30:33]
	v_mfma_f32_16x16x32_bf16 v[34:37], v[130:133], v[200:203], v[34:37]
	v_mfma_f32_16x16x32_bf16 v[34:37], v[134:137], v[204:207], v[34:37]
	v_mfma_f32_16x16x32_bf16 v[26:29], v[138:141], v[200:203], v[26:29]
	v_mfma_f32_16x16x32_bf16 v[26:29], v[142:145], v[204:207], v[26:29]
	v_mfma_f32_16x16x32_bf16 v[22:25], v[146:149], v[200:203], v[22:25]
	v_mfma_f32_16x16x32_bf16 v[22:25], v[150:153], v[204:207], v[22:25]
	v_mfma_f32_16x16x32_bf16 v[14:17], v[170:173], v[200:203], v[14:17]
	v_mfma_f32_16x16x32_bf16 v[14:17], v[180:183], v[204:207], v[14:17]
	v_mfma_f32_16x16x32_bf16 v[18:21], v[130:133], v[208:211], v[18:21]
	v_mfma_f32_16x16x32_bf16 v[18:21], v[134:137], v[212:215], v[18:21]
	v_mfma_f32_16x16x32_bf16 v[10:13], v[138:141], v[208:211], v[10:13]
	v_mfma_f32_16x16x32_bf16 v[10:13], v[142:145], v[212:215], v[10:13]
	v_mfma_f32_16x16x32_bf16 v[6:9], v[146:149], v[208:211], v[6:9]
	v_mfma_f32_16x16x32_bf16 v[6:9], v[150:153], v[212:215], v[6:9]
	v_mfma_f32_16x16x32_bf16 v[2:5], v[170:173], v[208:211], v[2:5]
	v_mfma_f32_16x16x32_bf16 v[2:5], v[180:183], v[212:215], v[2:5]
	s_barrier
	s_add_i32 s57, s57, 2
	s_add_u32 s26, s26, 0x100
	s_addc_u32 s27, s27, 0
	s_add_u32 s55, s55, 0x100
	s_addc_u32 s56, s56, 0
	s_cmp_gt_u32 s57, 61
	s_mov_b32 s28, s51
	s_cbranch_scc0 .LBB0_772
	s_setprio 0
	s_and_b64 vcc, exec, s[8:9]
	s_cbranch_vccz .LBB0_775
	s_barrier

; #define PG8_STAGE(bufoff, gbase, voff) do { _Pragma("unroll") for (int _i = 0; _i < 2; ++_i) \
;         __builtin_amdgcn_global_load_lds((const unsigned*)((const char*)(gbase) + (voff)[_i]), (LAS unsigned*)(lds + (bufoff) + ldsw + _i * 8192), 16, 0, 0); } while (0)
; #define PG8_LDA(dst, off) do { _Pragma("unroll") for (int m = 0; m < 4; ++m) _Pragma("unroll") for (int k = 0; k < 2; ++k) dst[m][k] = *(const LAS bf16x8*)(lds + (off) + aoff + m * 2048 + k * 1024); } while (0)
; template <class Epi, bool ALIGN_EPI = true>
; __device__ __forceinline__ void gemm_phase(LAS unsigned char* lds, const Gemm g, const StaticOrder& S, const Epi& E) {
;     ...
;     Unit cur, nxt; int ui = 0;
;     if (!S.next(0, cur)) return;
;     Acc acc;
; #pragma unroll
;     for (int a = 0; a < 2; ++a)
; #pragma unroll
;         for (int b = 0; b < 2; ++b)
; #pragma unroll
;             for (int m = 0; m < 4; ++m)
; #pragma unroll
;                 for (int n = 0; n < 2; ++n) acc[a][b][m][n] = (f32x4){0.f, 0.f, 0.f, 0.f};
;     bf16x8 At[4][2], B0[2][2], B1[2][2];
;     const char* cA = PG8_ABASE(cur); const char* cB = PG8_BBASE(cur);
;     int o0 = 6 * HTB, o1 = 7 * HTB, o2 = 8 * HTB;
;     PG8_STAGE(PG8_SB(0, 0), cB, voffB); PG8_STAGE(PG8_SB(0, 1), cB + hstep, voffB); PG8_STAGE(o0, cA, voffA); PG8_STAGE(PG8_SA1(0), cA + hstep, voffA);
;     if (wr == 1) PG8_BAR;
;     PG8_WAIT_V(2); PG8_BAR;
;     PG8_STAGE(PG8_SB(1, 0), cB + kstep, voffB); PG8_STAGE(o1, cA + kstep, voffA); PG8_STAGE(PG8_SB(1, 1), cB + hstep + kstep, voffB);
;     PG8_WAIT_V(6); PG8_BAR;
;     for (;;) {
;         const bool has_next = S.next(ui + 1, nxt);
;         const char* nA = has_next ? PG8_ABASE(nxt) : cA; const char* nB = has_next ? PG8_BBASE(nxt) : cB;
;         for (int t = 0; t < nt; t += 2) {
;             const bool last = (t == nt - 2);
;             const char* a1 = cA + (size_t)(t + 1) * kstep;
;             const char* a2 = last ? nA : cA + (size_t)(t + 2) * kstep; const char* b2 = last ? nB : cB + (size_t)(t + 2) * kstep;
;             const char* a3 = a2 + kstep; const char* b3 = b2 + kstep;
;             PG8_LDB(B0, 0, 0); PG8_LDB(B1, 0, 1); PG8_SCHED; PG8_LDA(At, o0); PG8_STAGE(PG8_SA1(1), a1 + hstep, voffA); PG8_STAGE(o2, a2, voffA);
;             PG8_WAIT_V(10); PG8_WAIT_L(0); PG8_BAR; PG8_MMA(0, 0, At, B0); PG8_MMA(0, 1, At, B1); PG8_BAR; PG8_SCHED;
.LBB0_902:
	s_ashr_i32 s47, s46, 31
	s_lshl_b64 s[48:49], s[46:47], 21
	s_add_u32 s48, s16, s48
	s_addc_u32 s49, s17, s49
	s_and_b64 s[50:51], s[8:9], exec
	s_cselect_b32 s11, s49, s53
	s_cselect_b32 s13, s48, s52
	s_ashr_i32 s45, s44, 31
	s_lshl_b64 s[50:51], s[44:45], 21
	v_readlane_b32 s56, v252, 13
	v_readlane_b32 s57, v252, 14
	s_add_u32 s50, s56, s50
	s_addc_u32 s51, s57, s51
	s_and_b64 s[56:57], s[8:9], exec
	s_cselect_b32 s33, s51, s55
	s_cselect_b32 s45, s50, s54
	s_add_u32 s52, s52, 0x100080
	s_addc_u32 s53, s53, 0
	s_add_u32 s47, s54, 0x100
	v_mov_b32_e32 v2, 0
	s_addc_u32 s74, s55, 0
	s_mov_b32 s75, -2
	s_mov_b32 s54, s73
	v_mov_b32_e32 v3, v2
	v_mov_b32_e32 v4, v2
	v_mov_b32_e32 v5, v2
	v_mov_b32_e32 v66, v2
	v_mov_b32_e32 v67, v2
	v_mov_b32_e32 v68, v2
	v_mov_b32_e32 v69, v2
	v_mov_b32_e32 v10, v2
	v_mov_b32_e32 v11, v2
	v_mov_b32_e32 v12, v2
	v_mov_b32_e32 v13, v2
	v_mov_b32_e32 v74, v2
	v_mov_b32_e32 v75, v2
	v_mov_b32_e32 v76, v2
	v_mov_b32_e32 v77, v2
	v_mov_b32_e32 v18, v2
	v_mov_b32_e32 v19, v2
	v_mov_b32_e32 v20, v2
	v_mov_b32_e32 v21, v2
	v_mov_b32_e32 v82, v2
	v_mov_b32_e32 v83, v2
	v_mov_b32_e32 v84, v2
	v_mov_b32_e32 v85, v2
	v_mov_b32_e32 v26, v2
	v_mov_b32_e32 v27, v2
	v_mov_b32_e32 v28, v2
	v_mov_b32_e32 v29, v2
	v_mov_b32_e32 v90, v2
	v_mov_b32_e32 v91, v2
	v_mov_b32_e32 v92, v2
	v_mov_b32_e32 v93, v2
	v_mov_b32_e32 v6, v2
	v_mov_b32_e32 v7, v2
	v_mov_b32_e32 v8, v2
	v_mov_b32_e32 v9, v2
	v_mov_b32_e32 v70, v2
	v_mov_b32_e32 v71, v2
	v_mov_b32_e32 v72, v2
	v_mov_b32_e32 v73, v2
	v_mov_b32_e32 v14, v2
	v_mov_b32_e32 v15, v2
	v_mov_b32_e32 v16, v2
	v_mov_b32_e32 v17, v2
	v_mov_b32_e32 v78, v2
	v_mov_b32_e32 v79, v2
	v_mov_b32_e32 v80, v2
	v_mov_b32_e32 v81, v2
	v_mov_b32_e32 v22, v2
	v_mov_b32_e32 v23, v2
	v_mov_b32_e32 v24, v2
	v_mov_b32_e32 v25, v2
	v_mov_b32_e32 v86, v2
	v_mov_b32_e32 v87, v2
	v_mov_b32_e32 v88, v2
	v_mov_b32_e32 v89, v2
	v_mov_b32_e32 v30, v2
	v_mov_b32_e32 v31, v2
	v_mov_b32_e32 v32, v2
	v_mov_b32_e32 v33, v2
	v_mov_b32_e32 v94, v2
	v_mov_b32_e32 v95, v2
	v_mov_b32_e32 v96, v2
	v_mov_b32_e32 v97, v2
	v_mov_b32_e32 v34, v2
	v_mov_b32_e32 v35, v2
	v_mov_b32_e32 v36, v2
	v_mov_b32_e32 v37, v2
	v_mov_b32_e32 v98, v2
	v_mov_b32_e32 v99, v2
	v_mov_b32_e32 v100, v2
	v_mov_b32_e32 v101, v2
	v_mov_b32_e32 v42, v2
	v_mov_b32_e32 v43, v2
	v_mov_b32_e32 v44, v2
	v_mov_b32_e32 v45, v2
	v_mov_b32_e32 v106, v2
	v_mov_b32_e32 v107, v2
	v_mov_b32_e32 v108, v2
	v_mov_b32_e32 v109, v2
	v_mov_b32_e32 v50, v2
	v_mov_b32_e32 v51, v2
	v_mov_b32_e32 v52, v2
	v_mov_b32_e32 v53, v2
	v_mov_b32_e32 v146, v2
	v_mov_b32_e32 v147, v2
	v_mov_b32_e32 v148, v2
	v_mov_b32_e32 v149, v2
	v_mov_b32_e32 v58, v2
	v_mov_b32_e32 v59, v2
	v_mov_b32_e32 v60, v2
	v_mov_b32_e32 v61, v2
	v_mov_b32_e32 v154, v2
	v_mov_b32_e32 v155, v2
	v_mov_b32_e32 v156, v2
	v_mov_b32_e32 v157, v2
	v_mov_b32_e32 v38, v2
	v_mov_b32_e32 v39, v2
	v_mov_b32_e32 v40, v2
	v_mov_b32_e32 v41, v2
	v_mov_b32_e32 v102, v2
	v_mov_b32_e32 v103, v2
	v_mov_b32_e32 v104, v2
	v_mov_b32_e32 v105, v2
	v_mov_b32_e32 v46, v2
	v_mov_b32_e32 v47, v2
	v_mov_b32_e32 v48, v2
	v_mov_b32_e32 v49, v2
	v_mov_b32_e32 v122, v2
	v_mov_b32_e32 v123, v2
	v_mov_b32_e32 v124, v2
	v_mov_b32_e32 v125, v2
	v_mov_b32_e32 v54, v2
	v_mov_b32_e32 v55, v2
	v_mov_b32_e32 v56, v2
	v_mov_b32_e32 v57, v2
	v_mov_b32_e32 v150, v2
	v_mov_b32_e32 v151, v2
	v_mov_b32_e32 v152, v2
	v_mov_b32_e32 v153, v2
	v_mov_b32_e32 v62, v2
	v_mov_b32_e32 v63, v2
	v_mov_b32_e32 v64, v2
	v_mov_b32_e32 v65, v2
	v_mov_b32_e32 v158, v2
	v_mov_b32_e32 v159, v2
	v_mov_b32_e32 v160, v2
	v_mov_b32_e32 v161, v2
	s_and_b64 vcc, exec, s[22:23]
	s_cbranch_vccz .Lkprio_skip_P9
	s_setprio 1
.Lkprio_skip_P9:
.LBB0_903:
	ds_read_b128 v[110:113], v218 offset:32768
	ds_read_b128 v[114:117], v218 offset:33792
	ds_read_b128 v[118:121], v218 offset:34816
	ds_read_b128 v[126:129], v218 offset:35840
	ds_read_b128 v[130:133], v218 offset:49152
	ds_read_b128 v[134:137], v218 offset:50176
	ds_read_b128 v[138:141], v218 offset:51200
	ds_read_b128 v[142:145], v218 offset:52224
	s_mov_b32 s73, s69
	s_mov_b32 s69, s66
	s_mov_b32 s66, s54
	s_add_u32 s54, s52, 0xfff00080
	s_addc_u32 s55, s53, -1
	s_cmp_eq_u32 s75, 60
	s_cselect_b32 s56, s13, s54
	s_cselect_b32 s54, s45, s47
	s_cselect_b32 s57, s11, s55
	s_cselect_b32 s55, s33, s74
	v_add_u32_e32 v210, s66, v216
	v_lshl_add_u64 v[214:215], s[52:53], 0, v[174:175]
	s_add_i32 m0, s59, 0x4000
	ds_read_b128 v[182:185], v210
	ds_read_b128 v[186:189], v210 offset:1024
	ds_read_b128 v[190:193], v210 offset:2048
	ds_read_b128 v[194:197], v210 offset:3072
	ds_read_b128 v[198:201], v210 offset:4096
	ds_read_b128 v[202:205], v210 offset:5120
	ds_read_b128 v[206:209], v210 offset:6144
	ds_read_b128 v[210:213], v210 offset:7168
	global_load_lds_dwordx4 v[214:215], off
	v_lshl_add_u64 v[214:215], s[52:53], 0, v[176:177]
	s_add_i32 m0, s59, 0x6000
	s_add_i32 s76, s59, s73
	global_load_lds_dwordx4 v[214:215], off
	v_lshl_add_u64 v[214:215], s[56:57], 0, v[162:163]
	s_mov_b32 m0, s76
	v_lshl_add_u64 v[220:221], s[56:57], 0, v[166:167]
	global_load_lds_dwordx4 v[214:215], off
	s_add_i32 m0, s76, 0x2000
	s_nop 0
	global_load_lds_dwordx4 v[220:221], off
	s_waitcnt vmcnt(10)
	s_waitcnt lgkmcnt(0)
	s_barrier
; #define PG8_STAGE(bufoff, gbase, voff) do { _Pragma("unroll") for (int _i = 0; _i < 2; ++_i) \
;         __builtin_amdgcn_global_load_lds((const unsigned*)((const char*)(gbase) + (voff)[_i]), (LAS unsigned*)(lds + (bufoff) + ldsw + _i * 8192), 16, 0, 0); } while (0)
; #define PG8_LDA(dst, off) do { _Pragma("unroll") for (int m = 0; m < 4; ++m) _Pragma("unroll") for (int k = 0; k < 2; ++k) dst[m][k] = *(const LAS bf16x8*)(lds + (off) + aoff + m * 2048 + k * 1024); } while (0)
; #define PG8_MMA(ai, bj, At, Bt) do { __builtin_amdgcn_s_setprio(1); _Pragma("unroll") for (int m = 0; m < 4; ++m) _Pragma("unroll") for (int n = 0; n < 2; ++n) _Pragma("unroll") for (int k = 0; k < 2; ++k) \
;         acc[ai][bj][m][n] = __builtin_amdgcn_mfma_f32_16x16x32_bf16(Bt[n][k], At[m][k], acc[ai][bj][m][n], 0, 0, 0); __builtin_amdgcn_s_setprio(0); } while (0)
; #define PG8_WAIT_V(n) asm volatile("s_waitcnt vmcnt(" #n ")" ::: "memory")
; #define PG8_WAIT_L(n) asm volatile("s_waitcnt lgkmcnt(" #n ")" ::: "memory")
; #define PG8_BAR __builtin_amdgcn_s_barrier()
; #define PG8_SCHED __builtin_amdgcn_sched_barrier(0)
; template <class Epi, bool ALIGN_EPI = true>
; __device__ __forceinline__ void gemm_phase(LAS unsigned char* lds, const Gemm g, const StaticOrder& S, const Epi& E) {
;     ...
;             PG8_WAIT_V(10); PG8_WAIT_L(0); PG8_BAR; PG8_MMA(0, 0, At, B0); PG8_MMA(0, 1, At, B1); PG8_BAR; PG8_SCHED;
;             PG8_LDA(At, PG8_SA1(0)); PG8_STAGE(PG8_SB(0, 0), b2, voffB); PG8_STAGE(PG8_SB(0, 1), b2 + hstep, voffB);
;             PG8_WAIT_V(8); PG8_WAIT_L(0); PG8_BAR; PG8_MMA(1, 0, At, B0); PG8_MMA(1, 1, At, B1); PG8_BAR; PG8_SCHED;
	s_waitcnt lgkmcnt(0)
	v_mfma_f32_16x16x32_bf16 v[158:161], v[110:113], v[182:185], v[158:161]
	v_mfma_f32_16x16x32_bf16 v[158:161], v[114:117], v[186:189], v[158:161]
	v_mfma_f32_16x16x32_bf16 v[62:65], v[118:121], v[182:185], v[62:65]
	v_mfma_f32_16x16x32_bf16 v[62:65], v[126:129], v[186:189], v[62:65]
	v_mfma_f32_16x16x32_bf16 v[154:157], v[130:133], v[182:185], v[154:157]
	v_mfma_f32_16x16x32_bf16 v[154:157], v[134:137], v[186:189], v[154:157]
	v_mfma_f32_16x16x32_bf16 v[58:61], v[138:141], v[182:185], v[58:61]
	v_mfma_f32_16x16x32_bf16 v[58:61], v[142:145], v[186:189], v[58:61]
	v_mfma_f32_16x16x32_bf16 v[150:153], v[110:113], v[190:193], v[150:153]
	v_mfma_f32_16x16x32_bf16 v[150:153], v[114:117], v[194:197], v[150:153]
	v_mfma_f32_16x16x32_bf16 v[54:57], v[118:121], v[190:193], v[54:57]
	v_mfma_f32_16x16x32_bf16 v[54:57], v[126:129], v[194:197], v[54:57]
	v_mfma_f32_16x16x32_bf16 v[146:149], v[130:133], v[190:193], v[146:149]
	v_mfma_f32_16x16x32_bf16 v[146:149], v[134:137], v[194:197], v[146:149]
	v_mfma_f32_16x16x32_bf16 v[50:53], v[138:141], v[190:193], v[50:53]
	v_mfma_f32_16x16x32_bf16 v[50:53], v[142:145], v[194:197], v[50:53]
	v_mfma_f32_16x16x32_bf16 v[122:125], v[110:113], v[198:201], v[122:125]
	v_mfma_f32_16x16x32_bf16 v[122:125], v[114:117], v[202:205], v[122:125]
	v_mfma_f32_16x16x32_bf16 v[46:49], v[118:121], v[198:201], v[46:49]
	v_mfma_f32_16x16x32_bf16 v[46:49], v[126:129], v[202:205], v[46:49]
	v_mfma_f32_16x16x32_bf16 v[106:109], v[130:133], v[198:201], v[106:109]
	v_mfma_f32_16x16x32_bf16 v[106:109], v[134:137], v[202:205], v[106:109]
	v_mfma_f32_16x16x32_bf16 v[42:45], v[138:141], v[198:201], v[42:45]
	v_mfma_f32_16x16x32_bf16 v[42:45], v[142:145], v[202:205], v[42:45]
	v_mfma_f32_16x16x32_bf16 v[102:105], v[110:113], v[206:209], v[102:105]
	v_mfma_f32_16x16x32_bf16 v[102:105], v[114:117], v[210:213], v[102:105]
	v_mfma_f32_16x16x32_bf16 v[38:41], v[118:121], v[206:209], v[38:41]
	v_mfma_f32_16x16x32_bf16 v[38:41], v[126:129], v[210:213], v[38:41]
	v_mfma_f32_16x16x32_bf16 v[98:101], v[130:133], v[206:209], v[98:101]
	v_mfma_f32_16x16x32_bf16 v[98:101], v[134:137], v[210:213], v[98:101]
	v_mfma_f32_16x16x32_bf16 v[34:37], v[138:141], v[206:209], v[34:37]
	v_mfma_f32_16x16x32_bf16 v[34:37], v[142:145], v[210:213], v[34:37]
	s_barrier
	s_mov_b32 m0, s60
	v_lshl_add_u64 v[222:223], s[54:55], 0, v[164:165]
	s_add_u32 s76, s54, 0x100000
	ds_read_b128 v[182:185], v216
	ds_read_b128 v[186:189], v216 offset:1024
	ds_read_b128 v[190:193], v216 offset:2048
	ds_read_b128 v[194:197], v216 offset:3072
	ds_read_b128 v[198:201], v216 offset:4096
	ds_read_b128 v[202:205], v216 offset:5120
	ds_read_b128 v[206:209], v216 offset:6144
	ds_read_b128 v[210:213], v216 offset:7168
	global_load_lds_dwordx4 v[222:223], off
	v_lshl_add_u64 v[224:225], s[54:55], 0, v[168:169]
	s_mov_b32 m0, s61
	s_addc_u32 s77, s55, 0
	global_load_lds_dwordx4 v[224:225], off
	v_lshl_add_u64 v[226:227], s[76:77], 0, v[164:165]
	s_mov_b32 m0, s62
	s_nop 0
	global_load_lds_dwordx4 v[226:227], off
	v_lshl_add_u64 v[226:227], s[76:77], 0, v[168:169]
	s_mov_b32 m0, s63
	s_nop 0
	global_load_lds_dwordx4 v[226:227], off
	s_waitcnt vmcnt(8)
	s_waitcnt lgkmcnt(0)
	s_barrier
	s_waitcnt lgkmcnt(0)
	v_mfma_f32_16x16x32_bf16 v[94:97], v[110:113], v[182:185], v[94:97]
	v_mfma_f32_16x16x32_bf16 v[94:97], v[114:117], v[186:189], v[94:97]
	v_mfma_f32_16x16x32_bf16 v[30:33], v[118:121], v[182:185], v[30:33]
	v_mfma_f32_16x16x32_bf16 v[30:33], v[126:129], v[186:189], v[30:33]
	v_mfma_f32_16x16x32_bf16 v[90:93], v[130:133], v[182:185], v[90:93]
	v_mfma_f32_16x16x32_bf16 v[90:93], v[134:137], v[186:189], v[90:93]
	v_mfma_f32_16x16x32_bf16 v[26:29], v[138:141], v[182:185], v[26:29]
	v_mfma_f32_16x16x32_bf16 v[26:29], v[142:145], v[186:189], v[26:29]
	v_mfma_f32_16x16x32_bf16 v[86:89], v[110:113], v[190:193], v[86:89]
	v_mfma_f32_16x16x32_bf16 v[86:89], v[114:117], v[194:197], v[86:89]
	v_mfma_f32_16x16x32_bf16 v[22:25], v[118:121], v[190:193], v[22:25]
	v_mfma_f32_16x16x32_bf16 v[22:25], v[126:129], v[194:197], v[22:25]
	v_mfma_f32_16x16x32_bf16 v[82:85], v[130:133], v[190:193], v[82:85]
	v_mfma_f32_16x16x32_bf16 v[82:85], v[134:137], v[194:197], v[82:85]
	v_mfma_f32_16x16x32_bf16 v[18:21], v[138:141], v[190:193], v[18:21]
	v_mfma_f32_16x16x32_bf16 v[18:21], v[142:145], v[194:197], v[18:21]
	v_mfma_f32_16x16x32_bf16 v[78:81], v[110:113], v[198:201], v[78:81]
	v_mfma_f32_16x16x32_bf16 v[78:81], v[114:117], v[202:205], v[78:81]
	v_mfma_f32_16x16x32_bf16 v[14:17], v[118:121], v[198:201], v[14:17]
	v_mfma_f32_16x16x32_bf16 v[14:17], v[126:129], v[202:205], v[14:17]
	v_mfma_f32_16x16x32_bf16 v[74:77], v[130:133], v[198:201], v[74:77]
	v_mfma_f32_16x16x32_bf16 v[74:77], v[134:137], v[202:205], v[74:77]
	v_mfma_f32_16x16x32_bf16 v[10:13], v[138:141], v[198:201], v[10:13]
	v_mfma_f32_16x16x32_bf16 v[10:13], v[142:145], v[202:205], v[10:13]
	v_mfma_f32_16x16x32_bf16 v[70:73], v[110:113], v[206:209], v[70:73]
	v_mfma_f32_16x16x32_bf16 v[70:73], v[114:117], v[210:213], v[70:73]
	v_mfma_f32_16x16x32_bf16 v[6:9], v[118:121], v[206:209], v[6:9]
	v_mfma_f32_16x16x32_bf16 v[6:9], v[126:129], v[210:213], v[6:9]
	v_mfma_f32_16x16x32_bf16 v[66:69], v[130:133], v[206:209], v[66:69]
	v_mfma_f32_16x16x32_bf16 v[66:69], v[134:137], v[210:213], v[66:69]
	v_mfma_f32_16x16x32_bf16 v[2:5], v[138:141], v[206:209], v[2:5]
	v_mfma_f32_16x16x32_bf16 v[2:5], v[142:145], v[210:213], v[2:5]
	s_barrier
; #define PG8_STAGE(bufoff, gbase, voff) do { _Pragma("unroll") for (int _i = 0; _i < 2; ++_i) \
;         __builtin_amdgcn_global_load_lds((const unsigned*)((const char*)(gbase) + (voff)[_i]), (LAS unsigned*)(lds + (bufoff) + ldsw + _i * 8192), 16, 0, 0); } while (0)
; #define PG8_LDA(dst, off) do { _Pragma("unroll") for (int m = 0; m < 4; ++m) _Pragma("unroll") for (int k = 0; k < 2; ++k) dst[m][k] = *(const LAS bf16x8*)(lds + (off) + aoff + m * 2048 + k * 1024); } while (0)
; #define PG8_LDB(dst, b, h) do { _Pragma("unroll") for (int n = 0; n < 2; ++n) _Pragma("unroll") for (int k = 0; k < 2; ++k) dst[n][k] = *(const LAS bf16x8*)(lds + PG8_SB(b, h) + boff + n * 2048 + k * 1024); } while (0)
; #define PG8_MMA(ai, bj, At, Bt) do { __builtin_amdgcn_s_setprio(1); _Pragma("unroll") for (int m = 0; m < 4; ++m) _Pragma("unroll") for (int n = 0; n < 2; ++n) _Pragma("unroll") for (int k = 0; k < 2; ++k) \
;         acc[ai][bj][m][n] = __builtin_amdgcn_mfma_f32_16x16x32_bf16(Bt[n][k], At[m][k], acc[ai][bj][m][n], 0, 0, 0); __builtin_amdgcn_s_setprio(0); } while (0)
; #define PG8_WAIT_V(n) asm volatile("s_waitcnt vmcnt(" #n ")" ::: "memory")
; #define PG8_WAIT_L(n) asm volatile("s_waitcnt lgkmcnt(" #n ")" ::: "memory")
; #define PG8_BAR __builtin_amdgcn_s_barrier()
; #define PG8_SCHED __builtin_amdgcn_sched_barrier(0)
; template <class Epi, bool ALIGN_EPI = true>
; __device__ __forceinline__ void gemm_phase(LAS unsigned char* lds, const Gemm g, const StaticOrder& S, const Epi& E) {
;     ...
;             PG8_LDB(B0, 1, 0); PG8_LDB(B1, 1, 1); PG8_SCHED; PG8_LDA(At, o1); PG8_STAGE(PG8_SA1(0), a2 + hstep, voffA); PG8_STAGE(o0, a3, voffA);
;             PG8_WAIT_V(10); PG8_WAIT_L(0); PG8_BAR; PG8_MMA(0, 0, At, B0); PG8_MMA(0, 1, At, B1); PG8_BAR; PG8_SCHED;
	s_add_i32 s76, 0, 0x10000
	s_add_i32 s77, 0, 0x14000
	v_add_u32_e32 v126, s76, v171
	v_add_u32_e32 v142, s77, v171
	ds_read_b128 v[110:113], v126
	ds_read_b128 v[114:117], v126 offset:1024
	ds_read_b128 v[118:121], v126 offset:2048
	ds_read_b128 v[126:129], v126 offset:3072
	ds_read_b128 v[130:133], v142
	ds_read_b128 v[134:137], v142 offset:1024
	ds_read_b128 v[138:141], v142 offset:2048
	ds_read_b128 v[142:145], v142 offset:3072
	s_add_u32 s56, s56, 0x100000
	s_addc_u32 s57, s57, 0
	s_mov_b32 m0, s59
	v_add_u32_e32 v210, s69, v216
	v_lshl_add_u64 v[226:227], s[56:57], 0, v[162:163]
	ds_read_b128 v[182:185], v210
	ds_read_b128 v[186:189], v210 offset:1024
	ds_read_b128 v[190:193], v210 offset:2048
	ds_read_b128 v[194:197], v210 offset:3072
	ds_read_b128 v[198:201], v210 offset:4096
	ds_read_b128 v[202:205], v210 offset:5120
	ds_read_b128 v[206:209], v210 offset:6144
	ds_read_b128 v[210:213], v210 offset:7168
	global_load_lds_dwordx4 v[226:227], off
	v_lshl_add_u64 v[226:227], s[56:57], 0, v[166:167]
	s_mov_b32 m0, s64
	s_add_i32 s56, s59, s66
	global_load_lds_dwordx4 v[226:227], off
	v_lshl_add_u64 v[214:215], v[214:215], 0, s[24:25]
	s_mov_b32 m0, s56
	s_nop 0
	global_load_lds_dwordx4 v[214:215], off
	v_lshl_add_u64 v[214:215], v[220:221], 0, s[24:25]
	s_add_i32 m0, s56, 0x2000
	s_nop 0
	global_load_lds_dwordx4 v[214:215], off
	s_waitcnt vmcnt(10)
	s_waitcnt lgkmcnt(0)
	s_barrier
	s_waitcnt lgkmcnt(0)
	v_mfma_f32_16x16x32_bf16 v[158:161], v[110:113], v[182:185], v[158:161]
	v_mfma_f32_16x16x32_bf16 v[158:161], v[114:117], v[186:189], v[158:161]
	v_mfma_f32_16x16x32_bf16 v[62:65], v[118:121], v[182:185], v[62:65]
	v_mfma_f32_16x16x32_bf16 v[62:65], v[126:129], v[186:189], v[62:65]
	v_mfma_f32_16x16x32_bf16 v[154:157], v[130:133], v[182:185], v[154:157]
	v_mfma_f32_16x16x32_bf16 v[154:157], v[134:137], v[186:189], v[154:157]
	v_mfma_f32_16x16x32_bf16 v[58:61], v[138:141], v[182:185], v[58:61]
	v_mfma_f32_16x16x32_bf16 v[58:61], v[142:145], v[186:189], v[58:61]
	v_mfma_f32_16x16x32_bf16 v[150:153], v[110:113], v[190:193], v[150:153]
	v_mfma_f32_16x16x32_bf16 v[150:153], v[114:117], v[194:197], v[150:153]
	v_mfma_f32_16x16x32_bf16 v[54:57], v[118:121], v[190:193], v[54:57]
	v_mfma_f32_16x16x32_bf16 v[54:57], v[126:129], v[194:197], v[54:57]
	v_mfma_f32_16x16x32_bf16 v[146:149], v[130:133], v[190:193], v[146:149]
	v_mfma_f32_16x16x32_bf16 v[146:149], v[134:137], v[194:197], v[146:149]
	v_mfma_f32_16x16x32_bf16 v[50:53], v[138:141], v[190:193], v[50:53]
	v_mfma_f32_16x16x32_bf16 v[50:53], v[142:145], v[194:197], v[50:53]
	v_mfma_f32_16x16x32_bf16 v[122:125], v[110:113], v[198:201], v[122:125]
	v_mfma_f32_16x16x32_bf16 v[122:125], v[114:117], v[202:205], v[122:125]
	v_mfma_f32_16x16x32_bf16 v[46:49], v[118:121], v[198:201], v[46:49]
	v_mfma_f32_16x16x32_bf16 v[46:49], v[126:129], v[202:205], v[46:49]
	v_mfma_f32_16x16x32_bf16 v[106:109], v[130:133], v[198:201], v[106:109]
	v_mfma_f32_16x16x32_bf16 v[106:109], v[134:137], v[202:205], v[106:109]
	v_mfma_f32_16x16x32_bf16 v[42:45], v[138:141], v[198:201], v[42:45]
	v_mfma_f32_16x16x32_bf16 v[42:45], v[142:145], v[202:205], v[42:45]
	v_mfma_f32_16x16x32_bf16 v[102:105], v[110:113], v[206:209], v[102:105]
	v_mfma_f32_16x16x32_bf16 v[102:105], v[114:117], v[210:213], v[102:105]
	v_mfma_f32_16x16x32_bf16 v[38:41], v[118:121], v[206:209], v[38:41]
	v_mfma_f32_16x16x32_bf16 v[38:41], v[126:129], v[210:213], v[38:41]
	v_mfma_f32_16x16x32_bf16 v[98:101], v[130:133], v[206:209], v[98:101]
	v_mfma_f32_16x16x32_bf16 v[98:101], v[134:137], v[210:213], v[98:101]
	v_mfma_f32_16x16x32_bf16 v[34:37], v[138:141], v[206:209], v[34:37]
	v_mfma_f32_16x16x32_bf16 v[34:37], v[142:145], v[210:213], v[34:37]
	s_barrier
; #define PG8_STAGE(bufoff, gbase, voff) do { _Pragma("unroll") for (int _i = 0; _i < 2; ++_i) \
;         __builtin_amdgcn_global_load_lds((const unsigned*)((const char*)(gbase) + (voff)[_i]), (LAS unsigned*)(lds + (bufoff) + ldsw + _i * 8192), 16, 0, 0); } while (0)
; #define PG8_LDA(dst, off) do { _Pragma("unroll") for (int m = 0; m < 4; ++m) _Pragma("unroll") for (int k = 0; k < 2; ++k) dst[m][k] = *(const LAS bf16x8*)(lds + (off) + aoff + m * 2048 + k * 1024); } while (0)
; #define PG8_MMA(ai, bj, At, Bt) do { __builtin_amdgcn_s_setprio(1); _Pragma("unroll") for (int m = 0; m < 4; ++m) _Pragma("unroll") for (int n = 0; n < 2; ++n) _Pragma("unroll") for (int k = 0; k < 2; ++k) \
;         acc[ai][bj][m][n] = __builtin_amdgcn_mfma_f32_16x16x32_bf16(Bt[n][k], At[m][k], acc[ai][bj][m][n], 0, 0, 0); __builtin_amdgcn_s_setprio(0); } while (0)
; #define PG8_WAIT_V(n) asm volatile("s_waitcnt vmcnt(" #n ")" ::: "memory")
; #define PG8_WAIT_L(n) asm volatile("s_waitcnt lgkmcnt(" #n ")" ::: "memory")
; #define PG8_BAR __builtin_amdgcn_s_barrier()
; #define PG8_SCHED __builtin_amdgcn_sched_barrier(0)
; template <class Epi, bool ALIGN_EPI = true>
; __device__ __forceinline__ void gemm_phase(LAS unsigned char* lds, const Gemm g, const StaticOrder& S, const Epi& E) {
;     ...
;             PG8_LDA(At, PG8_SA1(1)); PG8_STAGE(PG8_SB(1, 0), b3, voffB); PG8_STAGE(PG8_SB(1, 1), b3 + hstep, voffB);
;             PG8_WAIT_V(8); PG8_WAIT_L(0); PG8_BAR; PG8_MMA(1, 0, At, B0); PG8_MMA(1, 1, At, B1); PG8_BAR; PG8_SCHED;
;             { const int t_ = o0; o0 = o2; o2 = o1; o1 = t_; }
;         }
;         if constexpr (ALIGN_EPI) { if (wr == 0) PG8_BAR; }
	s_add_i32 s56, s76, s58
	v_lshl_add_u64 v[214:215], v[222:223], 0, s[24:25]
	s_mov_b32 m0, s56
	ds_read_b128 v[182:185], v216 offset:16384
	ds_read_b128 v[186:189], v216 offset:17408
	ds_read_b128 v[190:193], v216 offset:18432
	ds_read_b128 v[194:197], v216 offset:19456
	ds_read_b128 v[198:201], v216 offset:20480
	ds_read_b128 v[202:205], v216 offset:21504
	ds_read_b128 v[206:209], v216 offset:22528
	ds_read_b128 v[210:213], v216 offset:23552
	global_load_lds_dwordx4 v[214:215], off
	s_add_i32 m0, s56, 0x2000
	s_add_u32 s54, s54, 0x100080
	v_lshl_add_u64 v[214:215], v[224:225], 0, s[24:25]
	s_addc_u32 s55, s55, 0
	s_add_i32 s56, s77, s58
	global_load_lds_dwordx4 v[214:215], off
	v_lshl_add_u64 v[214:215], s[54:55], 0, v[164:165]
	s_mov_b32 m0, s56
	s_nop 0
	global_load_lds_dwordx4 v[214:215], off
	v_lshl_add_u64 v[214:215], s[54:55], 0, v[168:169]
	s_add_i32 m0, s56, 0x2000
	s_nop 0
	global_load_lds_dwordx4 v[214:215], off
	s_waitcnt vmcnt(8)
	s_waitcnt lgkmcnt(0)
	s_barrier
	s_waitcnt lgkmcnt(0)
	v_mfma_f32_16x16x32_bf16 v[94:97], v[110:113], v[182:185], v[94:97]
	v_mfma_f32_16x16x32_bf16 v[94:97], v[114:117], v[186:189], v[94:97]
	v_mfma_f32_16x16x32_bf16 v[30:33], v[118:121], v[182:185], v[30:33]
	v_mfma_f32_16x16x32_bf16 v[30:33], v[126:129], v[186:189], v[30:33]
	v_mfma_f32_16x16x32_bf16 v[90:93], v[130:133], v[182:185], v[90:93]
	v_mfma_f32_16x16x32_bf16 v[90:93], v[134:137], v[186:189], v[90:93]
	v_mfma_f32_16x16x32_bf16 v[26:29], v[138:141], v[182:185], v[26:29]
	v_mfma_f32_16x16x32_bf16 v[26:29], v[142:145], v[186:189], v[26:29]
	v_mfma_f32_16x16x32_bf16 v[86:89], v[110:113], v[190:193], v[86:89]
	v_mfma_f32_16x16x32_bf16 v[86:89], v[114:117], v[194:197], v[86:89]
	v_mfma_f32_16x16x32_bf16 v[22:25], v[118:121], v[190:193], v[22:25]
	v_mfma_f32_16x16x32_bf16 v[22:25], v[126:129], v[194:197], v[22:25]
	v_mfma_f32_16x16x32_bf16 v[82:85], v[130:133], v[190:193], v[82:85]
	v_mfma_f32_16x16x32_bf16 v[82:85], v[134:137], v[194:197], v[82:85]
	v_mfma_f32_16x16x32_bf16 v[18:21], v[138:141], v[190:193], v[18:21]
	v_mfma_f32_16x16x32_bf16 v[18:21], v[142:145], v[194:197], v[18:21]
	v_mfma_f32_16x16x32_bf16 v[78:81], v[110:113], v[198:201], v[78:81]
	v_mfma_f32_16x16x32_bf16 v[78:81], v[114:117], v[202:205], v[78:81]
	v_mfma_f32_16x16x32_bf16 v[14:17], v[118:121], v[198:201], v[14:17]
	v_mfma_f32_16x16x32_bf16 v[14:17], v[126:129], v[202:205], v[14:17]
	v_mfma_f32_16x16x32_bf16 v[74:77], v[130:133], v[198:201], v[74:77]
	v_mfma_f32_16x16x32_bf16 v[74:77], v[134:137], v[202:205], v[74:77]
	v_mfma_f32_16x16x32_bf16 v[10:13], v[138:141], v[198:201], v[10:13]
	v_mfma_f32_16x16x32_bf16 v[10:13], v[142:145], v[202:205], v[10:13]
	v_mfma_f32_16x16x32_bf16 v[70:73], v[110:113], v[206:209], v[70:73]
	v_mfma_f32_16x16x32_bf16 v[70:73], v[114:117], v[210:213], v[70:73]
	v_mfma_f32_16x16x32_bf16 v[6:9], v[118:121], v[206:209], v[6:9]
	v_mfma_f32_16x16x32_bf16 v[6:9], v[126:129], v[210:213], v[6:9]
	v_mfma_f32_16x16x32_bf16 v[66:69], v[130:133], v[206:209], v[66:69]
	v_mfma_f32_16x16x32_bf16 v[66:69], v[134:137], v[210:213], v[66:69]
	v_mfma_f32_16x16x32_bf16 v[2:5], v[138:141], v[206:209], v[2:5]
	v_mfma_f32_16x16x32_bf16 v[2:5], v[142:145], v[210:213], v[2:5]
	s_barrier
	s_add_i32 s75, s75, 2
	s_add_u32 s52, s52, 0x100
	s_addc_u32 s53, s53, 0
	s_add_u32 s47, s47, 0x100
	s_addc_u32 s74, s74, 0
	s_cmp_gt_u32 s75, 61
	s_mov_b32 s54, s73
	s_cbranch_scc0 .LBB0_903
	s_setprio 0
	s_and_b64 vcc, exec, s[26:27]
	s_cbranch_vccz .LBB0_906
	s_barrier

; #define PG8_STAGE(bufoff, gbase, voff) do { _Pragma("unroll") for (int _i = 0; _i < 2; ++_i) \
;         __builtin_amdgcn_global_load_lds((const unsigned*)((const char*)(gbase) + (voff)[_i]), (LAS unsigned*)(lds + (bufoff) + ldsw + _i * 8192), 16, 0, 0); } while (0)
; #define PG8_LDA(dst, off) do { _Pragma("unroll") for (int m = 0; m < 4; ++m) _Pragma("unroll") for (int k = 0; k < 2; ++k) dst[m][k] = *(const LAS bf16x8*)(lds + (off) + aoff + m * 2048 + k * 1024); } while (0)
; #define PG8_WAIT_V(n) asm volatile("s_waitcnt vmcnt(" #n ")" ::: "memory")
; #define PG8_BAR __builtin_amdgcn_s_barrier()
; template <class Epi, bool ALIGN_EPI = true>
; __device__ __forceinline__ void gemm_phase(LAS unsigned char* lds, const Gemm g, const StaticOrder& S, const Epi& E) {
;     ...
;     for (int a = 0; a < 2; ++a)
; #pragma unroll
;         for (int b = 0; b < 2; ++b)
; #pragma unroll
;             for (int m = 0; m < 4; ++m)
; #pragma unroll
;                 for (int n = 0; n < 2; ++n) acc[a][b][m][n] = (f32x4){0.f, 0.f, 0.f, 0.f};
;     bf16x8 At[4][2], B0[2][2], B1[2][2];
;     const char* cA = PG8_ABASE(cur); const char* cB = PG8_BBASE(cur);
;     int o0 = 6 * HTB, o1 = 7 * HTB, o2 = 8 * HTB;
;     PG8_STAGE(PG8_SB(0, 0), cB, voffB); PG8_STAGE(PG8_SB(0, 1), cB + hstep, voffB); PG8_STAGE(o0, cA, voffA); PG8_STAGE(PG8_SA1(0), cA + hstep, voffA);
;     if (wr == 1) PG8_BAR;
;     PG8_WAIT_V(2); PG8_BAR;
;     PG8_STAGE(PG8_SB(1, 0), cB + kstep, voffB); PG8_STAGE(o1, cA + kstep, voffA); PG8_STAGE(PG8_SB(1, 1), cB + hstep + kstep, voffB);
;     PG8_WAIT_V(6); PG8_BAR;
;     for (;;) {
;         const bool has_next = S.next(ui + 1, nxt);
;         const char* nA = has_next ? PG8_ABASE(nxt) : cA; const char* nB = has_next ? PG8_BBASE(nxt) : cB;
;         for (int t = 0; t < nt; t += 2) {
;             const bool last = (t == nt - 2);
;             const char* a1 = cA + (size_t)(t + 1) * kstep;
;             const char* a2 = last ? nA : cA + (size_t)(t + 2) * kstep; const char* b2 = last ? nB : cB + (size_t)(t + 2) * kstep;
;             const char* a3 = a2 + kstep; const char* b3 = b2 + kstep;
;             PG8_LDB(B0, 0, 0); PG8_LDB(B1, 0, 1); PG8_SCHED; PG8_LDA(At, o0); PG8_STAGE(PG8_SA1(1), a1 + hstep, voffA); PG8_STAGE(o2, a2, voffA);
;             PG8_WAIT_V(10); PG8_WAIT_L(0); PG8_BAR; PG8_MMA(0, 0, At, B0); PG8_MMA(0, 1, At, B1); PG8_BAR; PG8_SCHED;
.LBB0_1076:
	s_add_u32 s28, s28, 0x2b0080
	s_addc_u32 s29, s29, 0
	s_add_u32 s55, s30, 0x100
	v_mov_b32_e32 v0, 0
	s_addc_u32 s56, s31, 0
	s_mov_b32 s57, -2
	s_mov_b32 s30, s52
	v_mov_b32_e32 v1, v0
	v_mov_b32_e32 v2, v0
	v_mov_b32_e32 v3, v0
	v_mov_b32_e32 v4, v0
	v_mov_b32_e32 v5, v0
	v_mov_b32_e32 v6, v0
	v_mov_b32_e32 v7, v0
	v_mov_b32_e32 v16, v0
	v_mov_b32_e32 v17, v0
	v_mov_b32_e32 v18, v0
	v_mov_b32_e32 v19, v0
	v_mov_b32_e32 v20, v0
	v_mov_b32_e32 v21, v0
	v_mov_b32_e32 v22, v0
	v_mov_b32_e32 v23, v0
	v_mov_b32_e32 v32, v0
	v_mov_b32_e32 v33, v0
	v_mov_b32_e32 v34, v0
	v_mov_b32_e32 v35, v0
	v_mov_b32_e32 v36, v0
	v_mov_b32_e32 v37, v0
	v_mov_b32_e32 v38, v0
	v_mov_b32_e32 v39, v0
	v_mov_b32_e32 v48, v0
	v_mov_b32_e32 v49, v0
	v_mov_b32_e32 v50, v0
	v_mov_b32_e32 v51, v0
	v_mov_b32_e32 v52, v0
	v_mov_b32_e32 v53, v0
	v_mov_b32_e32 v54, v0
	v_mov_b32_e32 v55, v0
	v_mov_b32_e32 v8, v0
	v_mov_b32_e32 v9, v0
	v_mov_b32_e32 v10, v0
	v_mov_b32_e32 v11, v0
	v_mov_b32_e32 v12, v0
	v_mov_b32_e32 v13, v0
	v_mov_b32_e32 v14, v0
	v_mov_b32_e32 v15, v0
	v_mov_b32_e32 v24, v0
	v_mov_b32_e32 v25, v0
	v_mov_b32_e32 v26, v0
	v_mov_b32_e32 v27, v0
	v_mov_b32_e32 v28, v0
	v_mov_b32_e32 v29, v0
	v_mov_b32_e32 v30, v0
	v_mov_b32_e32 v31, v0
	v_mov_b32_e32 v40, v0
	v_mov_b32_e32 v41, v0
	v_mov_b32_e32 v42, v0
	v_mov_b32_e32 v43, v0
	v_mov_b32_e32 v44, v0
	v_mov_b32_e32 v45, v0
	v_mov_b32_e32 v46, v0
	v_mov_b32_e32 v47, v0
	v_mov_b32_e32 v56, v0
	v_mov_b32_e32 v57, v0
	v_mov_b32_e32 v58, v0
	v_mov_b32_e32 v59, v0
	v_mov_b32_e32 v60, v0
	v_mov_b32_e32 v61, v0
	v_mov_b32_e32 v62, v0
	v_mov_b32_e32 v63, v0
	v_mov_b32_e32 v64, v0
	v_mov_b32_e32 v65, v0
	v_mov_b32_e32 v66, v0
	v_mov_b32_e32 v67, v0
	v_mov_b32_e32 v68, v0
	v_mov_b32_e32 v69, v0
	v_mov_b32_e32 v70, v0
	v_mov_b32_e32 v71, v0
	v_mov_b32_e32 v80, v0
	v_mov_b32_e32 v81, v0
	v_mov_b32_e32 v82, v0
	v_mov_b32_e32 v83, v0
	v_mov_b32_e32 v84, v0
	v_mov_b32_e32 v85, v0
	v_mov_b32_e32 v86, v0
	v_mov_b32_e32 v87, v0
	v_mov_b32_e32 v96, v0
	v_mov_b32_e32 v97, v0
	v_mov_b32_e32 v98, v0
	v_mov_b32_e32 v99, v0
	v_mov_b32_e32 v100, v0
	v_mov_b32_e32 v101, v0
	v_mov_b32_e32 v102, v0
	v_mov_b32_e32 v103, v0
	v_mov_b32_e32 v112, v0
	v_mov_b32_e32 v113, v0
	v_mov_b32_e32 v114, v0
	v_mov_b32_e32 v115, v0
	v_mov_b32_e32 v116, v0
	v_mov_b32_e32 v117, v0
	v_mov_b32_e32 v118, v0
	v_mov_b32_e32 v119, v0
	v_mov_b32_e32 v72, v0
	v_mov_b32_e32 v73, v0
	v_mov_b32_e32 v74, v0
	v_mov_b32_e32 v75, v0
	v_mov_b32_e32 v76, v0
	v_mov_b32_e32 v77, v0
	v_mov_b32_e32 v78, v0
	v_mov_b32_e32 v79, v0
	v_mov_b32_e32 v88, v0
	v_mov_b32_e32 v89, v0
	v_mov_b32_e32 v90, v0
	v_mov_b32_e32 v91, v0
	v_mov_b32_e32 v92, v0
	v_mov_b32_e32 v93, v0
	v_mov_b32_e32 v94, v0
	v_mov_b32_e32 v95, v0
	v_mov_b32_e32 v104, v0
	v_mov_b32_e32 v105, v0
	v_mov_b32_e32 v106, v0
	v_mov_b32_e32 v107, v0
	v_mov_b32_e32 v108, v0
	v_mov_b32_e32 v109, v0
	v_mov_b32_e32 v110, v0
	v_mov_b32_e32 v111, v0
	v_mov_b32_e32 v136, v0
	v_mov_b32_e32 v137, v0
	v_mov_b32_e32 v138, v0
	v_mov_b32_e32 v139, v0
	v_mov_b32_e32 v140, v0
	v_mov_b32_e32 v141, v0
	v_mov_b32_e32 v142, v0
	v_mov_b32_e32 v143, v0
	s_and_b64 vcc, exec, s[6:7]
	s_cbranch_vccz .Lkprio_skip_P11
	s_setprio 1
.Lkprio_skip_P11:
.LBB0_1077:
	ds_read_b128 v[120:123], v241 offset:32768
	ds_read_b128 v[124:127], v241 offset:33792
	ds_read_b128 v[128:131], v241 offset:34816
	ds_read_b128 v[132:135], v241 offset:35840
	ds_read_b128 v[144:147], v241 offset:49152
	ds_read_b128 v[148:151], v241 offset:50176
	ds_read_b128 v[152:155], v241 offset:51200
	ds_read_b128 v[156:159], v241 offset:52224
	s_mov_b32 s52, s49
	s_mov_b32 s49, s47
	s_mov_b32 s47, s30
	s_add_u32 s30, s28, 0xffd50080
	s_addc_u32 s31, s29, -1
	s_cmpk_eq_i32 s57, 0xa8
	s_cselect_b32 s36, s4, s30
	s_cselect_b32 s30, s26, s55
	s_cselect_b32 s37, s5, s31
	s_cselect_b32 s31, s27, s56
	v_add_u32_e32 v188, s47, v239
	v_lshl_add_u64 v[192:193], s[28:29], 0, v[212:213]
	s_add_i32 m0, s38, 0x4000
	ds_read_b128 v[160:163], v188
	ds_read_b128 v[164:167], v188 offset:1024
	ds_read_b128 v[168:171], v188 offset:2048
	ds_read_b128 v[172:175], v188 offset:3072
	ds_read_b128 v[176:179], v188 offset:4096
	ds_read_b128 v[180:183], v188 offset:5120
	ds_read_b128 v[184:187], v188 offset:6144
	ds_read_b128 v[188:191], v188 offset:7168
	global_load_lds_dwordx4 v[192:193], off
	v_lshl_add_u64 v[192:193], s[28:29], 0, v[214:215]
	s_add_i32 m0, s38, 0x6000
	s_add_i32 s58, s38, s52
	global_load_lds_dwordx4 v[192:193], off
	v_lshl_add_u64 v[192:193], s[36:37], 0, v[204:205]
	s_mov_b32 m0, s58
	v_lshl_add_u64 v[194:195], s[36:37], 0, v[208:209]
	global_load_lds_dwordx4 v[192:193], off
	s_add_i32 m0, s58, 0x2000
	s_nop 0
	global_load_lds_dwordx4 v[194:195], off
	s_waitcnt vmcnt(10)
	s_waitcnt lgkmcnt(0)
	s_barrier
; #define PG8_STAGE(bufoff, gbase, voff) do { _Pragma("unroll") for (int _i = 0; _i < 2; ++_i) \
;         __builtin_amdgcn_global_load_lds((const unsigned*)((const char*)(gbase) + (voff)[_i]), (LAS unsigned*)(lds + (bufoff) + ldsw + _i * 8192), 16, 0, 0); } while (0)
; #define PG8_LDA(dst, off) do { _Pragma("unroll") for (int m = 0; m < 4; ++m) _Pragma("unroll") for (int k = 0; k < 2; ++k) dst[m][k] = *(const LAS bf16x8*)(lds + (off) + aoff + m * 2048 + k * 1024); } while (0)
; #define PG8_MMA(ai, bj, At, Bt) do { __builtin_amdgcn_s_setprio(1); _Pragma("unroll") for (int m = 0; m < 4; ++m) _Pragma("unroll") for (int n = 0; n < 2; ++n) _Pragma("unroll") for (int k = 0; k < 2; ++k) \
;         acc[ai][bj][m][n] = __builtin_amdgcn_mfma_f32_16x16x32_bf16(Bt[n][k], At[m][k], acc[ai][bj][m][n], 0, 0, 0); __builtin_amdgcn_s_setprio(0); } while (0)
; #define PG8_WAIT_V(n) asm volatile("s_waitcnt vmcnt(" #n ")" ::: "memory")
; #define PG8_WAIT_L(n) asm volatile("s_waitcnt lgkmcnt(" #n ")" ::: "memory")
; #define PG8_BAR __builtin_amdgcn_s_barrier()
; #define PG8_SCHED __builtin_amdgcn_sched_barrier(0)
; template <class Epi, bool ALIGN_EPI = true>
; __device__ __forceinline__ void gemm_phase(LAS unsigned char* lds, const Gemm g, const StaticOrder& S, const Epi& E) {
;     ...
;             PG8_WAIT_V(10); PG8_WAIT_L(0); PG8_BAR; PG8_MMA(0, 0, At, B0); PG8_MMA(0, 1, At, B1); PG8_BAR; PG8_SCHED;
;             PG8_LDA(At, PG8_SA1(0)); PG8_STAGE(PG8_SB(0, 0), b2, voffB); PG8_STAGE(PG8_SB(0, 1), b2 + hstep, voffB);
;             PG8_WAIT_V(8); PG8_WAIT_L(0); PG8_BAR; PG8_MMA(1, 0, At, B0); PG8_MMA(1, 1, At, B1); PG8_BAR; PG8_SCHED;
	s_waitcnt lgkmcnt(0)
	v_mfma_f32_16x16x32_bf16 v[140:143], v[120:123], v[160:163], v[140:143]
	v_mfma_f32_16x16x32_bf16 v[140:143], v[124:127], v[164:167], v[140:143]
	v_mfma_f32_16x16x32_bf16 v[136:139], v[128:131], v[160:163], v[136:139]
	v_mfma_f32_16x16x32_bf16 v[136:139], v[132:135], v[164:167], v[136:139]
	v_mfma_f32_16x16x32_bf16 v[116:119], v[144:147], v[160:163], v[116:119]
	v_mfma_f32_16x16x32_bf16 v[116:119], v[148:151], v[164:167], v[116:119]
	v_mfma_f32_16x16x32_bf16 v[112:115], v[152:155], v[160:163], v[112:115]
	v_mfma_f32_16x16x32_bf16 v[112:115], v[156:159], v[164:167], v[112:115]
	v_mfma_f32_16x16x32_bf16 v[108:111], v[120:123], v[168:171], v[108:111]
	v_mfma_f32_16x16x32_bf16 v[108:111], v[124:127], v[172:175], v[108:111]
	v_mfma_f32_16x16x32_bf16 v[104:107], v[128:131], v[168:171], v[104:107]
	v_mfma_f32_16x16x32_bf16 v[104:107], v[132:135], v[172:175], v[104:107]
	v_mfma_f32_16x16x32_bf16 v[100:103], v[144:147], v[168:171], v[100:103]
	v_mfma_f32_16x16x32_bf16 v[100:103], v[148:151], v[172:175], v[100:103]
	v_mfma_f32_16x16x32_bf16 v[96:99], v[152:155], v[168:171], v[96:99]
	v_mfma_f32_16x16x32_bf16 v[96:99], v[156:159], v[172:175], v[96:99]
	v_mfma_f32_16x16x32_bf16 v[92:95], v[120:123], v[176:179], v[92:95]
	v_mfma_f32_16x16x32_bf16 v[92:95], v[124:127], v[180:183], v[92:95]
	v_mfma_f32_16x16x32_bf16 v[88:91], v[128:131], v[176:179], v[88:91]
	v_mfma_f32_16x16x32_bf16 v[88:91], v[132:135], v[180:183], v[88:91]
	v_mfma_f32_16x16x32_bf16 v[84:87], v[144:147], v[176:179], v[84:87]
	v_mfma_f32_16x16x32_bf16 v[84:87], v[148:151], v[180:183], v[84:87]
	v_mfma_f32_16x16x32_bf16 v[80:83], v[152:155], v[176:179], v[80:83]
	v_mfma_f32_16x16x32_bf16 v[80:83], v[156:159], v[180:183], v[80:83]
	v_mfma_f32_16x16x32_bf16 v[76:79], v[120:123], v[184:187], v[76:79]
	v_mfma_f32_16x16x32_bf16 v[76:79], v[124:127], v[188:191], v[76:79]
	v_mfma_f32_16x16x32_bf16 v[72:75], v[128:131], v[184:187], v[72:75]
	v_mfma_f32_16x16x32_bf16 v[72:75], v[132:135], v[188:191], v[72:75]
	v_mfma_f32_16x16x32_bf16 v[68:71], v[144:147], v[184:187], v[68:71]
	v_mfma_f32_16x16x32_bf16 v[68:71], v[148:151], v[188:191], v[68:71]
	v_mfma_f32_16x16x32_bf16 v[64:67], v[152:155], v[184:187], v[64:67]
	v_mfma_f32_16x16x32_bf16 v[64:67], v[156:159], v[188:191], v[64:67]
	s_barrier
	s_mov_b32 m0, s39
	v_lshl_add_u64 v[196:197], s[30:31], 0, v[206:207]
	s_add_u32 s58, s30, 0x2b0000
	ds_read_b128 v[160:163], v239
	ds_read_b128 v[164:167], v239 offset:1024
	ds_read_b128 v[168:171], v239 offset:2048
	ds_read_b128 v[172:175], v239 offset:3072
	ds_read_b128 v[176:179], v239 offset:4096
	ds_read_b128 v[180:183], v239 offset:5120
	ds_read_b128 v[184:187], v239 offset:6144
	ds_read_b128 v[188:191], v239 offset:7168
	global_load_lds_dwordx4 v[196:197], off
	v_lshl_add_u64 v[198:199], s[30:31], 0, v[210:211]
	s_mov_b32 m0, s40
	s_addc_u32 s59, s31, 0
	global_load_lds_dwordx4 v[198:199], off
	v_lshl_add_u64 v[200:201], s[58:59], 0, v[206:207]
	s_mov_b32 m0, s41
	s_nop 0
	global_load_lds_dwordx4 v[200:201], off
	v_lshl_add_u64 v[200:201], s[58:59], 0, v[210:211]
	s_mov_b32 m0, s42
	s_nop 0
	global_load_lds_dwordx4 v[200:201], off
	s_waitcnt vmcnt(8)
	s_waitcnt lgkmcnt(0)
	s_barrier
	s_waitcnt lgkmcnt(0)
	v_mfma_f32_16x16x32_bf16 v[60:63], v[120:123], v[160:163], v[60:63]
	v_mfma_f32_16x16x32_bf16 v[60:63], v[124:127], v[164:167], v[60:63]
	v_mfma_f32_16x16x32_bf16 v[56:59], v[128:131], v[160:163], v[56:59]
	v_mfma_f32_16x16x32_bf16 v[56:59], v[132:135], v[164:167], v[56:59]
	v_mfma_f32_16x16x32_bf16 v[52:55], v[144:147], v[160:163], v[52:55]
	v_mfma_f32_16x16x32_bf16 v[52:55], v[148:151], v[164:167], v[52:55]
	v_mfma_f32_16x16x32_bf16 v[48:51], v[152:155], v[160:163], v[48:51]
	v_mfma_f32_16x16x32_bf16 v[48:51], v[156:159], v[164:167], v[48:51]
	v_mfma_f32_16x16x32_bf16 v[44:47], v[120:123], v[168:171], v[44:47]
	v_mfma_f32_16x16x32_bf16 v[44:47], v[124:127], v[172:175], v[44:47]
	v_mfma_f32_16x16x32_bf16 v[40:43], v[128:131], v[168:171], v[40:43]
	v_mfma_f32_16x16x32_bf16 v[40:43], v[132:135], v[172:175], v[40:43]
	v_mfma_f32_16x16x32_bf16 v[36:39], v[144:147], v[168:171], v[36:39]
	v_mfma_f32_16x16x32_bf16 v[36:39], v[148:151], v[172:175], v[36:39]
	v_mfma_f32_16x16x32_bf16 v[32:35], v[152:155], v[168:171], v[32:35]
	v_mfma_f32_16x16x32_bf16 v[32:35], v[156:159], v[172:175], v[32:35]
	v_mfma_f32_16x16x32_bf16 v[28:31], v[120:123], v[176:179], v[28:31]
	v_mfma_f32_16x16x32_bf16 v[28:31], v[124:127], v[180:183], v[28:31]
	v_mfma_f32_16x16x32_bf16 v[24:27], v[128:131], v[176:179], v[24:27]
	v_mfma_f32_16x16x32_bf16 v[24:27], v[132:135], v[180:183], v[24:27]
	v_mfma_f32_16x16x32_bf16 v[20:23], v[144:147], v[176:179], v[20:23]
	v_mfma_f32_16x16x32_bf16 v[20:23], v[148:151], v[180:183], v[20:23]
	v_mfma_f32_16x16x32_bf16 v[16:19], v[152:155], v[176:179], v[16:19]
	v_mfma_f32_16x16x32_bf16 v[16:19], v[156:159], v[180:183], v[16:19]
	v_mfma_f32_16x16x32_bf16 v[12:15], v[120:123], v[184:187], v[12:15]
	v_mfma_f32_16x16x32_bf16 v[12:15], v[124:127], v[188:191], v[12:15]
	v_mfma_f32_16x16x32_bf16 v[8:11], v[128:131], v[184:187], v[8:11]
	v_mfma_f32_16x16x32_bf16 v[8:11], v[132:135], v[188:191], v[8:11]
	v_mfma_f32_16x16x32_bf16 v[4:7], v[144:147], v[184:187], v[4:7]
	v_mfma_f32_16x16x32_bf16 v[4:7], v[148:151], v[188:191], v[4:7]
	v_mfma_f32_16x16x32_bf16 v[0:3], v[152:155], v[184:187], v[0:3]
	v_mfma_f32_16x16x32_bf16 v[0:3], v[156:159], v[188:191], v[0:3]
	s_barrier
; #define PG8_STAGE(bufoff, gbase, voff) do { _Pragma("unroll") for (int _i = 0; _i < 2; ++_i) \
;         __builtin_amdgcn_global_load_lds((const unsigned*)((const char*)(gbase) + (voff)[_i]), (LAS unsigned*)(lds + (bufoff) + ldsw + _i * 8192), 16, 0, 0); } while (0)
; #define PG8_LDA(dst, off) do { _Pragma("unroll") for (int m = 0; m < 4; ++m) _Pragma("unroll") for (int k = 0; k < 2; ++k) dst[m][k] = *(const LAS bf16x8*)(lds + (off) + aoff + m * 2048 + k * 1024); } while (0)
; #define PG8_LDB(dst, b, h) do { _Pragma("unroll") for (int n = 0; n < 2; ++n) _Pragma("unroll") for (int k = 0; k < 2; ++k) dst[n][k] = *(const LAS bf16x8*)(lds + PG8_SB(b, h) + boff + n * 2048 + k * 1024); } while (0)
; #define PG8_MMA(ai, bj, At, Bt) do { __builtin_amdgcn_s_setprio(1); _Pragma("unroll") for (int m = 0; m < 4; ++m) _Pragma("unroll") for (int n = 0; n < 2; ++n) _Pragma("unroll") for (int k = 0; k < 2; ++k) \
;         acc[ai][bj][m][n] = __builtin_amdgcn_mfma_f32_16x16x32_bf16(Bt[n][k], At[m][k], acc[ai][bj][m][n], 0, 0, 0); __builtin_amdgcn_s_setprio(0); } while (0)
; #define PG8_WAIT_V(n) asm volatile("s_waitcnt vmcnt(" #n ")" ::: "memory")
; #define PG8_WAIT_L(n) asm volatile("s_waitcnt lgkmcnt(" #n ")" ::: "memory")
; #define PG8_BAR __builtin_amdgcn_s_barrier()
; #define PG8_SCHED __builtin_amdgcn_sched_barrier(0)
; template <class Epi, bool ALIGN_EPI = true>
; __device__ __forceinline__ void gemm_phase(LAS unsigned char* lds, const Gemm g, const StaticOrder& S, const Epi& E) {
;     ...
;             PG8_LDB(B0, 1, 0); PG8_LDB(B1, 1, 1); PG8_SCHED; PG8_LDA(At, o1); PG8_STAGE(PG8_SA1(0), a2 + hstep, voffA); PG8_STAGE(o0, a3, voffA);
;             PG8_WAIT_V(10); PG8_WAIT_L(0); PG8_BAR; PG8_MMA(0, 0, At, B0); PG8_MMA(0, 1, At, B1); PG8_BAR; PG8_SCHED;
	s_add_i32 s58, 0, 0x10000
	s_add_i32 s59, 0, 0x14000
	v_add_u32_e32 v132, s58, v238
	v_add_u32_e32 v156, s59, v238
	ds_read_b128 v[120:123], v132
	ds_read_b128 v[124:127], v132 offset:1024
	ds_read_b128 v[128:131], v132 offset:2048
	ds_read_b128 v[132:135], v132 offset:3072
	ds_read_b128 v[144:147], v156
	ds_read_b128 v[148:151], v156 offset:1024
	ds_read_b128 v[152:155], v156 offset:2048
	ds_read_b128 v[156:159], v156 offset:3072
	s_add_u32 s36, s36, 0x2b0000
	s_addc_u32 s37, s37, 0
	s_mov_b32 m0, s38
	v_add_u32_e32 v188, s49, v239
	v_lshl_add_u64 v[200:201], s[36:37], 0, v[204:205]
	ds_read_b128 v[160:163], v188
	ds_read_b128 v[164:167], v188 offset:1024
	ds_read_b128 v[168:171], v188 offset:2048
	ds_read_b128 v[172:175], v188 offset:3072
	ds_read_b128 v[176:179], v188 offset:4096
	ds_read_b128 v[180:183], v188 offset:5120
	ds_read_b128 v[184:187], v188 offset:6144
	ds_read_b128 v[188:191], v188 offset:7168
	global_load_lds_dwordx4 v[200:201], off
	v_lshl_add_u64 v[200:201], s[36:37], 0, v[208:209]
	s_mov_b32 m0, s43
	s_add_i32 s36, s38, s47
	global_load_lds_dwordx4 v[200:201], off
	v_lshl_add_u64 v[192:193], v[192:193], 0, s[8:9]
	s_mov_b32 m0, s36
	s_nop 0
	global_load_lds_dwordx4 v[192:193], off
	v_lshl_add_u64 v[192:193], v[194:195], 0, s[8:9]
	s_add_i32 m0, s36, 0x2000
	s_nop 0
	global_load_lds_dwordx4 v[192:193], off
	s_waitcnt vmcnt(10)
	s_waitcnt lgkmcnt(0)
	s_barrier
	s_waitcnt lgkmcnt(0)
	v_mfma_f32_16x16x32_bf16 v[140:143], v[120:123], v[160:163], v[140:143]
	v_mfma_f32_16x16x32_bf16 v[140:143], v[124:127], v[164:167], v[140:143]
	v_mfma_f32_16x16x32_bf16 v[136:139], v[128:131], v[160:163], v[136:139]
	v_mfma_f32_16x16x32_bf16 v[136:139], v[132:135], v[164:167], v[136:139]
	v_mfma_f32_16x16x32_bf16 v[116:119], v[144:147], v[160:163], v[116:119]
	v_mfma_f32_16x16x32_bf16 v[116:119], v[148:151], v[164:167], v[116:119]
	v_mfma_f32_16x16x32_bf16 v[112:115], v[152:155], v[160:163], v[112:115]
	v_mfma_f32_16x16x32_bf16 v[112:115], v[156:159], v[164:167], v[112:115]
	v_mfma_f32_16x16x32_bf16 v[108:111], v[120:123], v[168:171], v[108:111]
	v_mfma_f32_16x16x32_bf16 v[108:111], v[124:127], v[172:175], v[108:111]
	v_mfma_f32_16x16x32_bf16 v[104:107], v[128:131], v[168:171], v[104:107]
	v_mfma_f32_16x16x32_bf16 v[104:107], v[132:135], v[172:175], v[104:107]
	v_mfma_f32_16x16x32_bf16 v[100:103], v[144:147], v[168:171], v[100:103]
	v_mfma_f32_16x16x32_bf16 v[100:103], v[148:151], v[172:175], v[100:103]
	v_mfma_f32_16x16x32_bf16 v[96:99], v[152:155], v[168:171], v[96:99]
	v_mfma_f32_16x16x32_bf16 v[96:99], v[156:159], v[172:175], v[96:99]
	v_mfma_f32_16x16x32_bf16 v[92:95], v[120:123], v[176:179], v[92:95]
	v_mfma_f32_16x16x32_bf16 v[92:95], v[124:127], v[180:183], v[92:95]
	v_mfma_f32_16x16x32_bf16 v[88:91], v[128:131], v[176:179], v[88:91]
	v_mfma_f32_16x16x32_bf16 v[88:91], v[132:135], v[180:183], v[88:91]
	v_mfma_f32_16x16x32_bf16 v[84:87], v[144:147], v[176:179], v[84:87]
	v_mfma_f32_16x16x32_bf16 v[84:87], v[148:151], v[180:183], v[84:87]
	v_mfma_f32_16x16x32_bf16 v[80:83], v[152:155], v[176:179], v[80:83]
	v_mfma_f32_16x16x32_bf16 v[80:83], v[156:159], v[180:183], v[80:83]
	v_mfma_f32_16x16x32_bf16 v[76:79], v[120:123], v[184:187], v[76:79]
	v_mfma_f32_16x16x32_bf16 v[76:79], v[124:127], v[188:191], v[76:79]
	v_mfma_f32_16x16x32_bf16 v[72:75], v[128:131], v[184:187], v[72:75]
	v_mfma_f32_16x16x32_bf16 v[72:75], v[132:135], v[188:191], v[72:75]
	v_mfma_f32_16x16x32_bf16 v[68:71], v[144:147], v[184:187], v[68:71]
	v_mfma_f32_16x16x32_bf16 v[68:71], v[148:151], v[188:191], v[68:71]
	v_mfma_f32_16x16x32_bf16 v[64:67], v[152:155], v[184:187], v[64:67]
	v_mfma_f32_16x16x32_bf16 v[64:67], v[156:159], v[188:191], v[64:67]
	s_barrier
; #define PG8_STAGE(bufoff, gbase, voff) do { _Pragma("unroll") for (int _i = 0; _i < 2; ++_i) \
;         __builtin_amdgcn_global_load_lds((const unsigned*)((const char*)(gbase) + (voff)[_i]), (LAS unsigned*)(lds + (bufoff) + ldsw + _i * 8192), 16, 0, 0); } while (0)
; #define PG8_LDA(dst, off) do { _Pragma("unroll") for (int m = 0; m < 4; ++m) _Pragma("unroll") for (int k = 0; k < 2; ++k) dst[m][k] = *(const LAS bf16x8*)(lds + (off) + aoff + m * 2048 + k * 1024); } while (0)
; #define PG8_MMA(ai, bj, At, Bt) do { __builtin_amdgcn_s_setprio(1); _Pragma("unroll") for (int m = 0; m < 4; ++m) _Pragma("unroll") for (int n = 0; n < 2; ++n) _Pragma("unroll") for (int k = 0; k < 2; ++k) \
;         acc[ai][bj][m][n] = __builtin_amdgcn_mfma_f32_16x16x32_bf16(Bt[n][k], At[m][k], acc[ai][bj][m][n], 0, 0, 0); __builtin_amdgcn_s_setprio(0); } while (0)
; #define PG8_WAIT_V(n) asm volatile("s_waitcnt vmcnt(" #n ")" ::: "memory")
; #define PG8_WAIT_L(n) asm volatile("s_waitcnt lgkmcnt(" #n ")" ::: "memory")
; #define PG8_BAR __builtin_amdgcn_s_barrier()
; #define PG8_SCHED __builtin_amdgcn_sched_barrier(0)
; template <class Epi, bool ALIGN_EPI = true>
; __device__ __forceinline__ void gemm_phase(LAS unsigned char* lds, const Gemm g, const StaticOrder& S, const Epi& E) {
;     ...
;             PG8_LDA(At, PG8_SA1(1)); PG8_STAGE(PG8_SB(1, 0), b3, voffB); PG8_STAGE(PG8_SB(1, 1), b3 + hstep, voffB);
;             PG8_WAIT_V(8); PG8_WAIT_L(0); PG8_BAR; PG8_MMA(1, 0, At, B0); PG8_MMA(1, 1, At, B1); PG8_BAR; PG8_SCHED;
;             { const int t_ = o0; o0 = o2; o2 = o1; o1 = t_; }
;         }
;         if constexpr (ALIGN_EPI) { if (wr == 0) PG8_BAR; }
	s_add_i32 s36, s58, s35
	v_lshl_add_u64 v[192:193], v[196:197], 0, s[8:9]
	s_mov_b32 m0, s36
	ds_read_b128 v[160:163], v239 offset:16384
	ds_read_b128 v[164:167], v239 offset:17408
	ds_read_b128 v[168:171], v239 offset:18432
	ds_read_b128 v[172:175], v239 offset:19456
	ds_read_b128 v[176:179], v239 offset:20480
	ds_read_b128 v[180:183], v239 offset:21504
	ds_read_b128 v[184:187], v239 offset:22528
	ds_read_b128 v[188:191], v239 offset:23552
	global_load_lds_dwordx4 v[192:193], off
	s_add_i32 m0, s36, 0x2000
	s_add_u32 s30, s30, 0x2b0080
	v_lshl_add_u64 v[192:193], v[198:199], 0, s[8:9]
	s_addc_u32 s31, s31, 0
	s_add_i32 s36, s59, s35
	global_load_lds_dwordx4 v[192:193], off
	v_lshl_add_u64 v[192:193], s[30:31], 0, v[206:207]
	s_mov_b32 m0, s36
	s_nop 0
	global_load_lds_dwordx4 v[192:193], off
	v_lshl_add_u64 v[192:193], s[30:31], 0, v[210:211]
	s_add_i32 m0, s36, 0x2000
	s_nop 0
	global_load_lds_dwordx4 v[192:193], off
	s_waitcnt vmcnt(8)
	s_waitcnt lgkmcnt(0)
	s_barrier
	s_waitcnt lgkmcnt(0)
	v_mfma_f32_16x16x32_bf16 v[60:63], v[120:123], v[160:163], v[60:63]
	v_mfma_f32_16x16x32_bf16 v[60:63], v[124:127], v[164:167], v[60:63]
	v_mfma_f32_16x16x32_bf16 v[56:59], v[128:131], v[160:163], v[56:59]
	v_mfma_f32_16x16x32_bf16 v[56:59], v[132:135], v[164:167], v[56:59]
	v_mfma_f32_16x16x32_bf16 v[52:55], v[144:147], v[160:163], v[52:55]
	v_mfma_f32_16x16x32_bf16 v[52:55], v[148:151], v[164:167], v[52:55]
	v_mfma_f32_16x16x32_bf16 v[48:51], v[152:155], v[160:163], v[48:51]
	v_mfma_f32_16x16x32_bf16 v[48:51], v[156:159], v[164:167], v[48:51]
	v_mfma_f32_16x16x32_bf16 v[44:47], v[120:123], v[168:171], v[44:47]
	v_mfma_f32_16x16x32_bf16 v[44:47], v[124:127], v[172:175], v[44:47]
	v_mfma_f32_16x16x32_bf16 v[40:43], v[128:131], v[168:171], v[40:43]
	v_mfma_f32_16x16x32_bf16 v[40:43], v[132:135], v[172:175], v[40:43]
	v_mfma_f32_16x16x32_bf16 v[36:39], v[144:147], v[168:171], v[36:39]
	v_mfma_f32_16x16x32_bf16 v[36:39], v[148:151], v[172:175], v[36:39]
	v_mfma_f32_16x16x32_bf16 v[32:35], v[152:155], v[168:171], v[32:35]
	v_mfma_f32_16x16x32_bf16 v[32:35], v[156:159], v[172:175], v[32:35]
	v_mfma_f32_16x16x32_bf16 v[28:31], v[120:123], v[176:179], v[28:31]
	v_mfma_f32_16x16x32_bf16 v[28:31], v[124:127], v[180:183], v[28:31]
	v_mfma_f32_16x16x32_bf16 v[24:27], v[128:131], v[176:179], v[24:27]
	v_mfma_f32_16x16x32_bf16 v[24:27], v[132:135], v[180:183], v[24:27]
	v_mfma_f32_16x16x32_bf16 v[20:23], v[144:147], v[176:179], v[20:23]
	v_mfma_f32_16x16x32_bf16 v[20:23], v[148:151], v[180:183], v[20:23]
	v_mfma_f32_16x16x32_bf16 v[16:19], v[152:155], v[176:179], v[16:19]
	v_mfma_f32_16x16x32_bf16 v[16:19], v[156:159], v[180:183], v[16:19]
	v_mfma_f32_16x16x32_bf16 v[12:15], v[120:123], v[184:187], v[12:15]
	v_mfma_f32_16x16x32_bf16 v[12:15], v[124:127], v[188:191], v[12:15]
	v_mfma_f32_16x16x32_bf16 v[8:11], v[128:131], v[184:187], v[8:11]
	v_mfma_f32_16x16x32_bf16 v[8:11], v[132:135], v[188:191], v[8:11]
	v_mfma_f32_16x16x32_bf16 v[4:7], v[144:147], v[184:187], v[4:7]
	v_mfma_f32_16x16x32_bf16 v[4:7], v[148:151], v[188:191], v[4:7]
	v_mfma_f32_16x16x32_bf16 v[0:3], v[152:155], v[184:187], v[0:3]
	v_mfma_f32_16x16x32_bf16 v[0:3], v[156:159], v[188:191], v[0:3]
	s_barrier
	s_add_i32 s57, s57, 2
	s_add_u32 s28, s28, 0x100
	s_addc_u32 s29, s29, 0
	s_add_u32 s55, s55, 0x100
	s_addc_u32 s56, s56, 0
	s_cmpk_gt_u32 s57, 0xa9
	s_mov_b32 s30, s52
	s_cbranch_scc0 .LBB0_1077
	s_setprio 0
	s_and_b64 vcc, exec, s[10:11]
	s_cbranch_vccz .LBB0_1080
	s_barrier
